# static priority: per-segment s_setprio flips deleted, one s_setprio 1 for waves 4-7 per GEMM phase
# speedup vs baseline: 1.0128x; 1.0008x over previous
; #define PG8_STAGE(bufoff, gbase, voff) do { _Pragma("unroll") for (int _i = 0; _i < 2; ++_i) { \
;         const unsigned _m0 = ldsb + (unsigned)((bufoff) + _i * 8192); const char* _gb = (const char*)(gbase); \
;         asm volatile("s_mov_b32 m0, %0\n\ts_nop 0\n\tglobal_load_lds_dwordx4 %1, %2" :: "s"(_m0), "v"((voff)[_i]), "s"(_gb) : "m0", "memory"); } } while (0)
; #define PG8_BAR __builtin_amdgcn_s_barrier()
; template <class Epi, bool ALIGN_EPI>
; __device__ __forceinline__ void gemm_phase(LAS unsigned char* lds, const Gemm g, const StaticOrder& S, const Epi& E) {
;     ...
;     const int wid = __builtin_amdgcn_readfirstlane(tid >> 6), lane = tid & 63, wr = wid >> 2, wc = wid & 3, fr = lane & 15, fq = lane >> 4;
;     const int K = g.K, nt = K / BK, lda = g.lda;
;     unsigned voffA[2], voffB[2];
; #pragma unroll
;     for (int i = 0; i < 2; ++i) { int R, C; stage_rc(tid * 16 + i * 8192, R, C); const int Rb = (R & ~31) + perm32(R & 31);
;         voffA[i] = (unsigned)(R * lda + C) * 2u; voffB[i] = (unsigned)(Rb * K + C) * 2u; }
;     const size_t kstep = (size_t)(BK * 2);
;     const size_t hstepA = (size_t)HALF * lda * 2, hstepB = (size_t)HALF * K * 2;
;     const size_t tstepA = 2 * hstepA, tstepB = 2 * hstepB;
;     const unsigned ldsw = (unsigned)wid * 1024u;
;     const unsigned ldsb = (unsigned)(unsigned long)lds + ldsw;
;     const int aoff = lds_byte(wr * 64 + fr, fq * 8), boff = lds_byte(wc * 32 + fr, fq * 8);
;     ...
;     Unit cur, nxt; int ui = 0;
;     if (!S.next(0, cur)) return;
;     f32x4 acc[2][2][4][2];
; #pragma unroll
;     for (int a = 0; a < 2; ++a)
; #pragma unroll
;         for (int b = 0; b < 2; ++b)
; #pragma unroll
;             for (int m = 0; m < 4; ++m)
; #pragma unroll
;                 for (int n = 0; n < 2; ++n) acc[a][b][m][n] = (f32x4){0.f, 0.f, 0.f, 0.f};
;     bf16x8 At[4][2], B0[2][2], B1[2][2];
;     const char* cA = (const char*)g.A + (size_t)cur.pm * tstepA + (size_t)cur.pn * g.a_pn_off * 2 + (size_t)(cur.pm >> 4) * g.a_adj; const char* cB = (const char*)g.Bt + (size_t)cur.pn * tstepB;
;     PG8_STAGE(PG8_SB(0, 0), cB, voffB); PG8_STAGE(PG8_SB(0, 1), cB + hstepB, voffB); PG8_STAGE(PG8_SA(0, 0), cA, voffA); PG8_STAGE(PG8_SA(0, 1), cA + hstepA, voffA);
;     if (wr == 1) PG8_BAR;
.LBB0_134:
	s_andn2_b64 vcc, exec, s[6:7]
	s_cbranch_vccnz .LBB0_176
	v_bfe_i32 v6, v4, 27, 1
	v_lshlrev_b32_e32 v5, 4, v4
	v_lshrrev_b32_e32 v6, 22, v6
	v_add_u32_e32 v6, v5, v6
	v_and_b32_e32 v6, 0xfffffc00, v6
	v_sub_u32_e32 v6, v5, v6
	v_lshrrev_b32_e32 v7, 4, v6
	v_ashrrev_i32_e32 v0, 31, v4
	v_bitop3_b32 v6, v7, v6, 32 bitop3:0x6c
	v_lshrrev_b32_e32 v0, 26, v0
	v_ashrrev_i32_e32 v8, 31, v6
	v_add_u32_e32 v0, v4, v0
	v_lshrrev_b32_e32 v8, 26, v8
	v_ashrrev_i32_e32 v0, 6, v0
	v_add_u32_e32 v8, v6, v8
	v_lshlrev_b32_e32 v7, 3, v0
	v_ashrrev_i32_e32 v9, 6, v8
	v_and_b32_e32 v8, 0xc0, v8
	v_and_b32_e32 v7, -16, v7
	v_lshlrev_b32_e32 v0, 5, v0
	v_sub_u32_e32 v6, v6, v8
	v_add_u32_e32 v7, v9, v7
	v_and_b32_e32 v0, 32, v0
	v_ashrrev_i16_sdwa v6, v223, sext(v6) dst_sel:DWORD dst_unused:UNUSED_PAD src0_sel:DWORD src1_sel:BYTE_0
	v_add_u32_sdwa v6, v0, sext(v6) dst_sel:DWORD dst_unused:UNUSED_PAD src0_sel:DWORD src1_sel:WORD_0
	v_lshlrev_b32_e32 v0, 1, v7
	v_lshrrev_b32_e32 v8, 2, v7
	v_and_b32_e32 v9, 3, v9
	s_mov_b32 s5, 0x7fffffe0
	v_and_b32_e32 v0, 24, v0
	v_and_b32_e32 v8, 4, v8
	v_and_or_b32 v9, v7, s5, v9
	v_or3_b32 v8, v9, v8, v0
	v_mul_lo_u32 v0, v7, s43
	v_mul_lo_u32 v7, v8, s43
	v_add_u32_e32 v5, 0x2000, v5
	v_add_lshl_u32 v0, v6, v0, 1
	v_add_lshl_u32 v195, v7, v6, 1
	v_ashrrev_i32_e32 v6, 31, v5
	v_lshrrev_b32_e32 v6, 22, v6
	v_add_u32_e32 v6, v5, v6
	v_ashrrev_i32_e32 v6, 10, v6
	v_mul_i32_i24_e32 v7, 0x400, v6
	v_sub_u32_e32 v5, v5, v7
	v_lshrrev_b32_e32 v7, 4, v5
	v_bitop3_b32 v5, v7, v5, 32 bitop3:0x6c
	v_writelane_b32 v254, s85, 39
	v_ashrrev_i32_e32 v8, 31, v5
	v_writelane_b32 v254, s80, 40
	v_lshrrev_b32_e32 v8, 26, v8
	v_writelane_b32 v254, s67, 41
	v_lshlrev_b32_e32 v7, 3, v6
	v_add_u32_e32 v8, v5, v8
	v_writelane_b32 v254, s65, 42
	s_ashr_i32 s4, s8, 6
	v_and_b32_e32 v7, -16, v7
	v_ashrrev_i32_e32 v9, 6, v8
	v_writelane_b32 v254, s53, 43
	v_add_u32_e32 v7, v9, v7
	v_and_b32_e32 v8, 0xc0, v8
	v_and_b32_e32 v9, 3, v9
	s_lshl_b32 s17, s43, 9
	s_lshl_b32 s26, s4, 10
	v_lshlrev_b32_e32 v6, 5, v6
	v_sub_u32_e32 v5, v5, v8
	v_and_or_b32 v9, v7, s5, v9
	s_ashr_i32 s5, s8, 8
	s_lshl_b32 s15, s43, 8
	s_add_i32 s26, s26, 0
	s_ashr_i32 s9, s35, 4
	v_readlane_b32 s27, v254, 48
	s_mul_i32 s28, s17, s34
	v_readlane_b32 s29, v254, 46
	v_and_b32_e32 v6, 32, v6
	v_ashrrev_i16_sdwa v5, v223, sext(v5) dst_sel:DWORD dst_unused:UNUSED_PAD src0_sel:DWORD src1_sel:BYTE_0
	s_mul_hi_i32 s14, s9, s27
	s_mul_i32 s9, s9, s27
	s_mul_hi_i32 s27, s17, s34
	s_add_u32 s48, s29, s28
	v_readlane_b32 s28, v254, 44
	v_add_u32_sdwa v5, v6, sext(v5) dst_sel:DWORD dst_unused:UNUSED_PAD src0_sel:DWORD src1_sel:WORD_0
	v_lshlrev_b32_e32 v6, 1, v7
	v_lshrrev_b32_e32 v8, 2, v7
	s_mul_i32 s7, s17, s35
	s_addc_u32 s49, s28, s27
	s_add_i32 s27, s26, 0x10000
	s_add_i32 s28, s26, 0x12000
	v_readlane_b32 s29, v254, 60
	v_and_b32_e32 v6, 24, v6
	v_and_b32_e32 v8, 4, v8
	s_mul_hi_i32 s6, s17, s35
	s_add_u32 s31, s29, s7
	v_readlane_b32 s7, v254, 59
	v_or3_b32 v6, v9, v8, v6
	s_addc_u32 s36, s7, s6
	s_add_i32 s29, s26, 0x14000
	v_mul_lo_u32 v6, v6, s43
	s_mov_b32 m0, s27
	s_nop 0
	global_load_lds_dwordx4 v195, s[48:49]
	s_add_u32 s6, s48, s15
	v_add_lshl_u32 v241, v6, v5, 1
	s_mov_b32 m0, s28
	s_nop 0
	global_load_lds_dwordx4 v241, s[48:49]
	s_addc_u32 s7, s49, 0
	s_add_i32 s30, s26, 0x16000
	s_mov_b32 m0, s29
	s_nop 0
	global_load_lds_dwordx4 v195, s[6:7]
	s_add_u32 s54, s31, s9
	s_mov_b32 m0, s30
	s_nop 0
	global_load_lds_dwordx4 v241, s[6:7]
	s_addc_u32 s55, s36, s14
	s_add_i32 s31, s26, 0x2000
	s_add_i32 s41, s26, 0x4000
	v_mul_lo_u32 v7, v7, s43
	s_mov_b32 m0, s26
	s_nop 0
	global_load_lds_dwordx4 v0, s[54:55]
	s_add_u32 s36, s54, s15
	v_add_lshl_u32 v240, v5, v7, 1
	s_mov_b32 m0, s31
	s_nop 0
	global_load_lds_dwordx4 v240, s[54:55]
	s_addc_u32 s37, s55, 0
	s_add_i32 s42, s26, 0x6000
	s_mov_b32 m0, s41
	s_nop 0
	global_load_lds_dwordx4 v0, s[36:37]
	s_cmp_eq_u32 s5, 1
	s_mov_b32 m0, s42
	s_nop 0
	global_load_lds_dwordx4 v240, s[36:37]
	s_cselect_b64 s[36:37], -1, 0
	v_writelane_b32 v255, s36, 0
	s_cmp_lg_u32 s5, 1
	s_nop 0
	v_writelane_b32 v255, s37, 1
	s_cbranch_scc1 .LBB0_137
	s_barrier
	s_setprio 1

; #define PG8_STAGE(bufoff, gbase, voff) do { _Pragma("unroll") for (int _i = 0; _i < 2; ++_i) { \
;         const unsigned _m0 = ldsb + (unsigned)((bufoff) + _i * 8192); const char* _gb = (const char*)(gbase); \
;         asm volatile("s_mov_b32 m0, %0\n\ts_nop 0\n\tglobal_load_lds_dwordx4 %1, %2" :: "s"(_m0), "v"((voff)[_i]), "s"(_gb) : "m0", "memory"); } } while (0)
; #define PG8_LDA(dst, b, h) do { _Pragma("unroll") for (int m = 0; m < 4; ++m) _Pragma("unroll") for (int k = 0; k < 2; ++k) dst[m][k] = *(const LAS bf16x8*)(lds + PG8_SA(b, h) + aoff + m * 2048 + k * 1024); } while (0)
; #define PG8_LDB(dst, b, h) do { _Pragma("unroll") for (int n = 0; n < 2; ++n) _Pragma("unroll") for (int k = 0; k < 2; ++k) dst[n][k] = *(const LAS bf16x8*)(lds + PG8_SB(b, h) + boff + n * 2048 + k * 1024); } while (0)
; #define PG8_MMA(ai, bj, At, Bt) do { __builtin_amdgcn_s_setprio(1); _Pragma("unroll") for (int m = 0; m < 4; ++m) _Pragma("unroll") for (int n = 0; n < 2; ++n) _Pragma("unroll") for (int k = 0; k < 2; ++k) \
;         acc[ai][bj][m][n] = __builtin_amdgcn_mfma_f32_16x16x32_bf16(Bt[n][k], At[m][k], acc[ai][bj][m][n], 0, 0, 0); __builtin_amdgcn_s_setprio(0); } while (0)
; #define PG8_WAIT_V(n) asm volatile("s_waitcnt vmcnt(" #n ")" ::: "memory")
; #define PG8_WAIT_L(n) asm volatile("s_waitcnt lgkmcnt(" #n ")" ::: "memory")
; #define PG8_BAR __builtin_amdgcn_s_barrier()
; #define PG8_SCHED __builtin_amdgcn_sched_barrier(0)
; template <class Epi, bool ALIGN_EPI>
; __device__ __forceinline__ void gemm_phase(LAS unsigned char* lds, const Gemm g, const StaticOrder& S, const Epi& E) {
;     ...
;             const char* a1 = cA + (size_t)(t + 1) * kstep;
;             const char* a2 = last ? nA : cA + (size_t)(t + 2) * kstep; const char* b2 = last ? nB : cB + (size_t)(t + 2) * kstep;
;             const char* a3 = a2 + kstep; const char* b3 = b2 + kstep;
;             PG8_LDB(B0, 0, 0); PG8_LDB(B1, 0, 1); PG8_SCHED; PG8_LDA(At, 0, 0); PG8_STAGE(PG8_SA(1, 1), a1 + hstepA, voffA);
;             PG8_WAIT_V(8); PG8_WAIT_L(0); PG8_BAR; PG8_MMA(0, 0, At, B0); PG8_MMA(0, 1, At, B1); PG8_BAR; PG8_SCHED;
;             PG8_LDA(At, 0, 1); PG8_STAGE(PG8_SB(0, 0), b2, voffB); PG8_STAGE(PG8_SB(0, 1), b2 + hstepB, voffB); PG8_STAGE(PG8_SA(0, 0), a2, voffA);
;             PG8_WAIT_V(8); PG8_WAIT_L(0); PG8_BAR; PG8_MMA(1, 0, At, B0); PG8_MMA(1, 1, At, B1); PG8_BAR; PG8_SCHED;
.LBB0_150:
	s_add_u32 s4, s48, 0x100
	s_addc_u32 s5, s49, 0
	s_add_u32 s37, s54, 0x100
	s_addc_u32 s44, s55, 0
	s_mov_b32 s45, 0
	s_waitcnt lgkmcnt(0)
	s_add_i32 s51, s45, 2
	s_cmp_eq_u32 s67, s45
	s_cselect_b32 s56, s0, s37
	s_cselect_b32 s57, s1, s44
	s_cselect_b32 s54, s94, s4
	s_cselect_b32 s55, s95, s5
	s_add_u32 s48, s56, 0x80
	s_addc_u32 s49, s57, 0
	s_add_u32 s45, s37, s15
	s_addc_u32 s59, s44, 0
	s_add_u32 s58, s45, 0xffffff80
	s_addc_u32 s59, s59, -1
	s_mov_b32 m0, s68
	s_nop 0
	global_load_lds_dwordx4 v0, s[58:59]
	s_nop 0
	s_mov_b32 m0, s85
	s_nop 0
	global_load_lds_dwordx4 v240, s[58:59]
	s_waitcnt vmcnt(8)
	s_waitcnt lgkmcnt(0)
	s_barrier
	s_waitcnt lgkmcnt(0)
	v_mfma_f32_16x16x32_bf16 v[172:175], v[108:111], v[156:159], 0
	v_mfma_f32_16x16x32_bf16 v[172:175], v[120:123], v[160:163], v[172:175]
	v_mfma_f32_16x16x32_bf16 v[168:171], v[128:131], v[156:159], 0
	v_mfma_f32_16x16x32_bf16 v[168:171], v[132:135], v[160:163], v[168:171]
	v_mfma_f32_16x16x32_bf16 v[140:143], v[136:139], v[156:159], 0
	v_mfma_f32_16x16x32_bf16 v[140:143], v[144:147], v[160:163], v[140:143]
	v_mfma_f32_16x16x32_bf16 v[124:127], v[148:151], v[156:159], 0
	v_mfma_f32_16x16x32_bf16 v[124:127], v[152:155], v[160:163], v[124:127]
	v_mfma_f32_16x16x32_bf16 v[100:103], v[148:151], v[164:167], 0
	v_mfma_f32_16x16x32_bf16 v[100:103], v[152:155], v[176:179], v[100:103]
	v_mfma_f32_16x16x32_bf16 v[104:107], v[136:139], v[164:167], 0
	v_mfma_f32_16x16x32_bf16 v[104:107], v[144:147], v[176:179], v[104:107]
	v_mfma_f32_16x16x32_bf16 v[112:115], v[128:131], v[164:167], 0
	v_mfma_f32_16x16x32_bf16 v[112:115], v[132:135], v[176:179], v[112:115]
	v_mfma_f32_16x16x32_bf16 v[116:119], v[108:111], v[164:167], 0
	v_mfma_f32_16x16x32_bf16 v[116:119], v[120:123], v[176:179], v[116:119]
	v_mfma_f32_16x16x32_bf16 v[96:99], v[108:111], v[180:183], 0
	v_mfma_f32_16x16x32_bf16 v[96:99], v[120:123], v[184:187], v[96:99]
	v_mfma_f32_16x16x32_bf16 v[92:95], v[128:131], v[180:183], 0
	v_mfma_f32_16x16x32_bf16 v[92:95], v[132:135], v[184:187], v[92:95]
	v_mfma_f32_16x16x32_bf16 v[88:91], v[136:139], v[180:183], 0
	v_mfma_f32_16x16x32_bf16 v[88:91], v[144:147], v[184:187], v[88:91]
	v_mfma_f32_16x16x32_bf16 v[84:87], v[148:151], v[180:183], 0
	v_mfma_f32_16x16x32_bf16 v[84:87], v[152:155], v[184:187], v[84:87]
	v_mfma_f32_16x16x32_bf16 v[68:71], v[148:151], v[188:191], 0
	v_mfma_f32_16x16x32_bf16 v[68:71], v[152:155], v[202:205], v[68:71]
	v_mfma_f32_16x16x32_bf16 v[72:75], v[136:139], v[188:191], 0
	v_mfma_f32_16x16x32_bf16 v[72:75], v[144:147], v[202:205], v[72:75]
	v_mfma_f32_16x16x32_bf16 v[76:79], v[128:131], v[188:191], 0
	v_mfma_f32_16x16x32_bf16 v[76:79], v[132:135], v[202:205], v[76:79]
	v_mfma_f32_16x16x32_bf16 v[80:83], v[108:111], v[188:191], 0
	v_mfma_f32_16x16x32_bf16 v[80:83], v[120:123], v[202:205], v[80:83]
	s_barrier
	ds_read_b128 v[156:159], v245 offset:16384
	ds_read_b128 v[160:163], v245 offset:17408
	ds_read_b128 v[164:167], v245 offset:18432
	ds_read_b128 v[176:179], v245 offset:19456
	ds_read_b128 v[180:183], v245 offset:20480
	ds_read_b128 v[184:187], v245 offset:21504
	ds_read_b128 v[188:191], v245 offset:22528
	ds_read_b128 v[202:205], v245 offset:23552
	s_mov_b32 m0, s27
	s_nop 0
	global_load_lds_dwordx4 v195, s[54:55]
	s_add_u32 s58, s54, s15
	s_mov_b32 m0, s28
	s_nop 0
	global_load_lds_dwordx4 v241, s[54:55]
	s_addc_u32 s59, s55, 0
	s_mov_b32 m0, s29
	s_nop 0
	global_load_lds_dwordx4 v195, s[58:59]
	s_nop 0
	s_mov_b32 m0, s30
	s_nop 0
	global_load_lds_dwordx4 v241, s[58:59]
	s_nop 0
	s_mov_b32 m0, s26
	s_nop 0
	global_load_lds_dwordx4 v0, s[56:57]
	s_nop 0
	s_mov_b32 m0, s31
	s_nop 0
	global_load_lds_dwordx4 v240, s[56:57]
	s_waitcnt vmcnt(8)
	s_waitcnt lgkmcnt(0)
	s_barrier
	s_waitcnt lgkmcnt(0)
	v_mfma_f32_16x16x32_bf16 v[64:67], v[108:111], v[156:159], 0
	v_mfma_f32_16x16x32_bf16 v[64:67], v[120:123], v[160:163], v[64:67]
	v_mfma_f32_16x16x32_bf16 v[60:63], v[128:131], v[156:159], 0
	v_mfma_f32_16x16x32_bf16 v[60:63], v[132:135], v[160:163], v[60:63]
	v_mfma_f32_16x16x32_bf16 v[56:59], v[136:139], v[156:159], 0
	v_mfma_f32_16x16x32_bf16 v[56:59], v[144:147], v[160:163], v[56:59]
	v_mfma_f32_16x16x32_bf16 v[52:55], v[148:151], v[156:159], 0
	v_mfma_f32_16x16x32_bf16 v[52:55], v[152:155], v[160:163], v[52:55]
	v_mfma_f32_16x16x32_bf16 v[36:39], v[148:151], v[164:167], 0
	v_mfma_f32_16x16x32_bf16 v[36:39], v[152:155], v[176:179], v[36:39]
	v_mfma_f32_16x16x32_bf16 v[40:43], v[136:139], v[164:167], 0
	v_mfma_f32_16x16x32_bf16 v[40:43], v[144:147], v[176:179], v[40:43]
	v_mfma_f32_16x16x32_bf16 v[44:47], v[128:131], v[164:167], 0
	v_mfma_f32_16x16x32_bf16 v[44:47], v[132:135], v[176:179], v[44:47]
	v_mfma_f32_16x16x32_bf16 v[48:51], v[108:111], v[164:167], 0
	v_mfma_f32_16x16x32_bf16 v[48:51], v[120:123], v[176:179], v[48:51]
	v_mfma_f32_16x16x32_bf16 v[32:35], v[108:111], v[180:183], 0
	v_mfma_f32_16x16x32_bf16 v[32:35], v[120:123], v[184:187], v[32:35]
	v_mfma_f32_16x16x32_bf16 v[28:31], v[128:131], v[180:183], 0
	v_mfma_f32_16x16x32_bf16 v[28:31], v[132:135], v[184:187], v[28:31]
	v_mfma_f32_16x16x32_bf16 v[24:27], v[136:139], v[180:183], 0
	v_mfma_f32_16x16x32_bf16 v[24:27], v[144:147], v[184:187], v[24:27]
	v_mfma_f32_16x16x32_bf16 v[20:23], v[148:151], v[180:183], 0
	v_mfma_f32_16x16x32_bf16 v[20:23], v[152:155], v[184:187], v[20:23]
	v_mfma_f32_16x16x32_bf16 v[4:7], v[148:151], v[188:191], 0
	v_mfma_f32_16x16x32_bf16 v[4:7], v[152:155], v[202:205], v[4:7]
	v_mfma_f32_16x16x32_bf16 v[8:11], v[136:139], v[188:191], 0
	v_mfma_f32_16x16x32_bf16 v[8:11], v[144:147], v[202:205], v[8:11]
	v_mfma_f32_16x16x32_bf16 v[12:15], v[128:131], v[188:191], 0
	v_mfma_f32_16x16x32_bf16 v[12:15], v[132:135], v[202:205], v[12:15]
	v_mfma_f32_16x16x32_bf16 v[16:19], v[108:111], v[188:191], 0
	v_mfma_f32_16x16x32_bf16 v[16:19], v[120:123], v[202:205], v[16:19]
	s_barrier
; #define PG8_STAGE(bufoff, gbase, voff) do { _Pragma("unroll") for (int _i = 0; _i < 2; ++_i) { \
;         const unsigned _m0 = ldsb + (unsigned)((bufoff) + _i * 8192); const char* _gb = (const char*)(gbase); \
;         asm volatile("s_mov_b32 m0, %0\n\ts_nop 0\n\tglobal_load_lds_dwordx4 %1, %2" :: "s"(_m0), "v"((voff)[_i]), "s"(_gb) : "m0", "memory"); } } while (0)
; #define PG8_LDA(dst, b, h) do { _Pragma("unroll") for (int m = 0; m < 4; ++m) _Pragma("unroll") for (int k = 0; k < 2; ++k) dst[m][k] = *(const LAS bf16x8*)(lds + PG8_SA(b, h) + aoff + m * 2048 + k * 1024); } while (0)
; #define PG8_LDB(dst, b, h) do { _Pragma("unroll") for (int n = 0; n < 2; ++n) _Pragma("unroll") for (int k = 0; k < 2; ++k) dst[n][k] = *(const LAS bf16x8*)(lds + PG8_SB(b, h) + boff + n * 2048 + k * 1024); } while (0)
; #define PG8_MMA(ai, bj, At, Bt) do { __builtin_amdgcn_s_setprio(1); _Pragma("unroll") for (int m = 0; m < 4; ++m) _Pragma("unroll") for (int n = 0; n < 2; ++n) _Pragma("unroll") for (int k = 0; k < 2; ++k) \
;         acc[ai][bj][m][n] = __builtin_amdgcn_mfma_f32_16x16x32_bf16(Bt[n][k], At[m][k], acc[ai][bj][m][n], 0, 0, 0); __builtin_amdgcn_s_setprio(0); } while (0)
; #define PG8_WAIT_V(n) asm volatile("s_waitcnt vmcnt(" #n ")" ::: "memory")
; #define PG8_WAIT_L(n) asm volatile("s_waitcnt lgkmcnt(" #n ")" ::: "memory")
; #define PG8_BAR __builtin_amdgcn_s_barrier()
; #define PG8_SCHED __builtin_amdgcn_sched_barrier(0)
; template <class Epi, bool ALIGN_EPI>
; __device__ __forceinline__ void gemm_phase(LAS unsigned char* lds, const Gemm g, const StaticOrder& S, const Epi& E) {
;     ...
;             PG8_LDB(B0, 1, 0); PG8_LDB(B1, 1, 1); PG8_SCHED; PG8_LDA(At, 1, 0); PG8_STAGE(PG8_SA(0, 1), a2 + hstepA, voffA);
;             PG8_WAIT_V(8); PG8_WAIT_L(0); PG8_BAR; PG8_MMA(0, 0, At, B0); PG8_MMA(0, 1, At, B1); PG8_BAR; PG8_SCHED;
;             PG8_LDA(At, 1, 1); PG8_STAGE(PG8_SB(1, 0), b3, voffB); PG8_STAGE(PG8_SB(1, 1), b3 + hstepB, voffB); PG8_STAGE(PG8_SA(1, 0), a3, voffA);
;             PG8_WAIT_V(8); PG8_WAIT_L(0); PG8_BAR; PG8_MMA(1, 0, At, B0); PG8_MMA(1, 1, At, B1); PG8_BAR; PG8_SCHED;
;         }
	v_add_u32_e32 v132, 0x18000, v244
	v_add_u32_e32 v152, 0x1c000, v244
	ds_read_b128 v[108:111], v132
	ds_read_b128 v[120:123], v132 offset:1024
	ds_read_b128 v[128:131], v132 offset:2048
	ds_read_b128 v[132:135], v132 offset:3072
	ds_read_b128 v[136:139], v152
	ds_read_b128 v[144:147], v152 offset:1024
	ds_read_b128 v[148:151], v152 offset:2048
	ds_read_b128 v[152:155], v152 offset:3072
	ds_read_b128 v[156:159], v245 offset:32768
	ds_read_b128 v[160:163], v245 offset:33792
	ds_read_b128 v[164:167], v245 offset:34816
	ds_read_b128 v[176:179], v245 offset:35840
	ds_read_b128 v[180:183], v245 offset:36864
	ds_read_b128 v[184:187], v245 offset:37888
	ds_read_b128 v[188:191], v245 offset:38912
	ds_read_b128 v[202:205], v245 offset:39936
	s_add_u32 s56, s56, s15
	s_addc_u32 s57, s57, 0
	s_mov_b32 m0, s41
	s_nop 0
	global_load_lds_dwordx4 v0, s[56:57]
	s_nop 0
	s_mov_b32 m0, s42
	s_nop 0
	global_load_lds_dwordx4 v240, s[56:57]
	s_waitcnt vmcnt(8)
	s_waitcnt lgkmcnt(0)
	s_barrier
	s_waitcnt lgkmcnt(0)
	v_mfma_f32_16x16x32_bf16 v[172:175], v[108:111], v[156:159], v[172:175]
	v_mfma_f32_16x16x32_bf16 v[172:175], v[120:123], v[160:163], v[172:175]
	v_mfma_f32_16x16x32_bf16 v[168:171], v[128:131], v[156:159], v[168:171]
	v_mfma_f32_16x16x32_bf16 v[168:171], v[132:135], v[160:163], v[168:171]
	v_mfma_f32_16x16x32_bf16 v[140:143], v[136:139], v[156:159], v[140:143]
	v_mfma_f32_16x16x32_bf16 v[140:143], v[144:147], v[160:163], v[140:143]
	v_mfma_f32_16x16x32_bf16 v[124:127], v[148:151], v[156:159], v[124:127]
	v_mfma_f32_16x16x32_bf16 v[124:127], v[152:155], v[160:163], v[124:127]
	v_mfma_f32_16x16x32_bf16 v[100:103], v[148:151], v[164:167], v[100:103]
	v_mfma_f32_16x16x32_bf16 v[100:103], v[152:155], v[176:179], v[100:103]
	v_mfma_f32_16x16x32_bf16 v[104:107], v[136:139], v[164:167], v[104:107]
	v_mfma_f32_16x16x32_bf16 v[104:107], v[144:147], v[176:179], v[104:107]
	v_mfma_f32_16x16x32_bf16 v[112:115], v[128:131], v[164:167], v[112:115]
	v_mfma_f32_16x16x32_bf16 v[112:115], v[132:135], v[176:179], v[112:115]
	v_mfma_f32_16x16x32_bf16 v[116:119], v[108:111], v[164:167], v[116:119]
	v_mfma_f32_16x16x32_bf16 v[116:119], v[120:123], v[176:179], v[116:119]
	v_mfma_f32_16x16x32_bf16 v[96:99], v[108:111], v[180:183], v[96:99]
	v_mfma_f32_16x16x32_bf16 v[96:99], v[120:123], v[184:187], v[96:99]
	v_mfma_f32_16x16x32_bf16 v[92:95], v[128:131], v[180:183], v[92:95]
	v_mfma_f32_16x16x32_bf16 v[92:95], v[132:135], v[184:187], v[92:95]
	v_mfma_f32_16x16x32_bf16 v[88:91], v[136:139], v[180:183], v[88:91]
	v_mfma_f32_16x16x32_bf16 v[88:91], v[144:147], v[184:187], v[88:91]
	v_mfma_f32_16x16x32_bf16 v[84:87], v[148:151], v[180:183], v[84:87]
	v_mfma_f32_16x16x32_bf16 v[84:87], v[152:155], v[184:187], v[84:87]
	v_mfma_f32_16x16x32_bf16 v[68:71], v[148:151], v[188:191], v[68:71]
	v_mfma_f32_16x16x32_bf16 v[68:71], v[152:155], v[202:205], v[68:71]
	v_mfma_f32_16x16x32_bf16 v[72:75], v[136:139], v[188:191], v[72:75]
	v_mfma_f32_16x16x32_bf16 v[72:75], v[144:147], v[202:205], v[72:75]
	v_mfma_f32_16x16x32_bf16 v[76:79], v[128:131], v[188:191], v[76:79]
	v_mfma_f32_16x16x32_bf16 v[76:79], v[132:135], v[202:205], v[76:79]
	v_mfma_f32_16x16x32_bf16 v[80:83], v[108:111], v[188:191], v[80:83]
	v_mfma_f32_16x16x32_bf16 v[80:83], v[120:123], v[202:205], v[80:83]
	s_barrier
	ds_read_b128 v[156:159], v245 offset:49152
	ds_read_b128 v[160:163], v245 offset:50176
	ds_read_b128 v[164:167], v245 offset:51200
	ds_read_b128 v[176:179], v245 offset:52224
	ds_read_b128 v[180:183], v245 offset:53248
	ds_read_b128 v[184:187], v245 offset:54272
	ds_read_b128 v[188:191], v245 offset:55296
	ds_read_b128 v[202:205], v245 offset:56320
	s_add_u32 s54, s54, 0x80
	s_addc_u32 s55, s55, 0
	s_mov_b32 m0, s46
	s_nop 0
	global_load_lds_dwordx4 v195, s[54:55]
	s_nop 0
	s_mov_b32 m0, s50
	s_nop 0
	global_load_lds_dwordx4 v241, s[54:55]
	s_add_u32 s54, s58, 0x80
	s_addc_u32 s55, s59, 0
	s_mov_b32 m0, s61
	s_nop 0
	global_load_lds_dwordx4 v195, s[54:55]
	s_nop 0
	s_mov_b32 m0, s65
	s_nop 0
	global_load_lds_dwordx4 v241, s[54:55]
	s_nop 0
	s_mov_b32 m0, s53
	s_nop 0
	global_load_lds_dwordx4 v0, s[48:49]
	s_nop 0
	s_mov_b32 m0, s60
	s_nop 0
	global_load_lds_dwordx4 v240, s[48:49]
	s_waitcnt vmcnt(8)
	s_waitcnt lgkmcnt(0)
	s_barrier
	s_waitcnt lgkmcnt(0)
	v_mfma_f32_16x16x32_bf16 v[64:67], v[108:111], v[156:159], v[64:67]
	v_mfma_f32_16x16x32_bf16 v[64:67], v[120:123], v[160:163], v[64:67]
	v_mfma_f32_16x16x32_bf16 v[60:63], v[128:131], v[156:159], v[60:63]
	v_mfma_f32_16x16x32_bf16 v[60:63], v[132:135], v[160:163], v[60:63]
	v_mfma_f32_16x16x32_bf16 v[56:59], v[136:139], v[156:159], v[56:59]
	v_mfma_f32_16x16x32_bf16 v[56:59], v[144:147], v[160:163], v[56:59]
	v_mfma_f32_16x16x32_bf16 v[52:55], v[148:151], v[156:159], v[52:55]
	v_mfma_f32_16x16x32_bf16 v[52:55], v[152:155], v[160:163], v[52:55]
	v_mfma_f32_16x16x32_bf16 v[36:39], v[148:151], v[164:167], v[36:39]
	v_mfma_f32_16x16x32_bf16 v[36:39], v[152:155], v[176:179], v[36:39]
	v_mfma_f32_16x16x32_bf16 v[40:43], v[136:139], v[164:167], v[40:43]
	v_mfma_f32_16x16x32_bf16 v[40:43], v[144:147], v[176:179], v[40:43]
	v_mfma_f32_16x16x32_bf16 v[44:47], v[128:131], v[164:167], v[44:47]
	v_mfma_f32_16x16x32_bf16 v[44:47], v[132:135], v[176:179], v[44:47]
	v_mfma_f32_16x16x32_bf16 v[48:51], v[108:111], v[164:167], v[48:51]
	v_mfma_f32_16x16x32_bf16 v[48:51], v[120:123], v[176:179], v[48:51]
	v_mfma_f32_16x16x32_bf16 v[32:35], v[108:111], v[180:183], v[32:35]
	v_mfma_f32_16x16x32_bf16 v[32:35], v[120:123], v[184:187], v[32:35]
	v_mfma_f32_16x16x32_bf16 v[28:31], v[128:131], v[180:183], v[28:31]
	v_mfma_f32_16x16x32_bf16 v[28:31], v[132:135], v[184:187], v[28:31]
	v_mfma_f32_16x16x32_bf16 v[24:27], v[136:139], v[180:183], v[24:27]
	v_mfma_f32_16x16x32_bf16 v[24:27], v[144:147], v[184:187], v[24:27]
	v_mfma_f32_16x16x32_bf16 v[20:23], v[148:151], v[180:183], v[20:23]
	v_mfma_f32_16x16x32_bf16 v[20:23], v[152:155], v[184:187], v[20:23]
	v_mfma_f32_16x16x32_bf16 v[4:7], v[148:151], v[188:191], v[4:7]
	v_mfma_f32_16x16x32_bf16 v[4:7], v[152:155], v[202:205], v[4:7]
	v_mfma_f32_16x16x32_bf16 v[8:11], v[136:139], v[188:191], v[8:11]
	v_mfma_f32_16x16x32_bf16 v[8:11], v[144:147], v[202:205], v[8:11]
	v_mfma_f32_16x16x32_bf16 v[12:15], v[128:131], v[188:191], v[12:15]
	v_mfma_f32_16x16x32_bf16 v[12:15], v[132:135], v[202:205], v[12:15]
	v_mfma_f32_16x16x32_bf16 v[16:19], v[108:111], v[188:191], v[16:19]
	v_mfma_f32_16x16x32_bf16 v[16:19], v[120:123], v[202:205], v[16:19]
	s_barrier
	s_add_u32 s4, s4, 0x100
	s_addc_u32 s5, s5, 0
	s_add_u32 s37, s37, 0x100
	s_addc_u32 s44, s44, 0
	s_cmp_ge_u32 s51, s43
	s_mov_b32 s45, s51
; #define PG8_STAGE(bufoff, gbase, voff) do { _Pragma("unroll") for (int _i = 0; _i < 2; ++_i) { \
;         const unsigned _m0 = ldsb + (unsigned)((bufoff) + _i * 8192); const char* _gb = (const char*)(gbase); \
;         asm volatile("s_mov_b32 m0, %0\n\ts_nop 0\n\tglobal_load_lds_dwordx4 %1, %2" :: "s"(_m0), "v"((voff)[_i]), "s"(_gb) : "m0", "memory"); } } while (0)
; #define PG8_LDA(dst, b, h) do { _Pragma("unroll") for (int m = 0; m < 4; ++m) _Pragma("unroll") for (int k = 0; k < 2; ++k) dst[m][k] = *(const LAS bf16x8*)(lds + PG8_SA(b, h) + aoff + m * 2048 + k * 1024); } while (0)
; #define PG8_LDB(dst, b, h) do { _Pragma("unroll") for (int n = 0; n < 2; ++n) _Pragma("unroll") for (int k = 0; k < 2; ++k) dst[n][k] = *(const LAS bf16x8*)(lds + PG8_SB(b, h) + boff + n * 2048 + k * 1024); } while (0)
; #define PG8_MMA(ai, bj, At, Bt) do { __builtin_amdgcn_s_setprio(1); _Pragma("unroll") for (int m = 0; m < 4; ++m) _Pragma("unroll") for (int n = 0; n < 2; ++n) _Pragma("unroll") for (int k = 0; k < 2; ++k) \
;         acc[ai][bj][m][n] = __builtin_amdgcn_mfma_f32_16x16x32_bf16(Bt[n][k], At[m][k], acc[ai][bj][m][n], 0, 0, 0); __builtin_amdgcn_s_setprio(0); } while (0)
; #define PG8_WAIT_V(n) asm volatile("s_waitcnt vmcnt(" #n ")" ::: "memory")
; #define PG8_WAIT_L(n) asm volatile("s_waitcnt lgkmcnt(" #n ")" ::: "memory")
; #define PG8_BAR __builtin_amdgcn_s_barrier()
; #define PG8_SCHED __builtin_amdgcn_sched_barrier(0)
; template <class Epi, bool ALIGN_EPI>
; __device__ __forceinline__ void gemm_phase(LAS unsigned char* lds, const Gemm g, const StaticOrder& S, const Epi& E) {
;     ...
;             PG8_LDB(B0, 0, 0); PG8_LDB(B1, 0, 1); PG8_SCHED; PG8_LDA(At, 0, 0); PG8_STAGE(PG8_SA(1, 1), a1 + hstepA, voffA);
;             PG8_WAIT_V(8); PG8_WAIT_L(0); PG8_BAR; PG8_MMA(0, 0, At, B0); PG8_MMA(0, 1, At, B1); PG8_BAR; PG8_SCHED;
;             PG8_LDA(At, 0, 1); PG8_STAGE(PG8_SB(0, 0), b2, voffB); PG8_STAGE(PG8_SB(0, 1), b2 + hstepB, voffB); PG8_STAGE(PG8_SA(0, 0), a2, voffA);
;             PG8_WAIT_V(8); PG8_WAIT_L(0); PG8_BAR; PG8_MMA(1, 0, At, B0); PG8_MMA(1, 1, At, B1); PG8_BAR; PG8_SCHED;
.LBB0_151:
	v_add_u32_e32 v132, 0x10000, v244
	v_add_u32_e32 v152, 0x14000, v244
	ds_read_b128 v[108:111], v132
	ds_read_b128 v[120:123], v132 offset:1024
	ds_read_b128 v[128:131], v132 offset:2048
	ds_read_b128 v[132:135], v132 offset:3072
	ds_read_b128 v[136:139], v152
	ds_read_b128 v[144:147], v152 offset:1024
	ds_read_b128 v[148:151], v152 offset:2048
	ds_read_b128 v[152:155], v152 offset:3072
	s_add_i32 s51, s45, 2
	s_cmp_eq_u32 s67, s45
	s_cselect_b32 s56, s0, s37
	s_cselect_b32 s57, s1, s44
	s_cselect_b32 s54, s94, s4
	s_cselect_b32 s55, s95, s5
	s_add_u32 s48, s56, 0x80
	s_addc_u32 s49, s57, 0
	ds_read_b128 v[156:159], v245
	ds_read_b128 v[160:163], v245 offset:1024
	ds_read_b128 v[164:167], v245 offset:2048
	ds_read_b128 v[176:179], v245 offset:3072
	ds_read_b128 v[180:183], v245 offset:4096
	ds_read_b128 v[184:187], v245 offset:5120
	ds_read_b128 v[188:191], v245 offset:6144
	ds_read_b128 v[202:205], v245 offset:7168
	s_add_u32 s45, s37, s15
	s_addc_u32 s59, s44, 0
	s_add_u32 s58, s45, 0xffffff80
	s_addc_u32 s59, s59, -1
	s_mov_b32 m0, s68
	s_nop 0
	global_load_lds_dwordx4 v0, s[58:59]
	s_nop 0
	s_mov_b32 m0, s85
	s_nop 0
	global_load_lds_dwordx4 v240, s[58:59]
	s_waitcnt vmcnt(8)
	s_waitcnt lgkmcnt(0)
	s_barrier
	s_waitcnt lgkmcnt(0)
	v_mfma_f32_16x16x32_bf16 v[172:175], v[108:111], v[156:159], v[172:175]
	v_mfma_f32_16x16x32_bf16 v[172:175], v[120:123], v[160:163], v[172:175]
	v_mfma_f32_16x16x32_bf16 v[168:171], v[128:131], v[156:159], v[168:171]
	v_mfma_f32_16x16x32_bf16 v[168:171], v[132:135], v[160:163], v[168:171]
	v_mfma_f32_16x16x32_bf16 v[140:143], v[136:139], v[156:159], v[140:143]
	v_mfma_f32_16x16x32_bf16 v[140:143], v[144:147], v[160:163], v[140:143]
	v_mfma_f32_16x16x32_bf16 v[124:127], v[148:151], v[156:159], v[124:127]
	v_mfma_f32_16x16x32_bf16 v[124:127], v[152:155], v[160:163], v[124:127]
	v_mfma_f32_16x16x32_bf16 v[100:103], v[148:151], v[164:167], v[100:103]
	v_mfma_f32_16x16x32_bf16 v[100:103], v[152:155], v[176:179], v[100:103]
	v_mfma_f32_16x16x32_bf16 v[104:107], v[136:139], v[164:167], v[104:107]
	v_mfma_f32_16x16x32_bf16 v[104:107], v[144:147], v[176:179], v[104:107]
	v_mfma_f32_16x16x32_bf16 v[112:115], v[128:131], v[164:167], v[112:115]
	v_mfma_f32_16x16x32_bf16 v[112:115], v[132:135], v[176:179], v[112:115]
	v_mfma_f32_16x16x32_bf16 v[116:119], v[108:111], v[164:167], v[116:119]
	v_mfma_f32_16x16x32_bf16 v[116:119], v[120:123], v[176:179], v[116:119]
	v_mfma_f32_16x16x32_bf16 v[96:99], v[108:111], v[180:183], v[96:99]
	v_mfma_f32_16x16x32_bf16 v[96:99], v[120:123], v[184:187], v[96:99]
	v_mfma_f32_16x16x32_bf16 v[92:95], v[128:131], v[180:183], v[92:95]
	v_mfma_f32_16x16x32_bf16 v[92:95], v[132:135], v[184:187], v[92:95]
	v_mfma_f32_16x16x32_bf16 v[88:91], v[136:139], v[180:183], v[88:91]
	v_mfma_f32_16x16x32_bf16 v[88:91], v[144:147], v[184:187], v[88:91]
	v_mfma_f32_16x16x32_bf16 v[84:87], v[148:151], v[180:183], v[84:87]
	v_mfma_f32_16x16x32_bf16 v[84:87], v[152:155], v[184:187], v[84:87]
	v_mfma_f32_16x16x32_bf16 v[68:71], v[148:151], v[188:191], v[68:71]
	v_mfma_f32_16x16x32_bf16 v[68:71], v[152:155], v[202:205], v[68:71]
	v_mfma_f32_16x16x32_bf16 v[72:75], v[136:139], v[188:191], v[72:75]
	v_mfma_f32_16x16x32_bf16 v[72:75], v[144:147], v[202:205], v[72:75]
	v_mfma_f32_16x16x32_bf16 v[76:79], v[128:131], v[188:191], v[76:79]
	v_mfma_f32_16x16x32_bf16 v[76:79], v[132:135], v[202:205], v[76:79]
	v_mfma_f32_16x16x32_bf16 v[80:83], v[108:111], v[188:191], v[80:83]
	v_mfma_f32_16x16x32_bf16 v[80:83], v[120:123], v[202:205], v[80:83]
	s_barrier
	ds_read_b128 v[156:159], v245 offset:16384
	ds_read_b128 v[160:163], v245 offset:17408
	ds_read_b128 v[164:167], v245 offset:18432
	ds_read_b128 v[176:179], v245 offset:19456
	ds_read_b128 v[180:183], v245 offset:20480
	ds_read_b128 v[184:187], v245 offset:21504
	ds_read_b128 v[188:191], v245 offset:22528
	ds_read_b128 v[202:205], v245 offset:23552
	s_mov_b32 m0, s27
	s_nop 0
	global_load_lds_dwordx4 v195, s[54:55]
	s_add_u32 s58, s54, s15
	s_mov_b32 m0, s28
	s_nop 0
	global_load_lds_dwordx4 v241, s[54:55]
	s_addc_u32 s59, s55, 0
	s_mov_b32 m0, s29
	s_nop 0
	global_load_lds_dwordx4 v195, s[58:59]
	s_nop 0
	s_mov_b32 m0, s30
	s_nop 0
	global_load_lds_dwordx4 v241, s[58:59]
	s_nop 0
	s_mov_b32 m0, s26
	s_nop 0
	global_load_lds_dwordx4 v0, s[56:57]
	s_nop 0
	s_mov_b32 m0, s31
	s_nop 0
	global_load_lds_dwordx4 v240, s[56:57]
	s_waitcnt vmcnt(8)
	s_waitcnt lgkmcnt(0)
	s_barrier
	s_waitcnt lgkmcnt(0)
	v_mfma_f32_16x16x32_bf16 v[64:67], v[108:111], v[156:159], v[64:67]
	v_mfma_f32_16x16x32_bf16 v[64:67], v[120:123], v[160:163], v[64:67]
	v_mfma_f32_16x16x32_bf16 v[60:63], v[128:131], v[156:159], v[60:63]
	v_mfma_f32_16x16x32_bf16 v[60:63], v[132:135], v[160:163], v[60:63]
	v_mfma_f32_16x16x32_bf16 v[56:59], v[136:139], v[156:159], v[56:59]
	v_mfma_f32_16x16x32_bf16 v[56:59], v[144:147], v[160:163], v[56:59]
	v_mfma_f32_16x16x32_bf16 v[52:55], v[148:151], v[156:159], v[52:55]
	v_mfma_f32_16x16x32_bf16 v[52:55], v[152:155], v[160:163], v[52:55]
	v_mfma_f32_16x16x32_bf16 v[36:39], v[148:151], v[164:167], v[36:39]
	v_mfma_f32_16x16x32_bf16 v[36:39], v[152:155], v[176:179], v[36:39]
	v_mfma_f32_16x16x32_bf16 v[40:43], v[136:139], v[164:167], v[40:43]
	v_mfma_f32_16x16x32_bf16 v[40:43], v[144:147], v[176:179], v[40:43]
	v_mfma_f32_16x16x32_bf16 v[44:47], v[128:131], v[164:167], v[44:47]
	v_mfma_f32_16x16x32_bf16 v[44:47], v[132:135], v[176:179], v[44:47]
	v_mfma_f32_16x16x32_bf16 v[48:51], v[108:111], v[164:167], v[48:51]
	v_mfma_f32_16x16x32_bf16 v[48:51], v[120:123], v[176:179], v[48:51]
	v_mfma_f32_16x16x32_bf16 v[32:35], v[108:111], v[180:183], v[32:35]
	v_mfma_f32_16x16x32_bf16 v[32:35], v[120:123], v[184:187], v[32:35]
	v_mfma_f32_16x16x32_bf16 v[28:31], v[128:131], v[180:183], v[28:31]
	v_mfma_f32_16x16x32_bf16 v[28:31], v[132:135], v[184:187], v[28:31]
	v_mfma_f32_16x16x32_bf16 v[24:27], v[136:139], v[180:183], v[24:27]
	v_mfma_f32_16x16x32_bf16 v[24:27], v[144:147], v[184:187], v[24:27]
	v_mfma_f32_16x16x32_bf16 v[20:23], v[148:151], v[180:183], v[20:23]
	v_mfma_f32_16x16x32_bf16 v[20:23], v[152:155], v[184:187], v[20:23]
	v_mfma_f32_16x16x32_bf16 v[4:7], v[148:151], v[188:191], v[4:7]
	v_mfma_f32_16x16x32_bf16 v[4:7], v[152:155], v[202:205], v[4:7]
	v_mfma_f32_16x16x32_bf16 v[8:11], v[136:139], v[188:191], v[8:11]
	v_mfma_f32_16x16x32_bf16 v[8:11], v[144:147], v[202:205], v[8:11]
	v_mfma_f32_16x16x32_bf16 v[12:15], v[128:131], v[188:191], v[12:15]
	v_mfma_f32_16x16x32_bf16 v[12:15], v[132:135], v[202:205], v[12:15]
	v_mfma_f32_16x16x32_bf16 v[16:19], v[108:111], v[188:191], v[16:19]
	v_mfma_f32_16x16x32_bf16 v[16:19], v[120:123], v[202:205], v[16:19]
	s_barrier
; #define PG8_STAGE(bufoff, gbase, voff) do { _Pragma("unroll") for (int _i = 0; _i < 2; ++_i) { \
;         const unsigned _m0 = ldsb + (unsigned)((bufoff) + _i * 8192); const char* _gb = (const char*)(gbase); \
;         asm volatile("s_mov_b32 m0, %0\n\ts_nop 0\n\tglobal_load_lds_dwordx4 %1, %2" :: "s"(_m0), "v"((voff)[_i]), "s"(_gb) : "m0", "memory"); } } while (0)
; #define PG8_LDA(dst, b, h) do { _Pragma("unroll") for (int m = 0; m < 4; ++m) _Pragma("unroll") for (int k = 0; k < 2; ++k) dst[m][k] = *(const LAS bf16x8*)(lds + PG8_SA(b, h) + aoff + m * 2048 + k * 1024); } while (0)
; #define PG8_LDB(dst, b, h) do { _Pragma("unroll") for (int n = 0; n < 2; ++n) _Pragma("unroll") for (int k = 0; k < 2; ++k) dst[n][k] = *(const LAS bf16x8*)(lds + PG8_SB(b, h) + boff + n * 2048 + k * 1024); } while (0)
; #define PG8_MMA(ai, bj, At, Bt) do { __builtin_amdgcn_s_setprio(1); _Pragma("unroll") for (int m = 0; m < 4; ++m) _Pragma("unroll") for (int n = 0; n < 2; ++n) _Pragma("unroll") for (int k = 0; k < 2; ++k) \
;         acc[ai][bj][m][n] = __builtin_amdgcn_mfma_f32_16x16x32_bf16(Bt[n][k], At[m][k], acc[ai][bj][m][n], 0, 0, 0); __builtin_amdgcn_s_setprio(0); } while (0)
; #define PG8_WAIT_V(n) asm volatile("s_waitcnt vmcnt(" #n ")" ::: "memory")
; #define PG8_WAIT_L(n) asm volatile("s_waitcnt lgkmcnt(" #n ")" ::: "memory")
; #define PG8_BAR __builtin_amdgcn_s_barrier()
; #define PG8_SCHED __builtin_amdgcn_sched_barrier(0)
; template <class Epi, bool ALIGN_EPI>
; __device__ __forceinline__ void gemm_phase(LAS unsigned char* lds, const Gemm g, const StaticOrder& S, const Epi& E) {
;     ...
;             PG8_LDB(B0, 1, 0); PG8_LDB(B1, 1, 1); PG8_SCHED; PG8_LDA(At, 1, 0); PG8_STAGE(PG8_SA(0, 1), a2 + hstepA, voffA);
;             PG8_WAIT_V(8); PG8_WAIT_L(0); PG8_BAR; PG8_MMA(0, 0, At, B0); PG8_MMA(0, 1, At, B1); PG8_BAR; PG8_SCHED;
;             PG8_LDA(At, 1, 1); PG8_STAGE(PG8_SB(1, 0), b3, voffB); PG8_STAGE(PG8_SB(1, 1), b3 + hstepB, voffB); PG8_STAGE(PG8_SA(1, 0), a3, voffA);
;             PG8_WAIT_V(8); PG8_WAIT_L(0); PG8_BAR; PG8_MMA(1, 0, At, B0); PG8_MMA(1, 1, At, B1); PG8_BAR; PG8_SCHED;
;         }
;         if constexpr (ALIGN_EPI) { if (wr == 0) PG8_BAR; }
;         E(acc, cur, wr, wc, fr, fq);
;         if (!has_next) break;
	v_add_u32_e32 v132, 0x18000, v244
	v_add_u32_e32 v152, 0x1c000, v244
	ds_read_b128 v[108:111], v132
	ds_read_b128 v[120:123], v132 offset:1024
	ds_read_b128 v[128:131], v132 offset:2048
	ds_read_b128 v[132:135], v132 offset:3072
	ds_read_b128 v[136:139], v152
	ds_read_b128 v[144:147], v152 offset:1024
	ds_read_b128 v[148:151], v152 offset:2048
	ds_read_b128 v[152:155], v152 offset:3072
	ds_read_b128 v[156:159], v245 offset:32768
	ds_read_b128 v[160:163], v245 offset:33792
	ds_read_b128 v[164:167], v245 offset:34816
	ds_read_b128 v[176:179], v245 offset:35840
	ds_read_b128 v[180:183], v245 offset:36864
	ds_read_b128 v[184:187], v245 offset:37888
	ds_read_b128 v[188:191], v245 offset:38912
	ds_read_b128 v[202:205], v245 offset:39936
	s_add_u32 s56, s56, s15
	s_addc_u32 s57, s57, 0
	s_mov_b32 m0, s41
	s_nop 0
	global_load_lds_dwordx4 v0, s[56:57]
	s_nop 0
	s_mov_b32 m0, s42
	s_nop 0
	global_load_lds_dwordx4 v240, s[56:57]
	s_waitcnt vmcnt(8)
	s_waitcnt lgkmcnt(0)
	s_barrier
	s_waitcnt lgkmcnt(0)
	v_mfma_f32_16x16x32_bf16 v[172:175], v[108:111], v[156:159], v[172:175]
	v_mfma_f32_16x16x32_bf16 v[172:175], v[120:123], v[160:163], v[172:175]
	v_mfma_f32_16x16x32_bf16 v[168:171], v[128:131], v[156:159], v[168:171]
	v_mfma_f32_16x16x32_bf16 v[168:171], v[132:135], v[160:163], v[168:171]
	v_mfma_f32_16x16x32_bf16 v[140:143], v[136:139], v[156:159], v[140:143]
	v_mfma_f32_16x16x32_bf16 v[140:143], v[144:147], v[160:163], v[140:143]
	v_mfma_f32_16x16x32_bf16 v[124:127], v[148:151], v[156:159], v[124:127]
	v_mfma_f32_16x16x32_bf16 v[124:127], v[152:155], v[160:163], v[124:127]
	v_mfma_f32_16x16x32_bf16 v[100:103], v[148:151], v[164:167], v[100:103]
	v_mfma_f32_16x16x32_bf16 v[100:103], v[152:155], v[176:179], v[100:103]
	v_mfma_f32_16x16x32_bf16 v[104:107], v[136:139], v[164:167], v[104:107]
	v_mfma_f32_16x16x32_bf16 v[104:107], v[144:147], v[176:179], v[104:107]
	v_mfma_f32_16x16x32_bf16 v[112:115], v[128:131], v[164:167], v[112:115]
	v_mfma_f32_16x16x32_bf16 v[112:115], v[132:135], v[176:179], v[112:115]
	v_mfma_f32_16x16x32_bf16 v[116:119], v[108:111], v[164:167], v[116:119]
	v_mfma_f32_16x16x32_bf16 v[116:119], v[120:123], v[176:179], v[116:119]
	v_mfma_f32_16x16x32_bf16 v[96:99], v[108:111], v[180:183], v[96:99]
	v_mfma_f32_16x16x32_bf16 v[96:99], v[120:123], v[184:187], v[96:99]
	v_mfma_f32_16x16x32_bf16 v[92:95], v[128:131], v[180:183], v[92:95]
	v_mfma_f32_16x16x32_bf16 v[92:95], v[132:135], v[184:187], v[92:95]
	v_mfma_f32_16x16x32_bf16 v[88:91], v[136:139], v[180:183], v[88:91]
	v_mfma_f32_16x16x32_bf16 v[88:91], v[144:147], v[184:187], v[88:91]
	v_mfma_f32_16x16x32_bf16 v[84:87], v[148:151], v[180:183], v[84:87]
	v_mfma_f32_16x16x32_bf16 v[84:87], v[152:155], v[184:187], v[84:87]
	v_mfma_f32_16x16x32_bf16 v[68:71], v[148:151], v[188:191], v[68:71]
	v_mfma_f32_16x16x32_bf16 v[68:71], v[152:155], v[202:205], v[68:71]
	v_mfma_f32_16x16x32_bf16 v[72:75], v[136:139], v[188:191], v[72:75]
	v_mfma_f32_16x16x32_bf16 v[72:75], v[144:147], v[202:205], v[72:75]
	v_mfma_f32_16x16x32_bf16 v[76:79], v[128:131], v[188:191], v[76:79]
	v_mfma_f32_16x16x32_bf16 v[76:79], v[132:135], v[202:205], v[76:79]
	v_mfma_f32_16x16x32_bf16 v[80:83], v[108:111], v[188:191], v[80:83]
	v_mfma_f32_16x16x32_bf16 v[80:83], v[120:123], v[202:205], v[80:83]
	s_barrier
	ds_read_b128 v[156:159], v245 offset:49152
	ds_read_b128 v[160:163], v245 offset:50176
	ds_read_b128 v[164:167], v245 offset:51200
	ds_read_b128 v[176:179], v245 offset:52224
	ds_read_b128 v[180:183], v245 offset:53248
	ds_read_b128 v[184:187], v245 offset:54272
	ds_read_b128 v[188:191], v245 offset:55296
	ds_read_b128 v[202:205], v245 offset:56320
	s_add_u32 s54, s54, 0x80
	s_addc_u32 s55, s55, 0
	s_mov_b32 m0, s46
	s_nop 0
	global_load_lds_dwordx4 v195, s[54:55]
	s_nop 0
	s_mov_b32 m0, s50
	s_nop 0
	global_load_lds_dwordx4 v241, s[54:55]
	s_add_u32 s54, s58, 0x80
	s_addc_u32 s55, s59, 0
	s_mov_b32 m0, s61
	s_nop 0
	global_load_lds_dwordx4 v195, s[54:55]
	s_nop 0
	s_mov_b32 m0, s65
	s_nop 0
	global_load_lds_dwordx4 v241, s[54:55]
	s_nop 0
	s_mov_b32 m0, s53
	s_nop 0
	global_load_lds_dwordx4 v0, s[48:49]
	s_nop 0
	s_mov_b32 m0, s60
	s_nop 0
	global_load_lds_dwordx4 v240, s[48:49]
	s_waitcnt vmcnt(8)
	s_waitcnt lgkmcnt(0)
	s_barrier
	s_waitcnt lgkmcnt(0)
	v_mfma_f32_16x16x32_bf16 v[64:67], v[108:111], v[156:159], v[64:67]
	v_mfma_f32_16x16x32_bf16 v[64:67], v[120:123], v[160:163], v[64:67]
	v_mfma_f32_16x16x32_bf16 v[60:63], v[128:131], v[156:159], v[60:63]
	v_mfma_f32_16x16x32_bf16 v[60:63], v[132:135], v[160:163], v[60:63]
	v_mfma_f32_16x16x32_bf16 v[56:59], v[136:139], v[156:159], v[56:59]
	v_mfma_f32_16x16x32_bf16 v[56:59], v[144:147], v[160:163], v[56:59]
	v_mfma_f32_16x16x32_bf16 v[52:55], v[148:151], v[156:159], v[52:55]
	v_mfma_f32_16x16x32_bf16 v[52:55], v[152:155], v[160:163], v[52:55]
	v_mfma_f32_16x16x32_bf16 v[36:39], v[148:151], v[164:167], v[36:39]
	v_mfma_f32_16x16x32_bf16 v[36:39], v[152:155], v[176:179], v[36:39]
	v_mfma_f32_16x16x32_bf16 v[40:43], v[136:139], v[164:167], v[40:43]
	v_mfma_f32_16x16x32_bf16 v[40:43], v[144:147], v[176:179], v[40:43]
	v_mfma_f32_16x16x32_bf16 v[44:47], v[128:131], v[164:167], v[44:47]
	v_mfma_f32_16x16x32_bf16 v[44:47], v[132:135], v[176:179], v[44:47]
	v_mfma_f32_16x16x32_bf16 v[48:51], v[108:111], v[164:167], v[48:51]
	v_mfma_f32_16x16x32_bf16 v[48:51], v[120:123], v[176:179], v[48:51]
	v_mfma_f32_16x16x32_bf16 v[32:35], v[108:111], v[180:183], v[32:35]
	v_mfma_f32_16x16x32_bf16 v[32:35], v[120:123], v[184:187], v[32:35]
	v_mfma_f32_16x16x32_bf16 v[28:31], v[128:131], v[180:183], v[28:31]
	v_mfma_f32_16x16x32_bf16 v[28:31], v[132:135], v[184:187], v[28:31]
	v_mfma_f32_16x16x32_bf16 v[24:27], v[136:139], v[180:183], v[24:27]
	v_mfma_f32_16x16x32_bf16 v[24:27], v[144:147], v[184:187], v[24:27]
	v_mfma_f32_16x16x32_bf16 v[20:23], v[148:151], v[180:183], v[20:23]
	v_mfma_f32_16x16x32_bf16 v[20:23], v[152:155], v[184:187], v[20:23]
	v_mfma_f32_16x16x32_bf16 v[4:7], v[148:151], v[188:191], v[4:7]
	v_mfma_f32_16x16x32_bf16 v[4:7], v[152:155], v[202:205], v[4:7]
	v_mfma_f32_16x16x32_bf16 v[8:11], v[136:139], v[188:191], v[8:11]
	v_mfma_f32_16x16x32_bf16 v[8:11], v[144:147], v[202:205], v[8:11]
	v_mfma_f32_16x16x32_bf16 v[12:15], v[128:131], v[188:191], v[12:15]
	v_mfma_f32_16x16x32_bf16 v[12:15], v[132:135], v[202:205], v[12:15]
	v_mfma_f32_16x16x32_bf16 v[16:19], v[108:111], v[188:191], v[16:19]
	v_mfma_f32_16x16x32_bf16 v[16:19], v[120:123], v[202:205], v[16:19]
	s_barrier
	s_add_u32 s4, s4, 0x100
	s_addc_u32 s5, s5, 0
	s_add_u32 s37, s37, 0x100
	s_addc_u32 s44, s44, 0
	s_cmp_ge_u32 s51, s43
	s_mov_b32 s45, s51
	s_cbranch_scc0 .LBB0_151
	s_and_b64 vcc, exec, s[92:93]
	s_cbranch_vccz .LBB0_154
	s_barrier

; #define PG8_WAIT_V(n) asm volatile("s_waitcnt vmcnt(" #n ")" ::: "memory")
; #define PG8_BAR __builtin_amdgcn_s_barrier()
; template <class Epi, bool ALIGN_EPI>
; __device__ __forceinline__ void gemm_phase(LAS unsigned char* lds, const Gemm g, const StaticOrder& S, const Epi& E) {
;     ...
;     PG8_WAIT_V(0);
;     if constexpr (!ALIGN_EPI) { if (wr == 0) PG8_BAR; }
;     PG8_BAR;
.LBB0_175:
	s_setprio 0
	s_waitcnt vmcnt(0)
	v_readlane_b32 s53, v254, 43
	v_readlane_b32 s65, v254, 42
	v_readlane_b32 s67, v254, 41
	v_readlane_b32 s80, v254, 40
	v_readlane_b32 s85, v254, 39
	v_readlane_b32 s43, v255, 8
	s_barrier

; #define PG8_WAIT_V(n) asm volatile("s_waitcnt vmcnt(" #n ")" ::: "memory")
; #define PG8_BAR __builtin_amdgcn_s_barrier()
; template <class Epi, bool ALIGN_EPI>
; __device__ __forceinline__ void gemm_phase(LAS unsigned char* lds, const Gemm g, const StaticOrder& S, const Epi& E) {
;     int tid = threadIdx.x; asm volatile("" : "+v"(tid));
;     const int wid = __builtin_amdgcn_readfirstlane(tid >> 6), lane = tid & 63, wr = wid >> 2, wc = wid & 3, fr = lane & 15, fq = lane >> 4;
;     const int K = g.K, nt = K / BK, lda = g.lda;
;     unsigned voffA[2], voffB[2];
; #pragma unroll
;     for (int i = 0; i < 2; ++i) { int R, C; stage_rc(tid * 16 + i * 8192, R, C); const int Rb = (R & ~31) + perm32(R & 31);
;         voffA[i] = (unsigned)(R * lda + C) * 2u; voffB[i] = (unsigned)(Rb * K + C) * 2u; }
;     const size_t kstep = (size_t)(BK * 2);
;     const size_t hstepA = (size_t)HALF * lda * 2, hstepB = (size_t)HALF * K * 2;
;     const size_t tstepA = 2 * hstepA, tstepB = 2 * hstepB;
;     const unsigned ldsw = (unsigned)wid * 1024u;
;     const unsigned ldsb = (unsigned)(unsigned long)lds + ldsw;
;     const int aoff = lds_byte(wr * 64 + fr, fq * 8), boff = lds_byte(wc * 32 + fr, fq * 8);
;     ...
;     Unit cur, nxt; int ui = 0;
;     if (!S.next(0, cur)) return;
;     f32x4 acc[2][2][4][2];
; #pragma unroll
;     for (int a = 0; a < 2; ++a)
; #pragma unroll
;         for (int b = 0; b < 2; ++b)
; #pragma unroll
;             for (int m = 0; m < 4; ++m)
; #pragma unroll
;                 for (int n = 0; n < 2; ++n) acc[a][b][m][n] = (f32x4){0.f, 0.f, 0.f, 0.f};
;     bf16x8 At[4][2], B0[2][2], B1[2][2];
;     const char* cA = (const char*)g.A + (size_t)cur.pm * tstepA + (size_t)cur.pn * g.a_pn_off * 2 + (size_t)(cur.pm >> 4) * g.a_adj; const char* cB = (const char*)g.Bt + (size_t)cur.pn * tstepB;
;     PG8_STAGE(PG8_SB(0, 0), cB, voffB); PG8_STAGE(PG8_SB(0, 1), cB + hstepB, voffB); PG8_STAGE(PG8_SA(0, 0), cA, voffA); PG8_STAGE(PG8_SA(0, 1), cA + hstepA, voffA);
;     if (wr == 1) PG8_BAR;
;     PG8_WAIT_V(2); PG8_BAR;
;     PG8_STAGE(PG8_SB(1, 0), cB + kstep, voffB); PG8_STAGE(PG8_SA(1, 0), cA + kstep, voffA); PG8_STAGE(PG8_SB(1, 1), cB + hstepB + kstep, voffB);
.LBB0_184:
	s_andn2_b64 vcc, exec, s[0:1]
	s_cbranch_vccnz .LBB0_242
	v_bfe_i32 v4, v2, 27, 1
	v_lshlrev_b32_e32 v3, 4, v2
	v_lshrrev_b32_e32 v4, 22, v4
	v_add_u32_e32 v4, v3, v4
	v_and_b32_e32 v4, 0xfffffc00, v4
	v_sub_u32_e32 v4, v3, v4
	v_lshrrev_b32_e32 v5, 4, v4
	v_ashrrev_i32_e32 v0, 31, v2
	v_bitop3_b32 v4, v5, v4, 32 bitop3:0x6c
	v_lshrrev_b32_e32 v0, 26, v0
	v_ashrrev_i32_e32 v6, 31, v4
	v_add_u32_e32 v0, v2, v0
	v_lshrrev_b32_e32 v6, 26, v6
	v_ashrrev_i32_e32 v0, 6, v0
	v_add_u32_e32 v6, v4, v6
	v_lshlrev_b32_e32 v5, 3, v0
	v_ashrrev_i32_e32 v7, 6, v6
	v_and_b32_e32 v6, 0xc0, v6
	v_and_b32_e32 v5, -16, v5
	v_lshlrev_b32_e32 v0, 5, v0
	v_sub_u32_e32 v4, v4, v6
	v_add_u32_e32 v5, v7, v5
	v_and_b32_e32 v0, 32, v0
	v_ashrrev_i16_sdwa v4, v223, sext(v4) dst_sel:DWORD dst_unused:UNUSED_PAD src0_sel:DWORD src1_sel:BYTE_0
	v_add_u32_sdwa v4, v0, sext(v4) dst_sel:DWORD dst_unused:UNUSED_PAD src0_sel:DWORD src1_sel:WORD_0
	v_lshlrev_b32_e32 v0, 1, v5
	v_lshrrev_b32_e32 v6, 2, v5
	v_and_b32_e32 v7, 3, v7
	s_mov_b32 s0, 0x7fffffe0
	v_and_b32_e32 v0, 24, v0
	v_and_b32_e32 v6, 4, v6
	v_and_or_b32 v7, v5, s0, v7
	v_or3_b32 v6, v7, v6, v0
	v_mul_lo_u32 v0, v5, s43
	v_mul_lo_u32 v5, v6, s43
	v_add_u32_e32 v3, 0x2000, v3
	v_add_lshl_u32 v0, v4, v0, 1
	v_add_lshl_u32 v195, v5, v4, 1
	v_ashrrev_i32_e32 v4, 31, v3
	v_lshrrev_b32_e32 v4, 22, v4
	v_add_u32_e32 v4, v3, v4
	v_ashrrev_i32_e32 v4, 10, v4
	v_mul_i32_i24_e32 v5, 0x400, v4
	v_sub_u32_e32 v3, v3, v5
	v_lshrrev_b32_e32 v5, 4, v3
	v_bitop3_b32 v3, v5, v3, 32 bitop3:0x6c
	v_writelane_b32 v254, s85, 39
	v_ashrrev_i32_e32 v6, 31, v3
	v_writelane_b32 v254, s80, 40
	v_lshrrev_b32_e32 v6, 26, v6
	v_writelane_b32 v254, s67, 41
	v_lshlrev_b32_e32 v5, 3, v4
	v_add_u32_e32 v6, v3, v6
	v_writelane_b32 v254, s65, 42
	v_and_b32_e32 v5, -16, v5
	v_ashrrev_i32_e32 v7, 6, v6
	v_writelane_b32 v254, s53, 43
	s_ashr_i32 s4, s6, 6
	v_add_u32_e32 v5, v7, v5
	v_and_b32_e32 v7, 3, v7
	v_writelane_b32 v254, s75, 58
	v_and_b32_e32 v6, 0xc0, v6
	v_and_or_b32 v7, v5, s0, v7
	s_lshl_b32 s78, s43, 9
	s_lshl_b32 s0, s4, 10
	v_lshlrev_b32_e32 v4, 5, v4
	v_sub_u32_e32 v3, v3, v6
	s_ashr_i32 s5, s6, 8
	s_lshl_b32 s38, s43, 8
	s_add_i32 s29, s0, 0
	s_ashr_i32 s7, s14, 4
	v_readlane_b32 s9, v254, 48
	s_mul_i32 s15, s78, s96
	v_readlane_b32 s17, v254, 46
	v_and_b32_e32 v4, 32, v4
	v_ashrrev_i16_sdwa v3, v223, sext(v3) dst_sel:DWORD dst_unused:UNUSED_PAD src0_sel:DWORD src1_sel:BYTE_0
	s_mul_hi_i32 s8, s7, s9
	s_mul_i32 s7, s7, s9
	s_mul_hi_i32 s9, s78, s96
	s_add_u32 s48, s17, s15
	v_readlane_b32 s15, v254, 44
	v_add_u32_sdwa v3, v4, sext(v3) dst_sel:DWORD dst_unused:UNUSED_PAD src0_sel:DWORD src1_sel:WORD_0
	v_lshlrev_b32_e32 v4, 1, v5
	v_lshrrev_b32_e32 v6, 2, v5
	s_mul_i32 s1, s78, s14
	s_addc_u32 s49, s15, s9
	s_add_i32 s46, s29, 0x10000
	s_add_i32 s26, s29, 0x12000
	v_and_b32_e32 v4, 24, v4
	v_and_b32_e32 v6, 4, v6
	s_mul_hi_i32 s0, s78, s14
	s_add_u32 s9, s10, s1
	v_or3_b32 v4, v7, v6, v4
	s_addc_u32 s15, s11, s0
	s_add_i32 s27, s29, 0x14000
	v_mul_lo_u32 v4, v4, s43
	s_mov_b32 m0, s46
	s_nop 0
	global_load_lds_dwordx4 v195, s[48:49]
	s_add_u32 s0, s48, s38
	v_add_lshl_u32 v207, v4, v3, 1
	s_mov_b32 m0, s26
	s_nop 0
	global_load_lds_dwordx4 v207, s[48:49]
	s_addc_u32 s1, s49, 0
	s_add_i32 s30, s29, 0x16000
	s_mov_b32 m0, s27
	s_nop 0
	global_load_lds_dwordx4 v195, s[0:1]
	s_add_u32 s54, s9, s7
	s_mov_b32 m0, s30
	s_nop 0
	global_load_lds_dwordx4 v207, s[0:1]
	s_addc_u32 s55, s15, s8
	s_add_i32 s17, s29, 0x2000
	s_add_i32 s31, s29, 0x4000
	v_mul_lo_u32 v5, v5, s43
	s_mov_b32 m0, s29
	s_nop 0
	global_load_lds_dwordx4 v0, s[54:55]
	s_add_u32 s8, s54, s38
	v_add_lshl_u32 v206, v3, v5, 1
	s_mov_b32 m0, s17
	s_nop 0
	global_load_lds_dwordx4 v206, s[54:55]
	s_addc_u32 s9, s55, 0
	s_add_i32 s53, s29, 0x6000
	s_mov_b32 m0, s31
	s_nop 0
	global_load_lds_dwordx4 v0, s[8:9]
	s_cmp_eq_u32 s5, 1
	s_mov_b32 m0, s53
	s_nop 0
	global_load_lds_dwordx4 v206, s[8:9]
	s_cselect_b64 s[8:9], -1, 0
	v_writelane_b32 v255, s8, 2
	s_cmp_lg_u32 s5, 1
	s_nop 0
	v_writelane_b32 v255, s9, 3
	s_cbranch_scc1 .LBB0_187
	s_barrier
	s_setprio 1

; #define PG8_STAGE(bufoff, gbase, voff) do { _Pragma("unroll") for (int _i = 0; _i < 2; ++_i) { \
;         const unsigned _m0 = ldsb + (unsigned)((bufoff) + _i * 8192); const char* _gb = (const char*)(gbase); \
;         asm volatile("s_mov_b32 m0, %0\n\ts_nop 0\n\tglobal_load_lds_dwordx4 %1, %2" :: "s"(_m0), "v"((voff)[_i]), "s"(_gb) : "m0", "memory"); } } while (0)
; #define PG8_LDA(dst, b, h) do { _Pragma("unroll") for (int m = 0; m < 4; ++m) _Pragma("unroll") for (int k = 0; k < 2; ++k) dst[m][k] = *(const LAS bf16x8*)(lds + PG8_SA(b, h) + aoff + m * 2048 + k * 1024); } while (0)
; #define PG8_LDB(dst, b, h) do { _Pragma("unroll") for (int n = 0; n < 2; ++n) _Pragma("unroll") for (int k = 0; k < 2; ++k) dst[n][k] = *(const LAS bf16x8*)(lds + PG8_SB(b, h) + boff + n * 2048 + k * 1024); } while (0)
; #define PG8_WAIT_V(n) asm volatile("s_waitcnt vmcnt(" #n ")" ::: "memory")
; #define PG8_WAIT_L(n) asm volatile("s_waitcnt lgkmcnt(" #n ")" ::: "memory")
; #define PG8_BAR __builtin_amdgcn_s_barrier()
; #define PG8_SCHED __builtin_amdgcn_sched_barrier(0)
; template <class Epi, bool ALIGN_EPI>
; __device__ __forceinline__ void gemm_phase(LAS unsigned char* lds, const Gemm g, const StaticOrder& S, const Epi& E) {
;     ...
;         const bool has_next = S.next(ui + 1, nxt);
;         const char* nA = has_next ? (const char*)g.A + (size_t)nxt.pm * tstepA + (size_t)nxt.pn * g.a_pn_off * 2 + (size_t)(nxt.pm >> 4) * g.a_adj : cA; const char* nB = has_next ? (const char*)g.Bt + (size_t)nxt.pn * tstepB : cB;
;         for (int t = 0; t < nt; t += 2) {
;             const bool last = (t == nt - 2);
;             const char* a1 = cA + (size_t)(t + 1) * kstep;
;             const char* a2 = last ? nA : cA + (size_t)(t + 2) * kstep; const char* b2 = last ? nB : cB + (size_t)(t + 2) * kstep;
;             const char* a3 = a2 + kstep; const char* b3 = b2 + kstep;
;             PG8_LDB(B0, 0, 0); PG8_LDB(B1, 0, 1); PG8_SCHED; PG8_LDA(At, 0, 0); PG8_STAGE(PG8_SA(1, 1), a1 + hstepA, voffA);
;             PG8_WAIT_V(8); PG8_WAIT_L(0); PG8_BAR; PG8_MMA(0, 0, At, B0); PG8_MMA(0, 1, At, B1); PG8_BAR; PG8_SCHED;
;             PG8_LDA(At, 0, 1); PG8_STAGE(PG8_SB(0, 0), b2, voffB); PG8_STAGE(PG8_SB(0, 1), b2 + hstepB, voffB); PG8_STAGE(PG8_SA(0, 0), a2, voffA);
;             PG8_WAIT_V(8); PG8_WAIT_L(0); PG8_BAR; PG8_MMA(1, 0, At, B0); PG8_MMA(1, 1, At, B1); PG8_BAR; PG8_SCHED;
.LBB0_200:
	s_add_u32 s4, s48, 0x100
	s_addc_u32 s5, s49, 0
	s_add_u32 s15, s54, 0x100
	s_addc_u32 s42, s55, 0
	s_mov_b32 s43, 0
	s_add_i32 s44, s43, 2
	s_cmp_eq_u32 s68, s43
	s_cselect_b32 s56, s0, s15
	s_cselect_b32 s57, s1, s42
	s_cselect_b32 s54, s94, s4
	s_cselect_b32 s55, s95, s5
	s_add_u32 s48, s56, 0x80
	s_addc_u32 s49, s57, 0
	s_add_u32 s43, s15, s38
	s_addc_u32 s45, s42, 0
	s_add_u32 s58, s43, 0xffffff80
	s_addc_u32 s59, s45, -1
	s_mov_b32 m0, s37
	s_nop 0
	global_load_lds_dwordx4 v0, s[58:59]
	s_nop 0
	s_mov_b32 m0, s41
	s_nop 0
	global_load_lds_dwordx4 v206, s[58:59]
	s_waitcnt vmcnt(8)
	s_waitcnt lgkmcnt(0)
	s_barrier
	s_waitcnt lgkmcnt(0)
	v_mfma_f32_16x16x32_bf16 v[126:129], v[130:133], v[162:165], 0
	v_mfma_f32_16x16x32_bf16 v[126:129], v[134:137], v[166:169], v[126:129]
	v_mfma_f32_16x16x32_bf16 v[122:125], v[138:141], v[162:165], 0
	v_mfma_f32_16x16x32_bf16 v[122:125], v[142:145], v[166:169], v[122:125]
	v_mfma_f32_16x16x32_bf16 v[118:121], v[146:149], v[162:165], 0
	v_mfma_f32_16x16x32_bf16 v[118:121], v[150:153], v[166:169], v[118:121]
	v_mfma_f32_16x16x32_bf16 v[114:117], v[154:157], v[162:165], 0
	v_mfma_f32_16x16x32_bf16 v[114:117], v[158:161], v[166:169], v[114:117]
	v_mfma_f32_16x16x32_bf16 v[98:101], v[154:157], v[170:173], 0
	v_mfma_f32_16x16x32_bf16 v[98:101], v[158:161], v[174:177], v[98:101]
	v_mfma_f32_16x16x32_bf16 v[102:105], v[146:149], v[170:173], 0
	v_mfma_f32_16x16x32_bf16 v[102:105], v[150:153], v[174:177], v[102:105]
	v_mfma_f32_16x16x32_bf16 v[106:109], v[138:141], v[170:173], 0
	v_mfma_f32_16x16x32_bf16 v[106:109], v[142:145], v[174:177], v[106:109]
	v_mfma_f32_16x16x32_bf16 v[110:113], v[130:133], v[170:173], 0
	v_mfma_f32_16x16x32_bf16 v[110:113], v[134:137], v[174:177], v[110:113]
	v_mfma_f32_16x16x32_bf16 v[94:97], v[130:133], v[178:181], 0
	v_mfma_f32_16x16x32_bf16 v[94:97], v[134:137], v[182:185], v[94:97]
	v_mfma_f32_16x16x32_bf16 v[90:93], v[138:141], v[178:181], 0
	v_mfma_f32_16x16x32_bf16 v[90:93], v[142:145], v[182:185], v[90:93]
	v_mfma_f32_16x16x32_bf16 v[86:89], v[146:149], v[178:181], 0
	v_mfma_f32_16x16x32_bf16 v[86:89], v[150:153], v[182:185], v[86:89]
	v_mfma_f32_16x16x32_bf16 v[82:85], v[154:157], v[178:181], 0
	v_mfma_f32_16x16x32_bf16 v[82:85], v[158:161], v[182:185], v[82:85]
	v_mfma_f32_16x16x32_bf16 v[66:69], v[154:157], v[186:189], 0
	v_mfma_f32_16x16x32_bf16 v[66:69], v[158:161], v[190:193], v[66:69]
	v_mfma_f32_16x16x32_bf16 v[70:73], v[146:149], v[186:189], 0
	v_mfma_f32_16x16x32_bf16 v[70:73], v[150:153], v[190:193], v[70:73]
	v_mfma_f32_16x16x32_bf16 v[74:77], v[138:141], v[186:189], 0
	v_mfma_f32_16x16x32_bf16 v[74:77], v[142:145], v[190:193], v[74:77]
	v_mfma_f32_16x16x32_bf16 v[78:81], v[130:133], v[186:189], 0
	v_mfma_f32_16x16x32_bf16 v[78:81], v[134:137], v[190:193], v[78:81]
	s_barrier
	ds_read_b128 v[162:165], v246 offset:16384
	ds_read_b128 v[166:169], v246 offset:17408
	ds_read_b128 v[170:173], v246 offset:18432
	ds_read_b128 v[174:177], v246 offset:19456
	ds_read_b128 v[178:181], v246 offset:20480
	ds_read_b128 v[182:185], v246 offset:21504
	ds_read_b128 v[186:189], v246 offset:22528
	ds_read_b128 v[190:193], v246 offset:23552
	s_mov_b32 m0, s46
	s_nop 0
	global_load_lds_dwordx4 v195, s[54:55]
	s_add_u32 s58, s54, s38
	s_mov_b32 m0, s26
	s_nop 0
	global_load_lds_dwordx4 v207, s[54:55]
	s_addc_u32 s59, s55, 0
	s_mov_b32 m0, s27
	s_nop 0
	global_load_lds_dwordx4 v195, s[58:59]
	s_nop 0
	s_mov_b32 m0, s30
	s_nop 0
	global_load_lds_dwordx4 v207, s[58:59]
	s_nop 0
	s_mov_b32 m0, s29
	s_nop 0
	global_load_lds_dwordx4 v0, s[56:57]
	s_nop 0
	s_mov_b32 m0, s17
	s_nop 0
	global_load_lds_dwordx4 v206, s[56:57]
	s_waitcnt vmcnt(8)
	s_waitcnt lgkmcnt(0)
	s_barrier
	s_waitcnt lgkmcnt(0)
	v_mfma_f32_16x16x32_bf16 v[62:65], v[130:133], v[162:165], 0
	v_mfma_f32_16x16x32_bf16 v[62:65], v[134:137], v[166:169], v[62:65]
	v_mfma_f32_16x16x32_bf16 v[58:61], v[138:141], v[162:165], 0
	v_mfma_f32_16x16x32_bf16 v[58:61], v[142:145], v[166:169], v[58:61]
	v_mfma_f32_16x16x32_bf16 v[54:57], v[146:149], v[162:165], 0
	v_mfma_f32_16x16x32_bf16 v[54:57], v[150:153], v[166:169], v[54:57]
	v_mfma_f32_16x16x32_bf16 v[50:53], v[154:157], v[162:165], 0
	v_mfma_f32_16x16x32_bf16 v[50:53], v[158:161], v[166:169], v[50:53]
	v_mfma_f32_16x16x32_bf16 v[34:37], v[154:157], v[170:173], 0
	v_mfma_f32_16x16x32_bf16 v[34:37], v[158:161], v[174:177], v[34:37]
	v_mfma_f32_16x16x32_bf16 v[38:41], v[146:149], v[170:173], 0
	v_mfma_f32_16x16x32_bf16 v[38:41], v[150:153], v[174:177], v[38:41]
	v_mfma_f32_16x16x32_bf16 v[42:45], v[138:141], v[170:173], 0
	v_mfma_f32_16x16x32_bf16 v[42:45], v[142:145], v[174:177], v[42:45]
	v_mfma_f32_16x16x32_bf16 v[46:49], v[130:133], v[170:173], 0
	v_mfma_f32_16x16x32_bf16 v[46:49], v[134:137], v[174:177], v[46:49]
	v_mfma_f32_16x16x32_bf16 v[30:33], v[130:133], v[178:181], 0
	v_mfma_f32_16x16x32_bf16 v[30:33], v[134:137], v[182:185], v[30:33]
	v_mfma_f32_16x16x32_bf16 v[26:29], v[138:141], v[178:181], 0
	v_mfma_f32_16x16x32_bf16 v[26:29], v[142:145], v[182:185], v[26:29]
	v_mfma_f32_16x16x32_bf16 v[22:25], v[146:149], v[178:181], 0
	v_mfma_f32_16x16x32_bf16 v[22:25], v[150:153], v[182:185], v[22:25]
	v_mfma_f32_16x16x32_bf16 v[18:21], v[154:157], v[178:181], 0
	v_mfma_f32_16x16x32_bf16 v[18:21], v[158:161], v[182:185], v[18:21]
	v_mfma_f32_16x16x32_bf16 v[2:5], v[154:157], v[186:189], 0
	v_mfma_f32_16x16x32_bf16 v[2:5], v[158:161], v[190:193], v[2:5]
	v_mfma_f32_16x16x32_bf16 v[6:9], v[146:149], v[186:189], 0
	v_mfma_f32_16x16x32_bf16 v[6:9], v[150:153], v[190:193], v[6:9]
	v_mfma_f32_16x16x32_bf16 v[10:13], v[138:141], v[186:189], 0
	v_mfma_f32_16x16x32_bf16 v[10:13], v[142:145], v[190:193], v[10:13]
	v_mfma_f32_16x16x32_bf16 v[14:17], v[130:133], v[186:189], 0
	v_mfma_f32_16x16x32_bf16 v[14:17], v[134:137], v[190:193], v[14:17]
	s_barrier
; #define PG8_STAGE(bufoff, gbase, voff) do { _Pragma("unroll") for (int _i = 0; _i < 2; ++_i) { \
;         const unsigned _m0 = ldsb + (unsigned)((bufoff) + _i * 8192); const char* _gb = (const char*)(gbase); \
;         asm volatile("s_mov_b32 m0, %0\n\ts_nop 0\n\tglobal_load_lds_dwordx4 %1, %2" :: "s"(_m0), "v"((voff)[_i]), "s"(_gb) : "m0", "memory"); } } while (0)
; #define PG8_LDA(dst, b, h) do { _Pragma("unroll") for (int m = 0; m < 4; ++m) _Pragma("unroll") for (int k = 0; k < 2; ++k) dst[m][k] = *(const LAS bf16x8*)(lds + PG8_SA(b, h) + aoff + m * 2048 + k * 1024); } while (0)
; #define PG8_LDB(dst, b, h) do { _Pragma("unroll") for (int n = 0; n < 2; ++n) _Pragma("unroll") for (int k = 0; k < 2; ++k) dst[n][k] = *(const LAS bf16x8*)(lds + PG8_SB(b, h) + boff + n * 2048 + k * 1024); } while (0)
; #define PG8_MMA(ai, bj, At, Bt) do { __builtin_amdgcn_s_setprio(1); _Pragma("unroll") for (int m = 0; m < 4; ++m) _Pragma("unroll") for (int n = 0; n < 2; ++n) _Pragma("unroll") for (int k = 0; k < 2; ++k) \
;         acc[ai][bj][m][n] = __builtin_amdgcn_mfma_f32_16x16x32_bf16(Bt[n][k], At[m][k], acc[ai][bj][m][n], 0, 0, 0); __builtin_amdgcn_s_setprio(0); } while (0)
; #define PG8_WAIT_V(n) asm volatile("s_waitcnt vmcnt(" #n ")" ::: "memory")
; #define PG8_WAIT_L(n) asm volatile("s_waitcnt lgkmcnt(" #n ")" ::: "memory")
; #define PG8_BAR __builtin_amdgcn_s_barrier()
; #define PG8_SCHED __builtin_amdgcn_sched_barrier(0)
; template <class Epi, bool ALIGN_EPI>
; __device__ __forceinline__ void gemm_phase(LAS unsigned char* lds, const Gemm g, const StaticOrder& S, const Epi& E) {
;     ...
;             PG8_LDB(B0, 1, 0); PG8_LDB(B1, 1, 1); PG8_SCHED; PG8_LDA(At, 1, 0); PG8_STAGE(PG8_SA(0, 1), a2 + hstepA, voffA);
;             PG8_WAIT_V(8); PG8_WAIT_L(0); PG8_BAR; PG8_MMA(0, 0, At, B0); PG8_MMA(0, 1, At, B1); PG8_BAR; PG8_SCHED;
;             PG8_LDA(At, 1, 1); PG8_STAGE(PG8_SB(1, 0), b3, voffB); PG8_STAGE(PG8_SB(1, 1), b3 + hstepB, voffB); PG8_STAGE(PG8_SA(1, 0), a3, voffA);
;             PG8_WAIT_V(8); PG8_WAIT_L(0); PG8_BAR; PG8_MMA(1, 0, At, B0); PG8_MMA(1, 1, At, B1); PG8_BAR; PG8_SCHED;
;         }
;         if constexpr (ALIGN_EPI) { if (wr == 0) PG8_BAR; }
	v_add_u32_e32 v142, 0x18000, v245
	v_add_u32_e32 v158, 0x1c000, v245
	ds_read_b128 v[130:133], v142
	ds_read_b128 v[134:137], v142 offset:1024
	ds_read_b128 v[138:141], v142 offset:2048
	ds_read_b128 v[142:145], v142 offset:3072
	ds_read_b128 v[146:149], v158
	ds_read_b128 v[150:153], v158 offset:1024
	ds_read_b128 v[154:157], v158 offset:2048
	ds_read_b128 v[158:161], v158 offset:3072
	ds_read_b128 v[162:165], v246 offset:32768
	ds_read_b128 v[166:169], v246 offset:33792
	ds_read_b128 v[170:173], v246 offset:34816
	ds_read_b128 v[174:177], v246 offset:35840
	ds_read_b128 v[178:181], v246 offset:36864
	ds_read_b128 v[182:185], v246 offset:37888
	ds_read_b128 v[186:189], v246 offset:38912
	ds_read_b128 v[190:193], v246 offset:39936
	s_add_u32 s56, s56, s38
	s_addc_u32 s57, s57, 0
	s_mov_b32 m0, s31
	s_nop 0
	global_load_lds_dwordx4 v0, s[56:57]
	s_nop 0
	s_mov_b32 m0, s53
	s_nop 0
	global_load_lds_dwordx4 v206, s[56:57]
	s_waitcnt vmcnt(8)
	s_waitcnt lgkmcnt(0)
	s_barrier
	s_waitcnt lgkmcnt(0)
	v_mfma_f32_16x16x32_bf16 v[126:129], v[130:133], v[162:165], v[126:129]
	v_mfma_f32_16x16x32_bf16 v[126:129], v[134:137], v[166:169], v[126:129]
	v_mfma_f32_16x16x32_bf16 v[122:125], v[138:141], v[162:165], v[122:125]
	v_mfma_f32_16x16x32_bf16 v[122:125], v[142:145], v[166:169], v[122:125]
	v_mfma_f32_16x16x32_bf16 v[118:121], v[146:149], v[162:165], v[118:121]
	v_mfma_f32_16x16x32_bf16 v[118:121], v[150:153], v[166:169], v[118:121]
	v_mfma_f32_16x16x32_bf16 v[114:117], v[154:157], v[162:165], v[114:117]
	v_mfma_f32_16x16x32_bf16 v[114:117], v[158:161], v[166:169], v[114:117]
	v_mfma_f32_16x16x32_bf16 v[98:101], v[154:157], v[170:173], v[98:101]
	v_mfma_f32_16x16x32_bf16 v[98:101], v[158:161], v[174:177], v[98:101]
	v_mfma_f32_16x16x32_bf16 v[102:105], v[146:149], v[170:173], v[102:105]
	v_mfma_f32_16x16x32_bf16 v[102:105], v[150:153], v[174:177], v[102:105]
	v_mfma_f32_16x16x32_bf16 v[106:109], v[138:141], v[170:173], v[106:109]
	v_mfma_f32_16x16x32_bf16 v[106:109], v[142:145], v[174:177], v[106:109]
	v_mfma_f32_16x16x32_bf16 v[110:113], v[130:133], v[170:173], v[110:113]
	v_mfma_f32_16x16x32_bf16 v[110:113], v[134:137], v[174:177], v[110:113]
	v_mfma_f32_16x16x32_bf16 v[94:97], v[130:133], v[178:181], v[94:97]
	v_mfma_f32_16x16x32_bf16 v[94:97], v[134:137], v[182:185], v[94:97]
	v_mfma_f32_16x16x32_bf16 v[90:93], v[138:141], v[178:181], v[90:93]
	v_mfma_f32_16x16x32_bf16 v[90:93], v[142:145], v[182:185], v[90:93]
	v_mfma_f32_16x16x32_bf16 v[86:89], v[146:149], v[178:181], v[86:89]
	v_mfma_f32_16x16x32_bf16 v[86:89], v[150:153], v[182:185], v[86:89]
	v_mfma_f32_16x16x32_bf16 v[82:85], v[154:157], v[178:181], v[82:85]
	v_mfma_f32_16x16x32_bf16 v[82:85], v[158:161], v[182:185], v[82:85]
	v_mfma_f32_16x16x32_bf16 v[66:69], v[154:157], v[186:189], v[66:69]
	v_mfma_f32_16x16x32_bf16 v[66:69], v[158:161], v[190:193], v[66:69]
	v_mfma_f32_16x16x32_bf16 v[70:73], v[146:149], v[186:189], v[70:73]
	v_mfma_f32_16x16x32_bf16 v[70:73], v[150:153], v[190:193], v[70:73]
	v_mfma_f32_16x16x32_bf16 v[74:77], v[138:141], v[186:189], v[74:77]
	v_mfma_f32_16x16x32_bf16 v[74:77], v[142:145], v[190:193], v[74:77]
	v_mfma_f32_16x16x32_bf16 v[78:81], v[130:133], v[186:189], v[78:81]
	v_mfma_f32_16x16x32_bf16 v[78:81], v[134:137], v[190:193], v[78:81]
	s_barrier
	ds_read_b128 v[162:165], v246 offset:49152
	ds_read_b128 v[166:169], v246 offset:50176
	ds_read_b128 v[170:173], v246 offset:51200
	ds_read_b128 v[174:177], v246 offset:52224
	ds_read_b128 v[178:181], v246 offset:53248
	ds_read_b128 v[182:185], v246 offset:54272
	ds_read_b128 v[186:189], v246 offset:55296
	ds_read_b128 v[190:193], v246 offset:56320
	s_add_u32 s54, s54, 0x80
	s_addc_u32 s55, s55, 0
	s_mov_b32 m0, s85
	s_nop 0
	global_load_lds_dwordx4 v195, s[54:55]
	s_nop 0
	s_mov_b32 m0, s65
	s_nop 0
	global_load_lds_dwordx4 v207, s[54:55]
	s_add_u32 s54, s58, 0x80
	s_addc_u32 s55, s59, 0
	s_mov_b32 m0, s93
	s_nop 0
	global_load_lds_dwordx4 v195, s[54:55]
	s_nop 0
	s_mov_b32 m0, s28
	s_nop 0
	global_load_lds_dwordx4 v207, s[54:55]
	s_nop 0
	s_mov_b32 m0, s67
	s_nop 0
	global_load_lds_dwordx4 v0, s[48:49]
	s_nop 0
	s_mov_b32 m0, s92
	s_nop 0
	global_load_lds_dwordx4 v206, s[48:49]
	s_waitcnt vmcnt(8)
	s_waitcnt lgkmcnt(0)
	s_barrier
	s_waitcnt lgkmcnt(0)
	v_mfma_f32_16x16x32_bf16 v[62:65], v[130:133], v[162:165], v[62:65]
	v_mfma_f32_16x16x32_bf16 v[62:65], v[134:137], v[166:169], v[62:65]
	v_mfma_f32_16x16x32_bf16 v[58:61], v[138:141], v[162:165], v[58:61]
	v_mfma_f32_16x16x32_bf16 v[58:61], v[142:145], v[166:169], v[58:61]
	v_mfma_f32_16x16x32_bf16 v[54:57], v[146:149], v[162:165], v[54:57]
	v_mfma_f32_16x16x32_bf16 v[54:57], v[150:153], v[166:169], v[54:57]
	v_mfma_f32_16x16x32_bf16 v[50:53], v[154:157], v[162:165], v[50:53]
	v_mfma_f32_16x16x32_bf16 v[50:53], v[158:161], v[166:169], v[50:53]
	v_mfma_f32_16x16x32_bf16 v[34:37], v[154:157], v[170:173], v[34:37]
	v_mfma_f32_16x16x32_bf16 v[34:37], v[158:161], v[174:177], v[34:37]
	v_mfma_f32_16x16x32_bf16 v[38:41], v[146:149], v[170:173], v[38:41]
	v_mfma_f32_16x16x32_bf16 v[38:41], v[150:153], v[174:177], v[38:41]
	v_mfma_f32_16x16x32_bf16 v[42:45], v[138:141], v[170:173], v[42:45]
	v_mfma_f32_16x16x32_bf16 v[42:45], v[142:145], v[174:177], v[42:45]
	v_mfma_f32_16x16x32_bf16 v[46:49], v[130:133], v[170:173], v[46:49]
	v_mfma_f32_16x16x32_bf16 v[46:49], v[134:137], v[174:177], v[46:49]
	v_mfma_f32_16x16x32_bf16 v[30:33], v[130:133], v[178:181], v[30:33]
	v_mfma_f32_16x16x32_bf16 v[30:33], v[134:137], v[182:185], v[30:33]
	v_mfma_f32_16x16x32_bf16 v[26:29], v[138:141], v[178:181], v[26:29]
	v_mfma_f32_16x16x32_bf16 v[26:29], v[142:145], v[182:185], v[26:29]
	v_mfma_f32_16x16x32_bf16 v[22:25], v[146:149], v[178:181], v[22:25]
	v_mfma_f32_16x16x32_bf16 v[22:25], v[150:153], v[182:185], v[22:25]
	v_mfma_f32_16x16x32_bf16 v[18:21], v[154:157], v[178:181], v[18:21]
	v_mfma_f32_16x16x32_bf16 v[18:21], v[158:161], v[182:185], v[18:21]
	v_mfma_f32_16x16x32_bf16 v[2:5], v[154:157], v[186:189], v[2:5]
	v_mfma_f32_16x16x32_bf16 v[2:5], v[158:161], v[190:193], v[2:5]
	v_mfma_f32_16x16x32_bf16 v[6:9], v[146:149], v[186:189], v[6:9]
	v_mfma_f32_16x16x32_bf16 v[6:9], v[150:153], v[190:193], v[6:9]
	v_mfma_f32_16x16x32_bf16 v[10:13], v[138:141], v[186:189], v[10:13]
	v_mfma_f32_16x16x32_bf16 v[10:13], v[142:145], v[190:193], v[10:13]
	v_mfma_f32_16x16x32_bf16 v[14:17], v[130:133], v[186:189], v[14:17]
	v_mfma_f32_16x16x32_bf16 v[14:17], v[134:137], v[190:193], v[14:17]
	s_barrier
	s_add_u32 s4, s4, 0x100
	s_addc_u32 s5, s5, 0
	s_add_u32 s15, s15, 0x100
	s_addc_u32 s42, s42, 0
	s_cmp_ge_u32 s44, s36
	s_mov_b32 s43, s44
; #define PG8_STAGE(bufoff, gbase, voff) do { _Pragma("unroll") for (int _i = 0; _i < 2; ++_i) { \
;         const unsigned _m0 = ldsb + (unsigned)((bufoff) + _i * 8192); const char* _gb = (const char*)(gbase); \
;         asm volatile("s_mov_b32 m0, %0\n\ts_nop 0\n\tglobal_load_lds_dwordx4 %1, %2" :: "s"(_m0), "v"((voff)[_i]), "s"(_gb) : "m0", "memory"); } } while (0)
; #define PG8_LDA(dst, b, h) do { _Pragma("unroll") for (int m = 0; m < 4; ++m) _Pragma("unroll") for (int k = 0; k < 2; ++k) dst[m][k] = *(const LAS bf16x8*)(lds + PG8_SA(b, h) + aoff + m * 2048 + k * 1024); } while (0)
; #define PG8_LDB(dst, b, h) do { _Pragma("unroll") for (int n = 0; n < 2; ++n) _Pragma("unroll") for (int k = 0; k < 2; ++k) dst[n][k] = *(const LAS bf16x8*)(lds + PG8_SB(b, h) + boff + n * 2048 + k * 1024); } while (0)
; #define PG8_MMA(ai, bj, At, Bt) do { __builtin_amdgcn_s_setprio(1); _Pragma("unroll") for (int m = 0; m < 4; ++m) _Pragma("unroll") for (int n = 0; n < 2; ++n) _Pragma("unroll") for (int k = 0; k < 2; ++k) \
;         acc[ai][bj][m][n] = __builtin_amdgcn_mfma_f32_16x16x32_bf16(Bt[n][k], At[m][k], acc[ai][bj][m][n], 0, 0, 0); __builtin_amdgcn_s_setprio(0); } while (0)
; #define PG8_WAIT_V(n) asm volatile("s_waitcnt vmcnt(" #n ")" ::: "memory")
; #define PG8_WAIT_L(n) asm volatile("s_waitcnt lgkmcnt(" #n ")" ::: "memory")
; template <class Epi, bool ALIGN_EPI>
; __device__ __forceinline__ void gemm_phase(LAS unsigned char* lds, const Gemm g, const StaticOrder& S, const Epi& E) {
;     ...
;         for (int t = 0; t < nt; t += 2) {
;             const bool last = (t == nt - 2);
;             const char* a1 = cA + (size_t)(t + 1) * kstep;
;             const char* a2 = last ? nA : cA + (size_t)(t + 2) * kstep; const char* b2 = last ? nB : cB + (size_t)(t + 2) * kstep;
;             const char* a3 = a2 + kstep; const char* b3 = b2 + kstep;
;             PG8_LDB(B0, 0, 0); PG8_LDB(B1, 0, 1); PG8_SCHED; PG8_LDA(At, 0, 0); PG8_STAGE(PG8_SA(1, 1), a1 + hstepA, voffA);
;             PG8_WAIT_V(8); PG8_WAIT_L(0); PG8_BAR; PG8_MMA(0, 0, At, B0); PG8_MMA(0, 1, At, B1); PG8_BAR; PG8_SCHED;
;             PG8_LDA(At, 0, 1); PG8_STAGE(PG8_SB(0, 0), b2, voffB); PG8_STAGE(PG8_SB(0, 1), b2 + hstepB, voffB); PG8_STAGE(PG8_SA(0, 0), a2, voffA);
;             PG8_WAIT_V(8); PG8_WAIT_L(0); PG8_BAR; PG8_MMA(1, 0, At, B0); PG8_MMA(1, 1, At, B1); PG8_BAR; PG8_SCHED;
.LBB0_201:
	v_add_u32_e32 v142, 0x10000, v245
	v_add_u32_e32 v158, 0x14000, v245
	ds_read_b128 v[130:133], v142
	ds_read_b128 v[134:137], v142 offset:1024
	ds_read_b128 v[138:141], v142 offset:2048
	ds_read_b128 v[142:145], v142 offset:3072
	ds_read_b128 v[146:149], v158
	ds_read_b128 v[150:153], v158 offset:1024
	ds_read_b128 v[154:157], v158 offset:2048
	ds_read_b128 v[158:161], v158 offset:3072
	s_add_i32 s44, s43, 2
	s_cmp_eq_u32 s68, s43
	s_cselect_b32 s56, s0, s15
	s_cselect_b32 s57, s1, s42
	s_cselect_b32 s54, s94, s4
	s_cselect_b32 s55, s95, s5
	s_add_u32 s48, s56, 0x80
	s_addc_u32 s49, s57, 0
	ds_read_b128 v[162:165], v246
	ds_read_b128 v[166:169], v246 offset:1024
	ds_read_b128 v[170:173], v246 offset:2048
	ds_read_b128 v[174:177], v246 offset:3072
	ds_read_b128 v[178:181], v246 offset:4096
	ds_read_b128 v[182:185], v246 offset:5120
	ds_read_b128 v[186:189], v246 offset:6144
	ds_read_b128 v[190:193], v246 offset:7168
	s_add_u32 s43, s15, s38
	s_addc_u32 s45, s42, 0
	s_add_u32 s58, s43, 0xffffff80
	s_addc_u32 s59, s45, -1
	s_mov_b32 m0, s37
	s_nop 0
	global_load_lds_dwordx4 v0, s[58:59]
	s_nop 0
	s_mov_b32 m0, s41
	s_nop 0
	global_load_lds_dwordx4 v206, s[58:59]
	s_waitcnt vmcnt(8)
	s_waitcnt lgkmcnt(0)
	s_barrier
	s_waitcnt lgkmcnt(0)
	v_mfma_f32_16x16x32_bf16 v[126:129], v[130:133], v[162:165], v[126:129]
	v_mfma_f32_16x16x32_bf16 v[126:129], v[134:137], v[166:169], v[126:129]
	v_mfma_f32_16x16x32_bf16 v[122:125], v[138:141], v[162:165], v[122:125]
	v_mfma_f32_16x16x32_bf16 v[122:125], v[142:145], v[166:169], v[122:125]
	v_mfma_f32_16x16x32_bf16 v[118:121], v[146:149], v[162:165], v[118:121]
	v_mfma_f32_16x16x32_bf16 v[118:121], v[150:153], v[166:169], v[118:121]
	v_mfma_f32_16x16x32_bf16 v[114:117], v[154:157], v[162:165], v[114:117]
	v_mfma_f32_16x16x32_bf16 v[114:117], v[158:161], v[166:169], v[114:117]
	v_mfma_f32_16x16x32_bf16 v[98:101], v[154:157], v[170:173], v[98:101]
	v_mfma_f32_16x16x32_bf16 v[98:101], v[158:161], v[174:177], v[98:101]
	v_mfma_f32_16x16x32_bf16 v[102:105], v[146:149], v[170:173], v[102:105]
	v_mfma_f32_16x16x32_bf16 v[102:105], v[150:153], v[174:177], v[102:105]
	v_mfma_f32_16x16x32_bf16 v[106:109], v[138:141], v[170:173], v[106:109]
	v_mfma_f32_16x16x32_bf16 v[106:109], v[142:145], v[174:177], v[106:109]
	v_mfma_f32_16x16x32_bf16 v[110:113], v[130:133], v[170:173], v[110:113]
	v_mfma_f32_16x16x32_bf16 v[110:113], v[134:137], v[174:177], v[110:113]
	v_mfma_f32_16x16x32_bf16 v[94:97], v[130:133], v[178:181], v[94:97]
	v_mfma_f32_16x16x32_bf16 v[94:97], v[134:137], v[182:185], v[94:97]
	v_mfma_f32_16x16x32_bf16 v[90:93], v[138:141], v[178:181], v[90:93]
	v_mfma_f32_16x16x32_bf16 v[90:93], v[142:145], v[182:185], v[90:93]
	v_mfma_f32_16x16x32_bf16 v[86:89], v[146:149], v[178:181], v[86:89]
	v_mfma_f32_16x16x32_bf16 v[86:89], v[150:153], v[182:185], v[86:89]
	v_mfma_f32_16x16x32_bf16 v[82:85], v[154:157], v[178:181], v[82:85]
	v_mfma_f32_16x16x32_bf16 v[82:85], v[158:161], v[182:185], v[82:85]
	v_mfma_f32_16x16x32_bf16 v[66:69], v[154:157], v[186:189], v[66:69]
	v_mfma_f32_16x16x32_bf16 v[66:69], v[158:161], v[190:193], v[66:69]
	v_mfma_f32_16x16x32_bf16 v[70:73], v[146:149], v[186:189], v[70:73]
	v_mfma_f32_16x16x32_bf16 v[70:73], v[150:153], v[190:193], v[70:73]
	v_mfma_f32_16x16x32_bf16 v[74:77], v[138:141], v[186:189], v[74:77]
	v_mfma_f32_16x16x32_bf16 v[74:77], v[142:145], v[190:193], v[74:77]
	v_mfma_f32_16x16x32_bf16 v[78:81], v[130:133], v[186:189], v[78:81]
	v_mfma_f32_16x16x32_bf16 v[78:81], v[134:137], v[190:193], v[78:81]
	s_barrier
	ds_read_b128 v[162:165], v246 offset:16384
	ds_read_b128 v[166:169], v246 offset:17408
	ds_read_b128 v[170:173], v246 offset:18432
	ds_read_b128 v[174:177], v246 offset:19456
	ds_read_b128 v[178:181], v246 offset:20480
	ds_read_b128 v[182:185], v246 offset:21504
	ds_read_b128 v[186:189], v246 offset:22528
	ds_read_b128 v[190:193], v246 offset:23552
	s_mov_b32 m0, s46
	s_nop 0
	global_load_lds_dwordx4 v195, s[54:55]
	s_add_u32 s58, s54, s38
	s_mov_b32 m0, s26
	s_nop 0
	global_load_lds_dwordx4 v207, s[54:55]
	s_addc_u32 s59, s55, 0
	s_mov_b32 m0, s27
	s_nop 0
	global_load_lds_dwordx4 v195, s[58:59]
	s_nop 0
	s_mov_b32 m0, s30
	s_nop 0
	global_load_lds_dwordx4 v207, s[58:59]
	s_nop 0
	s_mov_b32 m0, s29
	s_nop 0
	global_load_lds_dwordx4 v0, s[56:57]
	s_nop 0
	s_mov_b32 m0, s17
	s_nop 0
	global_load_lds_dwordx4 v206, s[56:57]
	s_waitcnt vmcnt(8)
	s_waitcnt lgkmcnt(0)
	s_barrier
	s_waitcnt lgkmcnt(0)
	v_mfma_f32_16x16x32_bf16 v[62:65], v[130:133], v[162:165], v[62:65]
	v_mfma_f32_16x16x32_bf16 v[62:65], v[134:137], v[166:169], v[62:65]
	v_mfma_f32_16x16x32_bf16 v[58:61], v[138:141], v[162:165], v[58:61]
	v_mfma_f32_16x16x32_bf16 v[58:61], v[142:145], v[166:169], v[58:61]
	v_mfma_f32_16x16x32_bf16 v[54:57], v[146:149], v[162:165], v[54:57]
	v_mfma_f32_16x16x32_bf16 v[54:57], v[150:153], v[166:169], v[54:57]
	v_mfma_f32_16x16x32_bf16 v[50:53], v[154:157], v[162:165], v[50:53]
	v_mfma_f32_16x16x32_bf16 v[50:53], v[158:161], v[166:169], v[50:53]
	v_mfma_f32_16x16x32_bf16 v[34:37], v[154:157], v[170:173], v[34:37]
	v_mfma_f32_16x16x32_bf16 v[34:37], v[158:161], v[174:177], v[34:37]
	v_mfma_f32_16x16x32_bf16 v[38:41], v[146:149], v[170:173], v[38:41]
	v_mfma_f32_16x16x32_bf16 v[38:41], v[150:153], v[174:177], v[38:41]
	v_mfma_f32_16x16x32_bf16 v[42:45], v[138:141], v[170:173], v[42:45]
	v_mfma_f32_16x16x32_bf16 v[42:45], v[142:145], v[174:177], v[42:45]
	v_mfma_f32_16x16x32_bf16 v[46:49], v[130:133], v[170:173], v[46:49]
	v_mfma_f32_16x16x32_bf16 v[46:49], v[134:137], v[174:177], v[46:49]
	v_mfma_f32_16x16x32_bf16 v[30:33], v[130:133], v[178:181], v[30:33]
	v_mfma_f32_16x16x32_bf16 v[30:33], v[134:137], v[182:185], v[30:33]
	v_mfma_f32_16x16x32_bf16 v[26:29], v[138:141], v[178:181], v[26:29]
	v_mfma_f32_16x16x32_bf16 v[26:29], v[142:145], v[182:185], v[26:29]
	v_mfma_f32_16x16x32_bf16 v[22:25], v[146:149], v[178:181], v[22:25]
	v_mfma_f32_16x16x32_bf16 v[22:25], v[150:153], v[182:185], v[22:25]
	v_mfma_f32_16x16x32_bf16 v[18:21], v[154:157], v[178:181], v[18:21]
	v_mfma_f32_16x16x32_bf16 v[18:21], v[158:161], v[182:185], v[18:21]
	v_mfma_f32_16x16x32_bf16 v[2:5], v[154:157], v[186:189], v[2:5]
	v_mfma_f32_16x16x32_bf16 v[2:5], v[158:161], v[190:193], v[2:5]
	v_mfma_f32_16x16x32_bf16 v[6:9], v[146:149], v[186:189], v[6:9]
	v_mfma_f32_16x16x32_bf16 v[6:9], v[150:153], v[190:193], v[6:9]
	v_mfma_f32_16x16x32_bf16 v[10:13], v[138:141], v[186:189], v[10:13]
	v_mfma_f32_16x16x32_bf16 v[10:13], v[142:145], v[190:193], v[10:13]
	v_mfma_f32_16x16x32_bf16 v[14:17], v[130:133], v[186:189], v[14:17]
	v_mfma_f32_16x16x32_bf16 v[14:17], v[134:137], v[190:193], v[14:17]
	s_barrier
; #define PG8_STAGE(bufoff, gbase, voff) do { _Pragma("unroll") for (int _i = 0; _i < 2; ++_i) { \
;         const unsigned _m0 = ldsb + (unsigned)((bufoff) + _i * 8192); const char* _gb = (const char*)(gbase); \
;         asm volatile("s_mov_b32 m0, %0\n\ts_nop 0\n\tglobal_load_lds_dwordx4 %1, %2" :: "s"(_m0), "v"((voff)[_i]), "s"(_gb) : "m0", "memory"); } } while (0)
; #define PG8_LDA(dst, b, h) do { _Pragma("unroll") for (int m = 0; m < 4; ++m) _Pragma("unroll") for (int k = 0; k < 2; ++k) dst[m][k] = *(const LAS bf16x8*)(lds + PG8_SA(b, h) + aoff + m * 2048 + k * 1024); } while (0)
; #define PG8_LDB(dst, b, h) do { _Pragma("unroll") for (int n = 0; n < 2; ++n) _Pragma("unroll") for (int k = 0; k < 2; ++k) dst[n][k] = *(const LAS bf16x8*)(lds + PG8_SB(b, h) + boff + n * 2048 + k * 1024); } while (0)
; #define PG8_MMA(ai, bj, At, Bt) do { __builtin_amdgcn_s_setprio(1); _Pragma("unroll") for (int m = 0; m < 4; ++m) _Pragma("unroll") for (int n = 0; n < 2; ++n) _Pragma("unroll") for (int k = 0; k < 2; ++k) \
;         acc[ai][bj][m][n] = __builtin_amdgcn_mfma_f32_16x16x32_bf16(Bt[n][k], At[m][k], acc[ai][bj][m][n], 0, 0, 0); __builtin_amdgcn_s_setprio(0); } while (0)
; #define PG8_WAIT_V(n) asm volatile("s_waitcnt vmcnt(" #n ")" ::: "memory")
; #define PG8_WAIT_L(n) asm volatile("s_waitcnt lgkmcnt(" #n ")" ::: "memory")
; #define PG8_BAR __builtin_amdgcn_s_barrier()
; #define PG8_SCHED __builtin_amdgcn_sched_barrier(0)
; template <class Epi, bool ALIGN_EPI>
; __device__ __forceinline__ void gemm_phase(LAS unsigned char* lds, const Gemm g, const StaticOrder& S, const Epi& E) {
;     ...
;             PG8_LDB(B0, 1, 0); PG8_LDB(B1, 1, 1); PG8_SCHED; PG8_LDA(At, 1, 0); PG8_STAGE(PG8_SA(0, 1), a2 + hstepA, voffA);
;             PG8_WAIT_V(8); PG8_WAIT_L(0); PG8_BAR; PG8_MMA(0, 0, At, B0); PG8_MMA(0, 1, At, B1); PG8_BAR; PG8_SCHED;
;             PG8_LDA(At, 1, 1); PG8_STAGE(PG8_SB(1, 0), b3, voffB); PG8_STAGE(PG8_SB(1, 1), b3 + hstepB, voffB); PG8_STAGE(PG8_SA(1, 0), a3, voffA);
;             PG8_WAIT_V(8); PG8_WAIT_L(0); PG8_BAR; PG8_MMA(1, 0, At, B0); PG8_MMA(1, 1, At, B1); PG8_BAR; PG8_SCHED;
;         }
;         if constexpr (ALIGN_EPI) { if (wr == 0) PG8_BAR; }
;         E(acc, cur, wr, wc, fr, fq);
;         if (!has_next) break;
	v_add_u32_e32 v142, 0x18000, v245
	v_add_u32_e32 v158, 0x1c000, v245
	ds_read_b128 v[130:133], v142
	ds_read_b128 v[134:137], v142 offset:1024
	ds_read_b128 v[138:141], v142 offset:2048
	ds_read_b128 v[142:145], v142 offset:3072
	ds_read_b128 v[146:149], v158
	ds_read_b128 v[150:153], v158 offset:1024
	ds_read_b128 v[154:157], v158 offset:2048
	ds_read_b128 v[158:161], v158 offset:3072
	ds_read_b128 v[162:165], v246 offset:32768
	ds_read_b128 v[166:169], v246 offset:33792
	ds_read_b128 v[170:173], v246 offset:34816
	ds_read_b128 v[174:177], v246 offset:35840
	ds_read_b128 v[178:181], v246 offset:36864
	ds_read_b128 v[182:185], v246 offset:37888
	ds_read_b128 v[186:189], v246 offset:38912
	ds_read_b128 v[190:193], v246 offset:39936
	s_add_u32 s56, s56, s38
	s_addc_u32 s57, s57, 0
	s_mov_b32 m0, s31
	s_nop 0
	global_load_lds_dwordx4 v0, s[56:57]
	s_nop 0
	s_mov_b32 m0, s53
	s_nop 0
	global_load_lds_dwordx4 v206, s[56:57]
	s_waitcnt vmcnt(8)
	s_waitcnt lgkmcnt(0)
	s_barrier
	s_waitcnt lgkmcnt(0)
	v_mfma_f32_16x16x32_bf16 v[126:129], v[130:133], v[162:165], v[126:129]
	v_mfma_f32_16x16x32_bf16 v[126:129], v[134:137], v[166:169], v[126:129]
	v_mfma_f32_16x16x32_bf16 v[122:125], v[138:141], v[162:165], v[122:125]
	v_mfma_f32_16x16x32_bf16 v[122:125], v[142:145], v[166:169], v[122:125]
	v_mfma_f32_16x16x32_bf16 v[118:121], v[146:149], v[162:165], v[118:121]
	v_mfma_f32_16x16x32_bf16 v[118:121], v[150:153], v[166:169], v[118:121]
	v_mfma_f32_16x16x32_bf16 v[114:117], v[154:157], v[162:165], v[114:117]
	v_mfma_f32_16x16x32_bf16 v[114:117], v[158:161], v[166:169], v[114:117]
	v_mfma_f32_16x16x32_bf16 v[98:101], v[154:157], v[170:173], v[98:101]
	v_mfma_f32_16x16x32_bf16 v[98:101], v[158:161], v[174:177], v[98:101]
	v_mfma_f32_16x16x32_bf16 v[102:105], v[146:149], v[170:173], v[102:105]
	v_mfma_f32_16x16x32_bf16 v[102:105], v[150:153], v[174:177], v[102:105]
	v_mfma_f32_16x16x32_bf16 v[106:109], v[138:141], v[170:173], v[106:109]
	v_mfma_f32_16x16x32_bf16 v[106:109], v[142:145], v[174:177], v[106:109]
	v_mfma_f32_16x16x32_bf16 v[110:113], v[130:133], v[170:173], v[110:113]
	v_mfma_f32_16x16x32_bf16 v[110:113], v[134:137], v[174:177], v[110:113]
	v_mfma_f32_16x16x32_bf16 v[94:97], v[130:133], v[178:181], v[94:97]
	v_mfma_f32_16x16x32_bf16 v[94:97], v[134:137], v[182:185], v[94:97]
	v_mfma_f32_16x16x32_bf16 v[90:93], v[138:141], v[178:181], v[90:93]
	v_mfma_f32_16x16x32_bf16 v[90:93], v[142:145], v[182:185], v[90:93]
	v_mfma_f32_16x16x32_bf16 v[86:89], v[146:149], v[178:181], v[86:89]
	v_mfma_f32_16x16x32_bf16 v[86:89], v[150:153], v[182:185], v[86:89]
	v_mfma_f32_16x16x32_bf16 v[82:85], v[154:157], v[178:181], v[82:85]
	v_mfma_f32_16x16x32_bf16 v[82:85], v[158:161], v[182:185], v[82:85]
	v_mfma_f32_16x16x32_bf16 v[66:69], v[154:157], v[186:189], v[66:69]
	v_mfma_f32_16x16x32_bf16 v[66:69], v[158:161], v[190:193], v[66:69]
	v_mfma_f32_16x16x32_bf16 v[70:73], v[146:149], v[186:189], v[70:73]
	v_mfma_f32_16x16x32_bf16 v[70:73], v[150:153], v[190:193], v[70:73]
	v_mfma_f32_16x16x32_bf16 v[74:77], v[138:141], v[186:189], v[74:77]
	v_mfma_f32_16x16x32_bf16 v[74:77], v[142:145], v[190:193], v[74:77]
	v_mfma_f32_16x16x32_bf16 v[78:81], v[130:133], v[186:189], v[78:81]
	v_mfma_f32_16x16x32_bf16 v[78:81], v[134:137], v[190:193], v[78:81]
	s_barrier
	ds_read_b128 v[162:165], v246 offset:49152
	ds_read_b128 v[166:169], v246 offset:50176
	ds_read_b128 v[170:173], v246 offset:51200
	ds_read_b128 v[174:177], v246 offset:52224
	ds_read_b128 v[178:181], v246 offset:53248
	ds_read_b128 v[182:185], v246 offset:54272
	ds_read_b128 v[186:189], v246 offset:55296
	ds_read_b128 v[190:193], v246 offset:56320
	s_add_u32 s54, s54, 0x80
	s_addc_u32 s55, s55, 0
	s_mov_b32 m0, s85
	s_nop 0
	global_load_lds_dwordx4 v195, s[54:55]
	s_nop 0
	s_mov_b32 m0, s65
	s_nop 0
	global_load_lds_dwordx4 v207, s[54:55]
	s_add_u32 s54, s58, 0x80
	s_addc_u32 s55, s59, 0
	s_mov_b32 m0, s93
	s_nop 0
	global_load_lds_dwordx4 v195, s[54:55]
	s_nop 0
	s_mov_b32 m0, s28
	s_nop 0
	global_load_lds_dwordx4 v207, s[54:55]
	s_nop 0
	s_mov_b32 m0, s67
	s_nop 0
	global_load_lds_dwordx4 v0, s[48:49]
	s_nop 0
	s_mov_b32 m0, s92
	s_nop 0
	global_load_lds_dwordx4 v206, s[48:49]
	s_waitcnt vmcnt(8)
	s_waitcnt lgkmcnt(0)
	s_barrier
	s_waitcnt lgkmcnt(0)
	v_mfma_f32_16x16x32_bf16 v[62:65], v[130:133], v[162:165], v[62:65]
	v_mfma_f32_16x16x32_bf16 v[62:65], v[134:137], v[166:169], v[62:65]
	v_mfma_f32_16x16x32_bf16 v[58:61], v[138:141], v[162:165], v[58:61]
	v_mfma_f32_16x16x32_bf16 v[58:61], v[142:145], v[166:169], v[58:61]
	v_mfma_f32_16x16x32_bf16 v[54:57], v[146:149], v[162:165], v[54:57]
	v_mfma_f32_16x16x32_bf16 v[54:57], v[150:153], v[166:169], v[54:57]
	v_mfma_f32_16x16x32_bf16 v[50:53], v[154:157], v[162:165], v[50:53]
	v_mfma_f32_16x16x32_bf16 v[50:53], v[158:161], v[166:169], v[50:53]
	v_mfma_f32_16x16x32_bf16 v[34:37], v[154:157], v[170:173], v[34:37]
	v_mfma_f32_16x16x32_bf16 v[34:37], v[158:161], v[174:177], v[34:37]
	v_mfma_f32_16x16x32_bf16 v[38:41], v[146:149], v[170:173], v[38:41]
	v_mfma_f32_16x16x32_bf16 v[38:41], v[150:153], v[174:177], v[38:41]
	v_mfma_f32_16x16x32_bf16 v[42:45], v[138:141], v[170:173], v[42:45]
	v_mfma_f32_16x16x32_bf16 v[42:45], v[142:145], v[174:177], v[42:45]
	v_mfma_f32_16x16x32_bf16 v[46:49], v[130:133], v[170:173], v[46:49]
	v_mfma_f32_16x16x32_bf16 v[46:49], v[134:137], v[174:177], v[46:49]
	v_mfma_f32_16x16x32_bf16 v[30:33], v[130:133], v[178:181], v[30:33]
	v_mfma_f32_16x16x32_bf16 v[30:33], v[134:137], v[182:185], v[30:33]
	v_mfma_f32_16x16x32_bf16 v[26:29], v[138:141], v[178:181], v[26:29]
	v_mfma_f32_16x16x32_bf16 v[26:29], v[142:145], v[182:185], v[26:29]
	v_mfma_f32_16x16x32_bf16 v[22:25], v[146:149], v[178:181], v[22:25]
	v_mfma_f32_16x16x32_bf16 v[22:25], v[150:153], v[182:185], v[22:25]
	v_mfma_f32_16x16x32_bf16 v[18:21], v[154:157], v[178:181], v[18:21]
	v_mfma_f32_16x16x32_bf16 v[18:21], v[158:161], v[182:185], v[18:21]
	v_mfma_f32_16x16x32_bf16 v[2:5], v[154:157], v[186:189], v[2:5]
	v_mfma_f32_16x16x32_bf16 v[2:5], v[158:161], v[190:193], v[2:5]
	v_mfma_f32_16x16x32_bf16 v[6:9], v[146:149], v[186:189], v[6:9]
	v_mfma_f32_16x16x32_bf16 v[6:9], v[150:153], v[190:193], v[6:9]
	v_mfma_f32_16x16x32_bf16 v[10:13], v[138:141], v[186:189], v[10:13]
	v_mfma_f32_16x16x32_bf16 v[10:13], v[142:145], v[190:193], v[10:13]
	v_mfma_f32_16x16x32_bf16 v[14:17], v[130:133], v[186:189], v[14:17]
	v_mfma_f32_16x16x32_bf16 v[14:17], v[134:137], v[190:193], v[14:17]
	s_barrier
	s_add_u32 s4, s4, 0x100
	s_addc_u32 s5, s5, 0
	s_add_u32 s15, s15, 0x100
	s_addc_u32 s42, s42, 0
	s_cmp_ge_u32 s44, s36
	s_mov_b32 s43, s44
	s_cbranch_scc0 .LBB0_201
	v_readlane_b32 s4, v255, 6
	v_readlane_b32 s5, v255, 7
	s_and_b64 vcc, exec, s[4:5]
	s_cbranch_vccz .LBB0_204
	s_barrier

; #define PG8_WAIT_V(n) asm volatile("s_waitcnt vmcnt(" #n ")" ::: "memory")
; #define PG8_BAR __builtin_amdgcn_s_barrier()
; template <class Epi, bool ALIGN_EPI>
; __device__ __forceinline__ void gemm_phase(LAS unsigned char* lds, const Gemm g, const StaticOrder& S, const Epi& E) {
;     ...
;     PG8_WAIT_V(0);
;     if constexpr (!ALIGN_EPI) { if (wr == 0) PG8_BAR; }
;     PG8_BAR;
.LBB0_241:
	s_setprio 0
	s_waitcnt vmcnt(0)
	s_barrier
	v_readlane_b32 s75, v254, 58
	v_readlane_b32 s53, v254, 43
	v_readlane_b32 s65, v254, 42
	v_readlane_b32 s67, v254, 41
	v_readlane_b32 s80, v254, 40
	v_readlane_b32 s85, v254, 39
	v_readlane_b32 s16, v255, 8

; #define PG8_WAIT_V(n) asm volatile("s_waitcnt vmcnt(" #n ")" ::: "memory")
; #define PG8_BAR __builtin_amdgcn_s_barrier()
; template <class Epi, bool ALIGN_EPI>
; __device__ __forceinline__ void gemm_phase(LAS unsigned char* lds, const Gemm g, const StaticOrder& S, const Epi& E) {
;     int tid = threadIdx.x; asm volatile("" : "+v"(tid));
;     const int wid = __builtin_amdgcn_readfirstlane(tid >> 6), lane = tid & 63, wr = wid >> 2, wc = wid & 3, fr = lane & 15, fq = lane >> 4;
;     const int K = g.K, nt = K / BK, lda = g.lda;
;     unsigned voffA[2], voffB[2];
; #pragma unroll
;     for (int i = 0; i < 2; ++i) { int R, C; stage_rc(tid * 16 + i * 8192, R, C); const int Rb = (R & ~31) + perm32(R & 31);
;         voffA[i] = (unsigned)(R * lda + C) * 2u; voffB[i] = (unsigned)(Rb * K + C) * 2u; }
;     const size_t kstep = (size_t)(BK * 2);
;     const size_t hstepA = (size_t)HALF * lda * 2, hstepB = (size_t)HALF * K * 2;
;     const size_t tstepA = 2 * hstepA, tstepB = 2 * hstepB;
;     const unsigned ldsw = (unsigned)wid * 1024u;
;     const unsigned ldsb = (unsigned)(unsigned long)lds + ldsw;
;     const int aoff = lds_byte(wr * 64 + fr, fq * 8), boff = lds_byte(wc * 32 + fr, fq * 8);
;     ...
;     Unit cur, nxt; int ui = 0;
;     if (!S.next(0, cur)) return;
;     f32x4 acc[2][2][4][2];
; #pragma unroll
;     for (int a = 0; a < 2; ++a)
; #pragma unroll
;         for (int b = 0; b < 2; ++b)
; #pragma unroll
;             for (int m = 0; m < 4; ++m)
; #pragma unroll
;                 for (int n = 0; n < 2; ++n) acc[a][b][m][n] = (f32x4){0.f, 0.f, 0.f, 0.f};
;     bf16x8 At[4][2], B0[2][2], B1[2][2];
;     const char* cA = (const char*)g.A + (size_t)cur.pm * tstepA + (size_t)cur.pn * g.a_pn_off * 2 + (size_t)(cur.pm >> 4) * g.a_adj; const char* cB = (const char*)g.Bt + (size_t)cur.pn * tstepB;
;     PG8_STAGE(PG8_SB(0, 0), cB, voffB); PG8_STAGE(PG8_SB(0, 1), cB + hstepB, voffB); PG8_STAGE(PG8_SA(0, 0), cA, voffA); PG8_STAGE(PG8_SA(0, 1), cA + hstepA, voffA);
;     if (wr == 1) PG8_BAR;
;     PG8_WAIT_V(2); PG8_BAR;
;     PG8_STAGE(PG8_SB(1, 0), cB + kstep, voffB); PG8_STAGE(PG8_SA(1, 0), cA + kstep, voffA); PG8_STAGE(PG8_SB(1, 1), cB + hstepB + kstep, voffB);
.LBB0_254:
	s_andn2_b64 vcc, exec, s[36:37]
	s_cbranch_vccnz .LBB0_290
	v_bfe_i32 v4, v0, 27, 1
	v_lshlrev_b32_e32 v2, 4, v0
	v_lshrrev_b32_e32 v4, 22, v4
	v_add_u32_e32 v4, v2, v4
	v_and_b32_e32 v4, 0xfffffc00, v4
	v_sub_u32_e32 v4, v2, v4
	s_waitcnt lgkmcnt(0)
	v_lshrrev_b32_e32 v5, 4, v4
	v_ashrrev_i32_e32 v3, 31, v0
	v_bitop3_b32 v4, v5, v4, 32 bitop3:0x6c
	v_lshrrev_b32_e32 v3, 26, v3
	v_ashrrev_i32_e32 v6, 31, v4
	v_add_u32_e32 v3, v0, v3
	v_lshrrev_b32_e32 v6, 26, v6
	v_ashrrev_i32_e32 v3, 6, v3
	v_add_u32_e32 v6, v4, v6
	v_lshlrev_b32_e32 v5, 3, v3
	v_ashrrev_i32_e32 v7, 6, v6
	v_and_b32_e32 v6, 0xc0, v6
	v_and_b32_e32 v5, -16, v5
	v_lshlrev_b32_e32 v3, 5, v3
	v_sub_u32_e32 v4, v4, v6
	v_add_u32_e32 v5, v7, v5
	v_and_b32_e32 v3, 32, v3
	v_ashrrev_i16_sdwa v4, v223, sext(v4) dst_sel:DWORD dst_unused:UNUSED_PAD src0_sel:DWORD src1_sel:BYTE_0
	v_add_u32_sdwa v3, v3, sext(v4) dst_sel:DWORD dst_unused:UNUSED_PAD src0_sel:DWORD src1_sel:WORD_0
	v_lshlrev_b32_e32 v4, 1, v5
	v_lshrrev_b32_e32 v6, 2, v5
	v_and_b32_e32 v7, 3, v7
	s_mov_b32 s5, 0x7fffffe0
	v_and_b32_e32 v4, 24, v4
	v_and_b32_e32 v6, 4, v6
	v_and_or_b32 v7, v5, s5, v7
	v_or3_b32 v4, v7, v6, v4
	v_lshlrev_b32_e32 v5, 11, v5
	v_mul_lo_u32 v4, v4, s26
	v_add_u32_e32 v2, 0x2000, v2
	v_lshl_add_u32 v165, v3, 1, v5
	v_add_lshl_u32 v167, v4, v3, 1
	v_ashrrev_i32_e32 v3, 31, v2
	v_lshrrev_b32_e32 v3, 22, v3
	v_add_u32_e32 v3, v2, v3
	v_ashrrev_i32_e32 v3, 10, v3
	v_mul_i32_i24_e32 v4, 0x400, v3
	v_sub_u32_e32 v2, v2, v4
	v_lshrrev_b32_e32 v4, 4, v2
	v_writelane_b32 v254, s85, 39
	v_bitop3_b32 v2, v4, v2, 32 bitop3:0x6c
	v_writelane_b32 v254, s80, 40
	v_ashrrev_i32_e32 v5, 31, v2
	v_writelane_b32 v254, s67, 41
	v_lshrrev_b32_e32 v5, 26, v5
	v_writelane_b32 v254, s65, 42
	v_lshlrev_b32_e32 v4, 3, v3
	v_add_u32_e32 v5, v2, v5
	v_writelane_b32 v254, s53, 43
	s_ashr_i32 s4, s7, 6
	v_and_b32_e32 v4, -16, v4
	v_ashrrev_i32_e32 v6, 6, v5
	v_writelane_b32 v254, s75, 58
	v_add_u32_e32 v4, v6, v4
	v_and_b32_e32 v6, 3, v6
	s_lshl_b32 s17, s4, 10
	v_and_or_b32 v6, v4, s5, v6
	s_ashr_i32 s5, s7, 8
	s_lshl_b32 s14, s26, 8
	s_lshl_b32 s15, s26, 9
	s_add_i32 s17, s17, 0
	s_lshl_b32 s6, s6, 1
	v_readlane_b32 s27, v254, 29
	s_add_u32 s69, s27, s6
	v_readlane_b32 s6, v254, 30
	s_addc_u32 s78, s6, 0
	s_and_b64 s[0:1], exec, s[0:1]
	v_readlane_b32 s0, v254, 55
	s_cselect_b32 s30, s0, s19
	v_readlane_b32 s0, v254, 54
	v_readlane_b32 s28, v254, 48
	v_and_b32_e32 v5, 0xc0, v5
	s_cselect_b32 s31, s0, s18
	s_ashr_i32 s95, s94, 31
	v_readlane_b32 s29, v254, 49
	v_lshlrev_b32_e32 v3, 5, v3
	v_sub_u32_e32 v2, v2, v5
	s_lshl_b64 s[0:1], s[94:95], 19
	s_mul_i32 s29, s15, s51
	v_and_b32_e32 v3, 32, v3
	v_ashrrev_i16_sdwa v2, v223, sext(v2) dst_sel:DWORD dst_unused:UNUSED_PAD src0_sel:DWORD src1_sel:BYTE_0
	s_mul_hi_i32 s6, s28, s51
	s_mul_i32 s27, s28, s51
	s_mul_hi_i32 s28, s15, s51
	s_add_u32 s56, s69, s29
	v_add_u32_sdwa v2, v3, sext(v2) dst_sel:DWORD dst_unused:UNUSED_PAD src0_sel:DWORD src1_sel:WORD_0
	v_lshlrev_b32_e32 v3, 1, v4
	v_lshrrev_b32_e32 v5, 2, v4
	s_addc_u32 s57, s78, s28
	s_add_i32 s42, s17, 0x10000
	s_add_i32 s43, s17, 0x12000
	v_and_b32_e32 v3, 24, v3
	v_and_b32_e32 v5, 4, v5
	s_add_u32 s28, s31, s0
	v_or3_b32 v3, v6, v5, v3
	s_addc_u32 s29, s30, s1
	s_add_i32 s46, s17, 0x14000
	v_mul_lo_u32 v3, v3, s26
	s_mov_b32 m0, s42
	s_nop 0
	global_load_lds_dwordx4 v167, s[56:57]
	s_add_u32 s0, s56, s14
	v_add_lshl_u32 v175, v3, v2, 1
	s_mov_b32 m0, s43
	s_nop 0
	global_load_lds_dwordx4 v175, s[56:57]
	s_addc_u32 s1, s57, 0
	s_add_i32 s50, s17, 0x16000
	s_mov_b32 m0, s46
	s_nop 0
	global_load_lds_dwordx4 v167, s[0:1]
	s_add_u32 s58, s28, s27
	s_mov_b32 m0, s50
	s_nop 0
	global_load_lds_dwordx4 v175, s[0:1]
	s_addc_u32 s59, s29, s6
	s_add_i32 s53, s17, 0x2000
	s_add_i32 s65, s17, 0x4000
	v_lshlrev_b32_e32 v4, 11, v4
	s_mov_b32 m0, s17
	s_nop 0
	global_load_lds_dwordx4 v165, s[58:59]
	s_add_u32 s28, s58, 0x40000
	v_lshl_add_u32 v171, v2, 1, v4
	s_mov_b32 m0, s53
	s_nop 0
	global_load_lds_dwordx4 v171, s[58:59]
	s_addc_u32 s29, s59, 0
	s_add_i32 s67, s17, 0x6000
	s_mov_b32 m0, s65
	s_nop 0
	global_load_lds_dwordx4 v165, s[28:29]
	s_cmp_eq_u32 s5, 1
	v_writelane_b32 v254, s31, 59
	s_mov_b32 m0, s67
	s_nop 0
	global_load_lds_dwordx4 v171, s[28:29]
	s_cselect_b64 s[28:29], -1, 0
	v_writelane_b32 v254, s28, 60
	s_mov_b32 s75, s30
	s_cmp_lg_u32 s5, 1
	v_writelane_b32 v254, s29, 61
	s_cbranch_scc1 .LBB0_257
	s_barrier
	s_setprio 1

; #define PG8_STAGE(bufoff, gbase, voff) do { _Pragma("unroll") for (int _i = 0; _i < 2; ++_i) { \
;         const unsigned _m0 = ldsb + (unsigned)((bufoff) + _i * 8192); const char* _gb = (const char*)(gbase); \
;         asm volatile("s_mov_b32 m0, %0\n\ts_nop 0\n\tglobal_load_lds_dwordx4 %1, %2" :: "s"(_m0), "v"((voff)[_i]), "s"(_gb) : "m0", "memory"); } } while (0)
; #define PG8_LDA(dst, b, h) do { _Pragma("unroll") for (int m = 0; m < 4; ++m) _Pragma("unroll") for (int k = 0; k < 2; ++k) dst[m][k] = *(const LAS bf16x8*)(lds + PG8_SA(b, h) + aoff + m * 2048 + k * 1024); } while (0)
; #define PG8_LDB(dst, b, h) do { _Pragma("unroll") for (int n = 0; n < 2; ++n) _Pragma("unroll") for (int k = 0; k < 2; ++k) dst[n][k] = *(const LAS bf16x8*)(lds + PG8_SB(b, h) + boff + n * 2048 + k * 1024); } while (0)
; #define PG8_WAIT_V(n) asm volatile("s_waitcnt vmcnt(" #n ")" ::: "memory")
; #define PG8_WAIT_L(n) asm volatile("s_waitcnt lgkmcnt(" #n ")" ::: "memory")
; #define PG8_BAR __builtin_amdgcn_s_barrier()
; #define PG8_SCHED __builtin_amdgcn_sched_barrier(0)
; template <class Epi, bool ALIGN_EPI>
; __device__ __forceinline__ void gemm_phase(LAS unsigned char* lds, const Gemm g, const StaticOrder& S, const Epi& E) {
;     ...
;         const bool has_next = S.next(ui + 1, nxt);
;         const char* nA = has_next ? (const char*)g.A + (size_t)nxt.pm * tstepA + (size_t)nxt.pn * g.a_pn_off * 2 + (size_t)(nxt.pm >> 4) * g.a_adj : cA; const char* nB = has_next ? (const char*)g.Bt + (size_t)nxt.pn * tstepB : cB;
;         for (int t = 0; t < nt; t += 2) {
;             const bool last = (t == nt - 2);
;             const char* a1 = cA + (size_t)(t + 1) * kstep;
;             const char* a2 = last ? nA : cA + (size_t)(t + 2) * kstep; const char* b2 = last ? nB : cB + (size_t)(t + 2) * kstep;
;             const char* a3 = a2 + kstep; const char* b3 = b2 + kstep;
;             PG8_LDB(B0, 0, 0); PG8_LDB(B1, 0, 1); PG8_SCHED; PG8_LDA(At, 0, 0); PG8_STAGE(PG8_SA(1, 1), a1 + hstepA, voffA);
;             PG8_WAIT_V(8); PG8_WAIT_L(0); PG8_BAR; PG8_MMA(0, 0, At, B0); PG8_MMA(0, 1, At, B1); PG8_BAR; PG8_SCHED;
;             PG8_LDA(At, 0, 1); PG8_STAGE(PG8_SB(0, 0), b2, voffB); PG8_STAGE(PG8_SB(0, 1), b2 + hstepB, voffB); PG8_STAGE(PG8_SA(0, 0), a2, voffA);
;             PG8_WAIT_V(8); PG8_WAIT_L(0); PG8_BAR; PG8_MMA(1, 0, At, B0); PG8_MMA(1, 1, At, B1); PG8_BAR; PG8_SCHED;
.LBB0_270:
	s_add_u32 s4, s56, 0x100
	s_addc_u32 s5, s57, 0
	s_add_u32 s0, s58, 0x40080
	s_addc_u32 s1, s59, 0
	s_mov_b32 s44, 0
	s_add_i32 s55, s44, 2
	s_add_u32 s45, s0, 0xfffc0080
	s_addc_u32 s56, s1, -1
	s_cmp_eq_u32 s68, s44
	s_cselect_b32 s60, s96, s45
	s_cselect_b32 s61, s97, s56
	s_cselect_b32 s58, s48, s4
	s_cselect_b32 s59, s49, s5
	s_add_u32 s56, s60, 0x80
	s_addc_u32 s57, s61, 0
	s_mov_b32 m0, s41
	s_nop 0
	global_load_lds_dwordx4 v165, s[0:1]
	s_nop 0
	s_mov_b32 m0, s30
	s_nop 0
	global_load_lds_dwordx4 v171, s[0:1]
	s_waitcnt vmcnt(8)
	s_waitcnt lgkmcnt(0)
	s_barrier
	s_waitcnt lgkmcnt(0)
	v_mfma_f32_16x16x32_bf16 v[126:129], v[130:133], v[182:185], 0
	v_mfma_f32_16x16x32_bf16 v[126:129], v[134:137], v[186:189], v[126:129]
	v_mfma_f32_16x16x32_bf16 v[122:125], v[138:141], v[182:185], 0
	v_mfma_f32_16x16x32_bf16 v[122:125], v[142:145], v[186:189], v[122:125]
	v_mfma_f32_16x16x32_bf16 v[118:121], v[146:149], v[182:185], 0
	v_mfma_f32_16x16x32_bf16 v[118:121], v[150:153], v[186:189], v[118:121]
	v_mfma_f32_16x16x32_bf16 v[110:113], v[154:157], v[182:185], 0
	v_mfma_f32_16x16x32_bf16 v[110:113], v[158:161], v[186:189], v[110:113]
	v_mfma_f32_16x16x32_bf16 v[94:97], v[154:157], v[190:193], 0
	v_mfma_f32_16x16x32_bf16 v[94:97], v[158:161], v[202:205], v[94:97]
	v_mfma_f32_16x16x32_bf16 v[102:105], v[146:149], v[190:193], 0
	v_mfma_f32_16x16x32_bf16 v[102:105], v[150:153], v[202:205], v[102:105]
	v_mfma_f32_16x16x32_bf16 v[106:109], v[138:141], v[190:193], 0
	v_mfma_f32_16x16x32_bf16 v[106:109], v[142:145], v[202:205], v[106:109]
	v_mfma_f32_16x16x32_bf16 v[114:117], v[130:133], v[190:193], 0
	v_mfma_f32_16x16x32_bf16 v[114:117], v[134:137], v[202:205], v[114:117]
	v_mfma_f32_16x16x32_bf16 v[98:101], v[130:133], v[206:209], 0
	v_mfma_f32_16x16x32_bf16 v[98:101], v[134:137], v[210:213], v[98:101]
	v_mfma_f32_16x16x32_bf16 v[90:93], v[138:141], v[206:209], 0
	v_mfma_f32_16x16x32_bf16 v[90:93], v[142:145], v[210:213], v[90:93]
	v_mfma_f32_16x16x32_bf16 v[86:89], v[146:149], v[206:209], 0
	v_mfma_f32_16x16x32_bf16 v[86:89], v[150:153], v[210:213], v[86:89]
	v_mfma_f32_16x16x32_bf16 v[78:81], v[154:157], v[206:209], 0
	v_mfma_f32_16x16x32_bf16 v[78:81], v[158:161], v[210:213], v[78:81]
	v_mfma_f32_16x16x32_bf16 v[66:69], v[154:157], v[214:217], 0
	v_mfma_f32_16x16x32_bf16 v[66:69], v[158:161], v[240:243], v[66:69]
	v_mfma_f32_16x16x32_bf16 v[70:73], v[146:149], v[214:217], 0
	v_mfma_f32_16x16x32_bf16 v[70:73], v[150:153], v[240:243], v[70:73]
	v_mfma_f32_16x16x32_bf16 v[74:77], v[138:141], v[214:217], 0
	v_mfma_f32_16x16x32_bf16 v[74:77], v[142:145], v[240:243], v[74:77]
	v_mfma_f32_16x16x32_bf16 v[82:85], v[130:133], v[214:217], 0
	v_mfma_f32_16x16x32_bf16 v[82:85], v[134:137], v[240:243], v[82:85]
	s_barrier
	ds_read_b128 v[182:185], v180 offset:16384
	ds_read_b128 v[186:189], v180 offset:17408
	ds_read_b128 v[190:193], v180 offset:18432
	ds_read_b128 v[202:205], v180 offset:19456
	ds_read_b128 v[206:209], v180 offset:20480
	ds_read_b128 v[210:213], v180 offset:21504
	ds_read_b128 v[214:217], v180 offset:22528
	ds_read_b128 v[240:243], v180 offset:23552
	s_mov_b32 m0, s42
	s_nop 0
	global_load_lds_dwordx4 v167, s[58:59]
	s_add_u32 s44, s58, s14
	s_mov_b32 m0, s43
	s_nop 0
	global_load_lds_dwordx4 v175, s[58:59]
	s_addc_u32 s45, s59, 0
	s_mov_b32 m0, s46
	s_nop 0
	global_load_lds_dwordx4 v167, s[44:45]
	s_nop 0
	s_mov_b32 m0, s50
	s_nop 0
	global_load_lds_dwordx4 v175, s[44:45]
	s_nop 0
	s_mov_b32 m0, s17
	s_nop 0
	global_load_lds_dwordx4 v165, s[60:61]
	s_nop 0
	s_mov_b32 m0, s53
	s_nop 0
	global_load_lds_dwordx4 v171, s[60:61]
	s_waitcnt vmcnt(8)
	s_waitcnt lgkmcnt(0)
	s_barrier
	s_waitcnt lgkmcnt(0)
	v_mfma_f32_16x16x32_bf16 v[62:65], v[130:133], v[182:185], 0
	v_mfma_f32_16x16x32_bf16 v[62:65], v[134:137], v[186:189], v[62:65]
	v_mfma_f32_16x16x32_bf16 v[58:61], v[138:141], v[182:185], 0
	v_mfma_f32_16x16x32_bf16 v[58:61], v[142:145], v[186:189], v[58:61]
	v_mfma_f32_16x16x32_bf16 v[54:57], v[146:149], v[182:185], 0
	v_mfma_f32_16x16x32_bf16 v[54:57], v[150:153], v[186:189], v[54:57]
	v_mfma_f32_16x16x32_bf16 v[50:53], v[154:157], v[182:185], 0
	v_mfma_f32_16x16x32_bf16 v[50:53], v[158:161], v[186:189], v[50:53]
	v_mfma_f32_16x16x32_bf16 v[30:33], v[154:157], v[190:193], 0
	v_mfma_f32_16x16x32_bf16 v[30:33], v[158:161], v[202:205], v[30:33]
	v_mfma_f32_16x16x32_bf16 v[38:41], v[146:149], v[190:193], 0
	v_mfma_f32_16x16x32_bf16 v[38:41], v[150:153], v[202:205], v[38:41]
	v_mfma_f32_16x16x32_bf16 v[42:45], v[138:141], v[190:193], 0
	v_mfma_f32_16x16x32_bf16 v[42:45], v[142:145], v[202:205], v[42:45]
	v_mfma_f32_16x16x32_bf16 v[46:49], v[130:133], v[190:193], 0
	v_mfma_f32_16x16x32_bf16 v[46:49], v[134:137], v[202:205], v[46:49]
	v_mfma_f32_16x16x32_bf16 v[34:37], v[130:133], v[206:209], 0
	v_mfma_f32_16x16x32_bf16 v[34:37], v[134:137], v[210:213], v[34:37]
	v_mfma_f32_16x16x32_bf16 v[26:29], v[138:141], v[206:209], 0
	v_mfma_f32_16x16x32_bf16 v[26:29], v[142:145], v[210:213], v[26:29]
	v_mfma_f32_16x16x32_bf16 v[22:25], v[146:149], v[206:209], 0
	v_mfma_f32_16x16x32_bf16 v[22:25], v[150:153], v[210:213], v[22:25]
	v_mfma_f32_16x16x32_bf16 v[14:17], v[154:157], v[206:209], 0
	v_mfma_f32_16x16x32_bf16 v[14:17], v[158:161], v[210:213], v[14:17]
	v_mfma_f32_16x16x32_bf16 v[2:5], v[154:157], v[214:217], 0
	v_mfma_f32_16x16x32_bf16 v[2:5], v[158:161], v[240:243], v[2:5]
	v_mfma_f32_16x16x32_bf16 v[6:9], v[146:149], v[214:217], 0
	v_mfma_f32_16x16x32_bf16 v[6:9], v[150:153], v[240:243], v[6:9]
	v_mfma_f32_16x16x32_bf16 v[10:13], v[138:141], v[214:217], 0
	v_mfma_f32_16x16x32_bf16 v[10:13], v[142:145], v[240:243], v[10:13]
	v_mfma_f32_16x16x32_bf16 v[18:21], v[130:133], v[214:217], 0
	v_mfma_f32_16x16x32_bf16 v[18:21], v[134:137], v[240:243], v[18:21]
	s_barrier
; #define PG8_STAGE(bufoff, gbase, voff) do { _Pragma("unroll") for (int _i = 0; _i < 2; ++_i) { \
;         const unsigned _m0 = ldsb + (unsigned)((bufoff) + _i * 8192); const char* _gb = (const char*)(gbase); \
;         asm volatile("s_mov_b32 m0, %0\n\ts_nop 0\n\tglobal_load_lds_dwordx4 %1, %2" :: "s"(_m0), "v"((voff)[_i]), "s"(_gb) : "m0", "memory"); } } while (0)
; #define PG8_LDA(dst, b, h) do { _Pragma("unroll") for (int m = 0; m < 4; ++m) _Pragma("unroll") for (int k = 0; k < 2; ++k) dst[m][k] = *(const LAS bf16x8*)(lds + PG8_SA(b, h) + aoff + m * 2048 + k * 1024); } while (0)
; #define PG8_LDB(dst, b, h) do { _Pragma("unroll") for (int n = 0; n < 2; ++n) _Pragma("unroll") for (int k = 0; k < 2; ++k) dst[n][k] = *(const LAS bf16x8*)(lds + PG8_SB(b, h) + boff + n * 2048 + k * 1024); } while (0)
; #define PG8_MMA(ai, bj, At, Bt) do { __builtin_amdgcn_s_setprio(1); _Pragma("unroll") for (int m = 0; m < 4; ++m) _Pragma("unroll") for (int n = 0; n < 2; ++n) _Pragma("unroll") for (int k = 0; k < 2; ++k) \
;         acc[ai][bj][m][n] = __builtin_amdgcn_mfma_f32_16x16x32_bf16(Bt[n][k], At[m][k], acc[ai][bj][m][n], 0, 0, 0); __builtin_amdgcn_s_setprio(0); } while (0)
; #define PG8_WAIT_V(n) asm volatile("s_waitcnt vmcnt(" #n ")" ::: "memory")
; #define PG8_WAIT_L(n) asm volatile("s_waitcnt lgkmcnt(" #n ")" ::: "memory")
; #define PG8_BAR __builtin_amdgcn_s_barrier()
; #define PG8_SCHED __builtin_amdgcn_sched_barrier(0)
; template <class Epi, bool ALIGN_EPI>
; __device__ __forceinline__ void gemm_phase(LAS unsigned char* lds, const Gemm g, const StaticOrder& S, const Epi& E) {
;     ...
;             PG8_LDB(B0, 1, 0); PG8_LDB(B1, 1, 1); PG8_SCHED; PG8_LDA(At, 1, 0); PG8_STAGE(PG8_SA(0, 1), a2 + hstepA, voffA);
;             PG8_WAIT_V(8); PG8_WAIT_L(0); PG8_BAR; PG8_MMA(0, 0, At, B0); PG8_MMA(0, 1, At, B1); PG8_BAR; PG8_SCHED;
;             PG8_LDA(At, 1, 1); PG8_STAGE(PG8_SB(1, 0), b3, voffB); PG8_STAGE(PG8_SB(1, 1), b3 + hstepB, voffB); PG8_STAGE(PG8_SA(1, 0), a3, voffA);
;             PG8_WAIT_V(8); PG8_WAIT_L(0); PG8_BAR; PG8_MMA(1, 0, At, B0); PG8_MMA(1, 1, At, B1); PG8_BAR; PG8_SCHED;
;         }
;         if constexpr (ALIGN_EPI) { if (wr == 0) PG8_BAR; }
	v_add_u32_e32 v0, 0x18000, v179
	ds_read_b128 v[130:133], v0
	ds_read_b128 v[134:137], v0 offset:1024
	ds_read_b128 v[138:141], v0 offset:2048
	ds_read_b128 v[142:145], v0 offset:3072
	v_add_u32_e32 v0, 0x1c000, v179
	ds_read_b128 v[146:149], v0
	ds_read_b128 v[150:153], v0 offset:1024
	ds_read_b128 v[154:157], v0 offset:2048
	ds_read_b128 v[158:161], v0 offset:3072
	ds_read_b128 v[182:185], v180 offset:32768
	ds_read_b128 v[186:189], v180 offset:33792
	ds_read_b128 v[190:193], v180 offset:34816
	ds_read_b128 v[202:205], v180 offset:35840
	ds_read_b128 v[206:209], v180 offset:36864
	ds_read_b128 v[210:213], v180 offset:37888
	ds_read_b128 v[214:217], v180 offset:38912
	ds_read_b128 v[240:243], v180 offset:39936
	s_add_u32 s60, s60, 0x40000
	s_addc_u32 s61, s61, 0
	s_mov_b32 m0, s65
	s_nop 0
	global_load_lds_dwordx4 v165, s[60:61]
	s_nop 0
	s_mov_b32 m0, s67
	s_nop 0
	global_load_lds_dwordx4 v171, s[60:61]
	s_waitcnt vmcnt(8)
	s_waitcnt lgkmcnt(0)
	s_barrier
	s_waitcnt lgkmcnt(0)
	v_mfma_f32_16x16x32_bf16 v[126:129], v[130:133], v[182:185], v[126:129]
	v_mfma_f32_16x16x32_bf16 v[126:129], v[134:137], v[186:189], v[126:129]
	v_mfma_f32_16x16x32_bf16 v[122:125], v[138:141], v[182:185], v[122:125]
	v_mfma_f32_16x16x32_bf16 v[122:125], v[142:145], v[186:189], v[122:125]
	v_mfma_f32_16x16x32_bf16 v[118:121], v[146:149], v[182:185], v[118:121]
	v_mfma_f32_16x16x32_bf16 v[118:121], v[150:153], v[186:189], v[118:121]
	v_mfma_f32_16x16x32_bf16 v[110:113], v[154:157], v[182:185], v[110:113]
	v_mfma_f32_16x16x32_bf16 v[110:113], v[158:161], v[186:189], v[110:113]
	v_mfma_f32_16x16x32_bf16 v[94:97], v[154:157], v[190:193], v[94:97]
	v_mfma_f32_16x16x32_bf16 v[94:97], v[158:161], v[202:205], v[94:97]
	v_mfma_f32_16x16x32_bf16 v[102:105], v[146:149], v[190:193], v[102:105]
	v_mfma_f32_16x16x32_bf16 v[102:105], v[150:153], v[202:205], v[102:105]
	v_mfma_f32_16x16x32_bf16 v[106:109], v[138:141], v[190:193], v[106:109]
	v_mfma_f32_16x16x32_bf16 v[106:109], v[142:145], v[202:205], v[106:109]
	v_mfma_f32_16x16x32_bf16 v[114:117], v[130:133], v[190:193], v[114:117]
	v_mfma_f32_16x16x32_bf16 v[114:117], v[134:137], v[202:205], v[114:117]
	v_mfma_f32_16x16x32_bf16 v[98:101], v[130:133], v[206:209], v[98:101]
	v_mfma_f32_16x16x32_bf16 v[98:101], v[134:137], v[210:213], v[98:101]
	v_mfma_f32_16x16x32_bf16 v[90:93], v[138:141], v[206:209], v[90:93]
	v_mfma_f32_16x16x32_bf16 v[90:93], v[142:145], v[210:213], v[90:93]
	v_mfma_f32_16x16x32_bf16 v[86:89], v[146:149], v[206:209], v[86:89]
	v_mfma_f32_16x16x32_bf16 v[86:89], v[150:153], v[210:213], v[86:89]
	v_mfma_f32_16x16x32_bf16 v[78:81], v[154:157], v[206:209], v[78:81]
	v_mfma_f32_16x16x32_bf16 v[78:81], v[158:161], v[210:213], v[78:81]
	v_mfma_f32_16x16x32_bf16 v[66:69], v[154:157], v[214:217], v[66:69]
	v_mfma_f32_16x16x32_bf16 v[66:69], v[158:161], v[240:243], v[66:69]
	v_mfma_f32_16x16x32_bf16 v[70:73], v[146:149], v[214:217], v[70:73]
	v_mfma_f32_16x16x32_bf16 v[70:73], v[150:153], v[240:243], v[70:73]
	v_mfma_f32_16x16x32_bf16 v[74:77], v[138:141], v[214:217], v[74:77]
	v_mfma_f32_16x16x32_bf16 v[74:77], v[142:145], v[240:243], v[74:77]
	v_mfma_f32_16x16x32_bf16 v[82:85], v[130:133], v[214:217], v[82:85]
	v_mfma_f32_16x16x32_bf16 v[82:85], v[134:137], v[240:243], v[82:85]
	s_barrier
	ds_read_b128 v[182:185], v180 offset:49152
	ds_read_b128 v[186:189], v180 offset:50176
	ds_read_b128 v[190:193], v180 offset:51200
	ds_read_b128 v[202:205], v180 offset:52224
	ds_read_b128 v[206:209], v180 offset:53248
	ds_read_b128 v[210:213], v180 offset:54272
	ds_read_b128 v[214:217], v180 offset:55296
	ds_read_b128 v[240:243], v180 offset:56320
	s_add_u32 s58, s58, 0x80
	s_addc_u32 s59, s59, 0
	s_mov_b32 m0, s89
	s_nop 0
	global_load_lds_dwordx4 v167, s[58:59]
	s_add_u32 s44, s44, 0x80
	s_mov_b32 m0, s95
	s_nop 0
	global_load_lds_dwordx4 v175, s[58:59]
	s_addc_u32 s45, s45, 0
	s_mov_b32 m0, s26
	s_nop 0
	global_load_lds_dwordx4 v167, s[44:45]
	s_nop 0
	s_mov_b32 m0, s27
	s_nop 0
	global_load_lds_dwordx4 v175, s[44:45]
	s_nop 0
	s_mov_b32 m0, s36
	s_nop 0
	global_load_lds_dwordx4 v165, s[56:57]
	s_nop 0
	s_mov_b32 m0, s37
	s_nop 0
	global_load_lds_dwordx4 v171, s[56:57]
	s_waitcnt vmcnt(8)
	s_waitcnt lgkmcnt(0)
	s_barrier
	s_waitcnt lgkmcnt(0)
	v_mfma_f32_16x16x32_bf16 v[62:65], v[130:133], v[182:185], v[62:65]
	v_mfma_f32_16x16x32_bf16 v[62:65], v[134:137], v[186:189], v[62:65]
	v_mfma_f32_16x16x32_bf16 v[58:61], v[138:141], v[182:185], v[58:61]
	v_mfma_f32_16x16x32_bf16 v[58:61], v[142:145], v[186:189], v[58:61]
	v_mfma_f32_16x16x32_bf16 v[54:57], v[146:149], v[182:185], v[54:57]
	v_mfma_f32_16x16x32_bf16 v[54:57], v[150:153], v[186:189], v[54:57]
	v_mfma_f32_16x16x32_bf16 v[50:53], v[154:157], v[182:185], v[50:53]
	v_mfma_f32_16x16x32_bf16 v[50:53], v[158:161], v[186:189], v[50:53]
	v_mfma_f32_16x16x32_bf16 v[30:33], v[154:157], v[190:193], v[30:33]
	v_mfma_f32_16x16x32_bf16 v[30:33], v[158:161], v[202:205], v[30:33]
	v_mfma_f32_16x16x32_bf16 v[38:41], v[146:149], v[190:193], v[38:41]
	v_mfma_f32_16x16x32_bf16 v[38:41], v[150:153], v[202:205], v[38:41]
	v_mfma_f32_16x16x32_bf16 v[42:45], v[138:141], v[190:193], v[42:45]
	v_mfma_f32_16x16x32_bf16 v[42:45], v[142:145], v[202:205], v[42:45]
	v_mfma_f32_16x16x32_bf16 v[46:49], v[130:133], v[190:193], v[46:49]
	v_mfma_f32_16x16x32_bf16 v[46:49], v[134:137], v[202:205], v[46:49]
	v_mfma_f32_16x16x32_bf16 v[34:37], v[130:133], v[206:209], v[34:37]
	v_mfma_f32_16x16x32_bf16 v[34:37], v[134:137], v[210:213], v[34:37]
	v_mfma_f32_16x16x32_bf16 v[26:29], v[138:141], v[206:209], v[26:29]
	v_mfma_f32_16x16x32_bf16 v[26:29], v[142:145], v[210:213], v[26:29]
	v_mfma_f32_16x16x32_bf16 v[22:25], v[146:149], v[206:209], v[22:25]
	v_mfma_f32_16x16x32_bf16 v[22:25], v[150:153], v[210:213], v[22:25]
	v_mfma_f32_16x16x32_bf16 v[14:17], v[154:157], v[206:209], v[14:17]
	v_mfma_f32_16x16x32_bf16 v[14:17], v[158:161], v[210:213], v[14:17]
	v_mfma_f32_16x16x32_bf16 v[2:5], v[154:157], v[214:217], v[2:5]
	v_mfma_f32_16x16x32_bf16 v[2:5], v[158:161], v[240:243], v[2:5]
	v_mfma_f32_16x16x32_bf16 v[6:9], v[146:149], v[214:217], v[6:9]
	v_mfma_f32_16x16x32_bf16 v[6:9], v[150:153], v[240:243], v[6:9]
	v_mfma_f32_16x16x32_bf16 v[10:13], v[138:141], v[214:217], v[10:13]
	v_mfma_f32_16x16x32_bf16 v[10:13], v[142:145], v[240:243], v[10:13]
	v_mfma_f32_16x16x32_bf16 v[18:21], v[130:133], v[214:217], v[18:21]
	v_mfma_f32_16x16x32_bf16 v[18:21], v[134:137], v[240:243], v[18:21]
	s_barrier
	s_add_u32 s4, s4, 0x100
	s_addc_u32 s5, s5, 0
	s_add_u32 s0, s0, 0x100
	s_addc_u32 s1, s1, 0
	s_cmp_ge_u32 s55, s31
	s_mov_b32 s44, s55
; #define PG8_STAGE(bufoff, gbase, voff) do { _Pragma("unroll") for (int _i = 0; _i < 2; ++_i) { \
;         const unsigned _m0 = ldsb + (unsigned)((bufoff) + _i * 8192); const char* _gb = (const char*)(gbase); \
;         asm volatile("s_mov_b32 m0, %0\n\ts_nop 0\n\tglobal_load_lds_dwordx4 %1, %2" :: "s"(_m0), "v"((voff)[_i]), "s"(_gb) : "m0", "memory"); } } while (0)
; #define PG8_LDA(dst, b, h) do { _Pragma("unroll") for (int m = 0; m < 4; ++m) _Pragma("unroll") for (int k = 0; k < 2; ++k) dst[m][k] = *(const LAS bf16x8*)(lds + PG8_SA(b, h) + aoff + m * 2048 + k * 1024); } while (0)
; #define PG8_LDB(dst, b, h) do { _Pragma("unroll") for (int n = 0; n < 2; ++n) _Pragma("unroll") for (int k = 0; k < 2; ++k) dst[n][k] = *(const LAS bf16x8*)(lds + PG8_SB(b, h) + boff + n * 2048 + k * 1024); } while (0)
; #define PG8_MMA(ai, bj, At, Bt) do { __builtin_amdgcn_s_setprio(1); _Pragma("unroll") for (int m = 0; m < 4; ++m) _Pragma("unroll") for (int n = 0; n < 2; ++n) _Pragma("unroll") for (int k = 0; k < 2; ++k) \
;         acc[ai][bj][m][n] = __builtin_amdgcn_mfma_f32_16x16x32_bf16(Bt[n][k], At[m][k], acc[ai][bj][m][n], 0, 0, 0); __builtin_amdgcn_s_setprio(0); } while (0)
; #define PG8_WAIT_V(n) asm volatile("s_waitcnt vmcnt(" #n ")" ::: "memory")
; #define PG8_WAIT_L(n) asm volatile("s_waitcnt lgkmcnt(" #n ")" ::: "memory")
; template <class Epi, bool ALIGN_EPI>
; __device__ __forceinline__ void gemm_phase(LAS unsigned char* lds, const Gemm g, const StaticOrder& S, const Epi& E) {
;     ...
;         for (int t = 0; t < nt; t += 2) {
;             const bool last = (t == nt - 2);
;             const char* a1 = cA + (size_t)(t + 1) * kstep;
;             const char* a2 = last ? nA : cA + (size_t)(t + 2) * kstep; const char* b2 = last ? nB : cB + (size_t)(t + 2) * kstep;
;             const char* a3 = a2 + kstep; const char* b3 = b2 + kstep;
;             PG8_LDB(B0, 0, 0); PG8_LDB(B1, 0, 1); PG8_SCHED; PG8_LDA(At, 0, 0); PG8_STAGE(PG8_SA(1, 1), a1 + hstepA, voffA);
;             PG8_WAIT_V(8); PG8_WAIT_L(0); PG8_BAR; PG8_MMA(0, 0, At, B0); PG8_MMA(0, 1, At, B1); PG8_BAR; PG8_SCHED;
;             PG8_LDA(At, 0, 1); PG8_STAGE(PG8_SB(0, 0), b2, voffB); PG8_STAGE(PG8_SB(0, 1), b2 + hstepB, voffB); PG8_STAGE(PG8_SA(0, 0), a2, voffA);
;             PG8_WAIT_V(8); PG8_WAIT_L(0); PG8_BAR; PG8_MMA(1, 0, At, B0); PG8_MMA(1, 1, At, B1); PG8_BAR; PG8_SCHED;
.LBB0_271:
	v_add_u32_e32 v0, 0x10000, v179
	ds_read_b128 v[130:133], v0
	ds_read_b128 v[134:137], v0 offset:1024
	ds_read_b128 v[138:141], v0 offset:2048
	ds_read_b128 v[142:145], v0 offset:3072
	v_add_u32_e32 v0, 0x14000, v179
	ds_read_b128 v[146:149], v0
	ds_read_b128 v[150:153], v0 offset:1024
	ds_read_b128 v[154:157], v0 offset:2048
	ds_read_b128 v[158:161], v0 offset:3072
	s_add_i32 s55, s44, 2
	s_add_u32 s45, s0, 0xfffc0080
	s_addc_u32 s56, s1, -1
	s_cmp_eq_u32 s68, s44
	s_cselect_b32 s60, s96, s45
	s_cselect_b32 s61, s97, s56
	s_cselect_b32 s58, s48, s4
	s_cselect_b32 s59, s49, s5
	s_add_u32 s56, s60, 0x80
	s_addc_u32 s57, s61, 0
	ds_read_b128 v[182:185], v180
	ds_read_b128 v[186:189], v180 offset:1024
	ds_read_b128 v[190:193], v180 offset:2048
	ds_read_b128 v[202:205], v180 offset:3072
	ds_read_b128 v[206:209], v180 offset:4096
	ds_read_b128 v[210:213], v180 offset:5120
	ds_read_b128 v[214:217], v180 offset:6144
	ds_read_b128 v[240:243], v180 offset:7168
	s_mov_b32 m0, s41
	s_nop 0
	global_load_lds_dwordx4 v165, s[0:1]
	s_nop 0
	s_mov_b32 m0, s30
	s_nop 0
	global_load_lds_dwordx4 v171, s[0:1]
	s_waitcnt vmcnt(8)
	s_waitcnt lgkmcnt(0)
	s_barrier
	s_waitcnt lgkmcnt(0)
	v_mfma_f32_16x16x32_bf16 v[126:129], v[130:133], v[182:185], v[126:129]
	v_mfma_f32_16x16x32_bf16 v[126:129], v[134:137], v[186:189], v[126:129]
	v_mfma_f32_16x16x32_bf16 v[122:125], v[138:141], v[182:185], v[122:125]
	v_mfma_f32_16x16x32_bf16 v[122:125], v[142:145], v[186:189], v[122:125]
	v_mfma_f32_16x16x32_bf16 v[118:121], v[146:149], v[182:185], v[118:121]
	v_mfma_f32_16x16x32_bf16 v[118:121], v[150:153], v[186:189], v[118:121]
	v_mfma_f32_16x16x32_bf16 v[110:113], v[154:157], v[182:185], v[110:113]
	v_mfma_f32_16x16x32_bf16 v[110:113], v[158:161], v[186:189], v[110:113]
	v_mfma_f32_16x16x32_bf16 v[94:97], v[154:157], v[190:193], v[94:97]
	v_mfma_f32_16x16x32_bf16 v[94:97], v[158:161], v[202:205], v[94:97]
	v_mfma_f32_16x16x32_bf16 v[102:105], v[146:149], v[190:193], v[102:105]
	v_mfma_f32_16x16x32_bf16 v[102:105], v[150:153], v[202:205], v[102:105]
	v_mfma_f32_16x16x32_bf16 v[106:109], v[138:141], v[190:193], v[106:109]
	v_mfma_f32_16x16x32_bf16 v[106:109], v[142:145], v[202:205], v[106:109]
	v_mfma_f32_16x16x32_bf16 v[114:117], v[130:133], v[190:193], v[114:117]
	v_mfma_f32_16x16x32_bf16 v[114:117], v[134:137], v[202:205], v[114:117]
	v_mfma_f32_16x16x32_bf16 v[98:101], v[130:133], v[206:209], v[98:101]
	v_mfma_f32_16x16x32_bf16 v[98:101], v[134:137], v[210:213], v[98:101]
	v_mfma_f32_16x16x32_bf16 v[90:93], v[138:141], v[206:209], v[90:93]
	v_mfma_f32_16x16x32_bf16 v[90:93], v[142:145], v[210:213], v[90:93]
	v_mfma_f32_16x16x32_bf16 v[86:89], v[146:149], v[206:209], v[86:89]
	v_mfma_f32_16x16x32_bf16 v[86:89], v[150:153], v[210:213], v[86:89]
	v_mfma_f32_16x16x32_bf16 v[78:81], v[154:157], v[206:209], v[78:81]
	v_mfma_f32_16x16x32_bf16 v[78:81], v[158:161], v[210:213], v[78:81]
	v_mfma_f32_16x16x32_bf16 v[66:69], v[154:157], v[214:217], v[66:69]
	v_mfma_f32_16x16x32_bf16 v[66:69], v[158:161], v[240:243], v[66:69]
	v_mfma_f32_16x16x32_bf16 v[70:73], v[146:149], v[214:217], v[70:73]
	v_mfma_f32_16x16x32_bf16 v[70:73], v[150:153], v[240:243], v[70:73]
	v_mfma_f32_16x16x32_bf16 v[74:77], v[138:141], v[214:217], v[74:77]
	v_mfma_f32_16x16x32_bf16 v[74:77], v[142:145], v[240:243], v[74:77]
	v_mfma_f32_16x16x32_bf16 v[82:85], v[130:133], v[214:217], v[82:85]
	v_mfma_f32_16x16x32_bf16 v[82:85], v[134:137], v[240:243], v[82:85]
	s_barrier
	ds_read_b128 v[182:185], v180 offset:16384
	ds_read_b128 v[186:189], v180 offset:17408
	ds_read_b128 v[190:193], v180 offset:18432
	ds_read_b128 v[202:205], v180 offset:19456
	ds_read_b128 v[206:209], v180 offset:20480
	ds_read_b128 v[210:213], v180 offset:21504
	ds_read_b128 v[214:217], v180 offset:22528
	ds_read_b128 v[240:243], v180 offset:23552
	s_mov_b32 m0, s42
	s_nop 0
	global_load_lds_dwordx4 v167, s[58:59]
	s_add_u32 s44, s58, s14
	s_mov_b32 m0, s43
	s_nop 0
	global_load_lds_dwordx4 v175, s[58:59]
	s_addc_u32 s45, s59, 0
	s_mov_b32 m0, s46
	s_nop 0
	global_load_lds_dwordx4 v167, s[44:45]
	s_nop 0
	s_mov_b32 m0, s50
	s_nop 0
	global_load_lds_dwordx4 v175, s[44:45]
	s_nop 0
	s_mov_b32 m0, s17
	s_nop 0
	global_load_lds_dwordx4 v165, s[60:61]
	s_nop 0
	s_mov_b32 m0, s53
	s_nop 0
	global_load_lds_dwordx4 v171, s[60:61]
	s_waitcnt vmcnt(8)
	s_waitcnt lgkmcnt(0)
	s_barrier
	s_waitcnt lgkmcnt(0)
	v_mfma_f32_16x16x32_bf16 v[62:65], v[130:133], v[182:185], v[62:65]
	v_mfma_f32_16x16x32_bf16 v[62:65], v[134:137], v[186:189], v[62:65]
	v_mfma_f32_16x16x32_bf16 v[58:61], v[138:141], v[182:185], v[58:61]
	v_mfma_f32_16x16x32_bf16 v[58:61], v[142:145], v[186:189], v[58:61]
	v_mfma_f32_16x16x32_bf16 v[54:57], v[146:149], v[182:185], v[54:57]
	v_mfma_f32_16x16x32_bf16 v[54:57], v[150:153], v[186:189], v[54:57]
	v_mfma_f32_16x16x32_bf16 v[50:53], v[154:157], v[182:185], v[50:53]
	v_mfma_f32_16x16x32_bf16 v[50:53], v[158:161], v[186:189], v[50:53]
	v_mfma_f32_16x16x32_bf16 v[30:33], v[154:157], v[190:193], v[30:33]
	v_mfma_f32_16x16x32_bf16 v[30:33], v[158:161], v[202:205], v[30:33]
	v_mfma_f32_16x16x32_bf16 v[38:41], v[146:149], v[190:193], v[38:41]
	v_mfma_f32_16x16x32_bf16 v[38:41], v[150:153], v[202:205], v[38:41]
	v_mfma_f32_16x16x32_bf16 v[42:45], v[138:141], v[190:193], v[42:45]
	v_mfma_f32_16x16x32_bf16 v[42:45], v[142:145], v[202:205], v[42:45]
	v_mfma_f32_16x16x32_bf16 v[46:49], v[130:133], v[190:193], v[46:49]
	v_mfma_f32_16x16x32_bf16 v[46:49], v[134:137], v[202:205], v[46:49]
	v_mfma_f32_16x16x32_bf16 v[34:37], v[130:133], v[206:209], v[34:37]
	v_mfma_f32_16x16x32_bf16 v[34:37], v[134:137], v[210:213], v[34:37]
	v_mfma_f32_16x16x32_bf16 v[26:29], v[138:141], v[206:209], v[26:29]
	v_mfma_f32_16x16x32_bf16 v[26:29], v[142:145], v[210:213], v[26:29]
	v_mfma_f32_16x16x32_bf16 v[22:25], v[146:149], v[206:209], v[22:25]
	v_mfma_f32_16x16x32_bf16 v[22:25], v[150:153], v[210:213], v[22:25]
	v_mfma_f32_16x16x32_bf16 v[14:17], v[154:157], v[206:209], v[14:17]
	v_mfma_f32_16x16x32_bf16 v[14:17], v[158:161], v[210:213], v[14:17]
	v_mfma_f32_16x16x32_bf16 v[2:5], v[154:157], v[214:217], v[2:5]
	v_mfma_f32_16x16x32_bf16 v[2:5], v[158:161], v[240:243], v[2:5]
	v_mfma_f32_16x16x32_bf16 v[6:9], v[146:149], v[214:217], v[6:9]
	v_mfma_f32_16x16x32_bf16 v[6:9], v[150:153], v[240:243], v[6:9]
	v_mfma_f32_16x16x32_bf16 v[10:13], v[138:141], v[214:217], v[10:13]
	v_mfma_f32_16x16x32_bf16 v[10:13], v[142:145], v[240:243], v[10:13]
	v_mfma_f32_16x16x32_bf16 v[18:21], v[130:133], v[214:217], v[18:21]
	v_mfma_f32_16x16x32_bf16 v[18:21], v[134:137], v[240:243], v[18:21]
	s_barrier
; #define PG8_STAGE(bufoff, gbase, voff) do { _Pragma("unroll") for (int _i = 0; _i < 2; ++_i) { \
;         const unsigned _m0 = ldsb + (unsigned)((bufoff) + _i * 8192); const char* _gb = (const char*)(gbase); \
;         asm volatile("s_mov_b32 m0, %0\n\ts_nop 0\n\tglobal_load_lds_dwordx4 %1, %2" :: "s"(_m0), "v"((voff)[_i]), "s"(_gb) : "m0", "memory"); } } while (0)
; #define PG8_LDA(dst, b, h) do { _Pragma("unroll") for (int m = 0; m < 4; ++m) _Pragma("unroll") for (int k = 0; k < 2; ++k) dst[m][k] = *(const LAS bf16x8*)(lds + PG8_SA(b, h) + aoff + m * 2048 + k * 1024); } while (0)
; #define PG8_LDB(dst, b, h) do { _Pragma("unroll") for (int n = 0; n < 2; ++n) _Pragma("unroll") for (int k = 0; k < 2; ++k) dst[n][k] = *(const LAS bf16x8*)(lds + PG8_SB(b, h) + boff + n * 2048 + k * 1024); } while (0)
; #define PG8_MMA(ai, bj, At, Bt) do { __builtin_amdgcn_s_setprio(1); _Pragma("unroll") for (int m = 0; m < 4; ++m) _Pragma("unroll") for (int n = 0; n < 2; ++n) _Pragma("unroll") for (int k = 0; k < 2; ++k) \
;         acc[ai][bj][m][n] = __builtin_amdgcn_mfma_f32_16x16x32_bf16(Bt[n][k], At[m][k], acc[ai][bj][m][n], 0, 0, 0); __builtin_amdgcn_s_setprio(0); } while (0)
; #define PG8_WAIT_V(n) asm volatile("s_waitcnt vmcnt(" #n ")" ::: "memory")
; #define PG8_WAIT_L(n) asm volatile("s_waitcnt lgkmcnt(" #n ")" ::: "memory")
; #define PG8_BAR __builtin_amdgcn_s_barrier()
; #define PG8_SCHED __builtin_amdgcn_sched_barrier(0)
; template <class Epi, bool ALIGN_EPI>
; __device__ __forceinline__ void gemm_phase(LAS unsigned char* lds, const Gemm g, const StaticOrder& S, const Epi& E) {
;     ...
;             PG8_LDB(B0, 1, 0); PG8_LDB(B1, 1, 1); PG8_SCHED; PG8_LDA(At, 1, 0); PG8_STAGE(PG8_SA(0, 1), a2 + hstepA, voffA);
;             PG8_WAIT_V(8); PG8_WAIT_L(0); PG8_BAR; PG8_MMA(0, 0, At, B0); PG8_MMA(0, 1, At, B1); PG8_BAR; PG8_SCHED;
;             PG8_LDA(At, 1, 1); PG8_STAGE(PG8_SB(1, 0), b3, voffB); PG8_STAGE(PG8_SB(1, 1), b3 + hstepB, voffB); PG8_STAGE(PG8_SA(1, 0), a3, voffA);
;             PG8_WAIT_V(8); PG8_WAIT_L(0); PG8_BAR; PG8_MMA(1, 0, At, B0); PG8_MMA(1, 1, At, B1); PG8_BAR; PG8_SCHED;
;         }
;         if constexpr (ALIGN_EPI) { if (wr == 0) PG8_BAR; }
;         E(acc, cur, wr, wc, fr, fq);
;         if (!has_next) break;
	v_add_u32_e32 v0, 0x18000, v179
	ds_read_b128 v[130:133], v0
	ds_read_b128 v[134:137], v0 offset:1024
	ds_read_b128 v[138:141], v0 offset:2048
	ds_read_b128 v[142:145], v0 offset:3072
	v_add_u32_e32 v0, 0x1c000, v179
	ds_read_b128 v[146:149], v0
	ds_read_b128 v[150:153], v0 offset:1024
	ds_read_b128 v[154:157], v0 offset:2048
	ds_read_b128 v[158:161], v0 offset:3072
	ds_read_b128 v[182:185], v180 offset:32768
	ds_read_b128 v[186:189], v180 offset:33792
	ds_read_b128 v[190:193], v180 offset:34816
	ds_read_b128 v[202:205], v180 offset:35840
	ds_read_b128 v[206:209], v180 offset:36864
	ds_read_b128 v[210:213], v180 offset:37888
	ds_read_b128 v[214:217], v180 offset:38912
	ds_read_b128 v[240:243], v180 offset:39936
	s_add_u32 s60, s60, 0x40000
	s_addc_u32 s61, s61, 0
	s_mov_b32 m0, s65
	s_nop 0
	global_load_lds_dwordx4 v165, s[60:61]
	s_nop 0
	s_mov_b32 m0, s67
	s_nop 0
	global_load_lds_dwordx4 v171, s[60:61]
	s_waitcnt vmcnt(8)
	s_waitcnt lgkmcnt(0)
	s_barrier
	s_waitcnt lgkmcnt(0)
	v_mfma_f32_16x16x32_bf16 v[126:129], v[130:133], v[182:185], v[126:129]
	v_mfma_f32_16x16x32_bf16 v[126:129], v[134:137], v[186:189], v[126:129]
	v_mfma_f32_16x16x32_bf16 v[122:125], v[138:141], v[182:185], v[122:125]
	v_mfma_f32_16x16x32_bf16 v[122:125], v[142:145], v[186:189], v[122:125]
	v_mfma_f32_16x16x32_bf16 v[118:121], v[146:149], v[182:185], v[118:121]
	v_mfma_f32_16x16x32_bf16 v[118:121], v[150:153], v[186:189], v[118:121]
	v_mfma_f32_16x16x32_bf16 v[110:113], v[154:157], v[182:185], v[110:113]
	v_mfma_f32_16x16x32_bf16 v[110:113], v[158:161], v[186:189], v[110:113]
	v_mfma_f32_16x16x32_bf16 v[94:97], v[154:157], v[190:193], v[94:97]
	v_mfma_f32_16x16x32_bf16 v[94:97], v[158:161], v[202:205], v[94:97]
	v_mfma_f32_16x16x32_bf16 v[102:105], v[146:149], v[190:193], v[102:105]
	v_mfma_f32_16x16x32_bf16 v[102:105], v[150:153], v[202:205], v[102:105]
	v_mfma_f32_16x16x32_bf16 v[106:109], v[138:141], v[190:193], v[106:109]
	v_mfma_f32_16x16x32_bf16 v[106:109], v[142:145], v[202:205], v[106:109]
	v_mfma_f32_16x16x32_bf16 v[114:117], v[130:133], v[190:193], v[114:117]
	v_mfma_f32_16x16x32_bf16 v[114:117], v[134:137], v[202:205], v[114:117]
	v_mfma_f32_16x16x32_bf16 v[98:101], v[130:133], v[206:209], v[98:101]
	v_mfma_f32_16x16x32_bf16 v[98:101], v[134:137], v[210:213], v[98:101]
	v_mfma_f32_16x16x32_bf16 v[90:93], v[138:141], v[206:209], v[90:93]
	v_mfma_f32_16x16x32_bf16 v[90:93], v[142:145], v[210:213], v[90:93]
	v_mfma_f32_16x16x32_bf16 v[86:89], v[146:149], v[206:209], v[86:89]
	v_mfma_f32_16x16x32_bf16 v[86:89], v[150:153], v[210:213], v[86:89]
	v_mfma_f32_16x16x32_bf16 v[78:81], v[154:157], v[206:209], v[78:81]
	v_mfma_f32_16x16x32_bf16 v[78:81], v[158:161], v[210:213], v[78:81]
	v_mfma_f32_16x16x32_bf16 v[66:69], v[154:157], v[214:217], v[66:69]
	v_mfma_f32_16x16x32_bf16 v[66:69], v[158:161], v[240:243], v[66:69]
	v_mfma_f32_16x16x32_bf16 v[70:73], v[146:149], v[214:217], v[70:73]
	v_mfma_f32_16x16x32_bf16 v[70:73], v[150:153], v[240:243], v[70:73]
	v_mfma_f32_16x16x32_bf16 v[74:77], v[138:141], v[214:217], v[74:77]
	v_mfma_f32_16x16x32_bf16 v[74:77], v[142:145], v[240:243], v[74:77]
	v_mfma_f32_16x16x32_bf16 v[82:85], v[130:133], v[214:217], v[82:85]
	v_mfma_f32_16x16x32_bf16 v[82:85], v[134:137], v[240:243], v[82:85]
	s_barrier
	ds_read_b128 v[182:185], v180 offset:49152
	ds_read_b128 v[186:189], v180 offset:50176
	ds_read_b128 v[190:193], v180 offset:51200
	ds_read_b128 v[202:205], v180 offset:52224
	ds_read_b128 v[206:209], v180 offset:53248
	ds_read_b128 v[210:213], v180 offset:54272
	ds_read_b128 v[214:217], v180 offset:55296
	ds_read_b128 v[240:243], v180 offset:56320
	s_add_u32 s58, s58, 0x80
	s_addc_u32 s59, s59, 0
	s_mov_b32 m0, s89
	s_nop 0
	global_load_lds_dwordx4 v167, s[58:59]
	s_add_u32 s44, s44, 0x80
	s_mov_b32 m0, s95
	s_nop 0
	global_load_lds_dwordx4 v175, s[58:59]
	s_addc_u32 s45, s45, 0
	s_mov_b32 m0, s26
	s_nop 0
	global_load_lds_dwordx4 v167, s[44:45]
	s_nop 0
	s_mov_b32 m0, s27
	s_nop 0
	global_load_lds_dwordx4 v175, s[44:45]
	s_nop 0
	s_mov_b32 m0, s36
	s_nop 0
	global_load_lds_dwordx4 v165, s[56:57]
	s_nop 0
	s_mov_b32 m0, s37
	s_nop 0
	global_load_lds_dwordx4 v171, s[56:57]
	s_waitcnt vmcnt(8)
	s_waitcnt lgkmcnt(0)
	s_barrier
	s_waitcnt lgkmcnt(0)
	v_mfma_f32_16x16x32_bf16 v[62:65], v[130:133], v[182:185], v[62:65]
	v_mfma_f32_16x16x32_bf16 v[62:65], v[134:137], v[186:189], v[62:65]
	v_mfma_f32_16x16x32_bf16 v[58:61], v[138:141], v[182:185], v[58:61]
	v_mfma_f32_16x16x32_bf16 v[58:61], v[142:145], v[186:189], v[58:61]
	v_mfma_f32_16x16x32_bf16 v[54:57], v[146:149], v[182:185], v[54:57]
	v_mfma_f32_16x16x32_bf16 v[54:57], v[150:153], v[186:189], v[54:57]
	v_mfma_f32_16x16x32_bf16 v[50:53], v[154:157], v[182:185], v[50:53]
	v_mfma_f32_16x16x32_bf16 v[50:53], v[158:161], v[186:189], v[50:53]
	v_mfma_f32_16x16x32_bf16 v[30:33], v[154:157], v[190:193], v[30:33]
	v_mfma_f32_16x16x32_bf16 v[30:33], v[158:161], v[202:205], v[30:33]
	v_mfma_f32_16x16x32_bf16 v[38:41], v[146:149], v[190:193], v[38:41]
	v_mfma_f32_16x16x32_bf16 v[38:41], v[150:153], v[202:205], v[38:41]
	v_mfma_f32_16x16x32_bf16 v[42:45], v[138:141], v[190:193], v[42:45]
	v_mfma_f32_16x16x32_bf16 v[42:45], v[142:145], v[202:205], v[42:45]
	v_mfma_f32_16x16x32_bf16 v[46:49], v[130:133], v[190:193], v[46:49]
	v_mfma_f32_16x16x32_bf16 v[46:49], v[134:137], v[202:205], v[46:49]
	v_mfma_f32_16x16x32_bf16 v[34:37], v[130:133], v[206:209], v[34:37]
	v_mfma_f32_16x16x32_bf16 v[34:37], v[134:137], v[210:213], v[34:37]
	v_mfma_f32_16x16x32_bf16 v[26:29], v[138:141], v[206:209], v[26:29]
	v_mfma_f32_16x16x32_bf16 v[26:29], v[142:145], v[210:213], v[26:29]
	v_mfma_f32_16x16x32_bf16 v[22:25], v[146:149], v[206:209], v[22:25]
	v_mfma_f32_16x16x32_bf16 v[22:25], v[150:153], v[210:213], v[22:25]
	v_mfma_f32_16x16x32_bf16 v[14:17], v[154:157], v[206:209], v[14:17]
	v_mfma_f32_16x16x32_bf16 v[14:17], v[158:161], v[210:213], v[14:17]
	v_mfma_f32_16x16x32_bf16 v[2:5], v[154:157], v[214:217], v[2:5]
	v_mfma_f32_16x16x32_bf16 v[2:5], v[158:161], v[240:243], v[2:5]
	v_mfma_f32_16x16x32_bf16 v[6:9], v[146:149], v[214:217], v[6:9]
	v_mfma_f32_16x16x32_bf16 v[6:9], v[150:153], v[240:243], v[6:9]
	v_mfma_f32_16x16x32_bf16 v[10:13], v[138:141], v[214:217], v[10:13]
	v_mfma_f32_16x16x32_bf16 v[10:13], v[142:145], v[240:243], v[10:13]
	v_mfma_f32_16x16x32_bf16 v[18:21], v[130:133], v[214:217], v[18:21]
	v_mfma_f32_16x16x32_bf16 v[18:21], v[134:137], v[240:243], v[18:21]
	s_barrier
	s_add_u32 s4, s4, 0x100
	s_addc_u32 s5, s5, 0
	s_add_u32 s0, s0, 0x100
	s_addc_u32 s1, s1, 0
	s_cmp_ge_u32 s55, s31
	s_mov_b32 s44, s55
	s_cbranch_scc0 .LBB0_271
	v_readlane_b32 s0, v254, 44
	v_readlane_b32 s1, v254, 45
	s_and_b64 vcc, exec, s[0:1]
	s_cbranch_vccz .LBB0_274
	s_barrier

; #define PG8_WAIT_V(n) asm volatile("s_waitcnt vmcnt(" #n ")" ::: "memory")
; #define PG8_BAR __builtin_amdgcn_s_barrier()
; template <class Epi, bool ALIGN_EPI>
; __device__ __forceinline__ void gemm_phase(LAS unsigned char* lds, const Gemm g, const StaticOrder& S, const Epi& E) {
;     ...
;     PG8_WAIT_V(0);
;     if constexpr (!ALIGN_EPI) { if (wr == 0) PG8_BAR; }
;     PG8_BAR;
.LBB0_289:
	s_setprio 0
	s_waitcnt vmcnt(0)
	v_readlane_b32 s75, v254, 58
	v_readlane_b32 s53, v254, 43
	v_readlane_b32 s65, v254, 42
	v_readlane_b32 s67, v254, 41
	v_readlane_b32 s80, v254, 40
	v_readlane_b32 s85, v254, 39
	s_barrier

; #define PG8_WAIT_V(n) asm volatile("s_waitcnt vmcnt(" #n ")" ::: "memory")
; #define PG8_BAR __builtin_amdgcn_s_barrier()
; template <class Epi, bool ALIGN_EPI>
; __device__ __forceinline__ void gemm_phase(LAS unsigned char* lds, const Gemm g, const StaticOrder& S, const Epi& E) {
;     int tid = threadIdx.x; asm volatile("" : "+v"(tid));
;     const int wid = __builtin_amdgcn_readfirstlane(tid >> 6), lane = tid & 63, wr = wid >> 2, wc = wid & 3, fr = lane & 15, fq = lane >> 4;
;     const int K = g.K, nt = K / BK, lda = g.lda;
;     unsigned voffA[2], voffB[2];
; #pragma unroll
;     for (int i = 0; i < 2; ++i) { int R, C; stage_rc(tid * 16 + i * 8192, R, C); const int Rb = (R & ~31) + perm32(R & 31);
;         voffA[i] = (unsigned)(R * lda + C) * 2u; voffB[i] = (unsigned)(Rb * K + C) * 2u; }
;     const size_t kstep = (size_t)(BK * 2);
;     const size_t hstepA = (size_t)HALF * lda * 2, hstepB = (size_t)HALF * K * 2;
;     const size_t tstepA = 2 * hstepA, tstepB = 2 * hstepB;
;     const unsigned ldsw = (unsigned)wid * 1024u;
;     const unsigned ldsb = (unsigned)(unsigned long)lds + ldsw;
;     const int aoff = lds_byte(wr * 64 + fr, fq * 8), boff = lds_byte(wc * 32 + fr, fq * 8);
;     ...
;     Unit cur, nxt; int ui = 0;
;     if (!S.next(0, cur)) return;
;     f32x4 acc[2][2][4][2];
; #pragma unroll
;     for (int a = 0; a < 2; ++a)
; #pragma unroll
;         for (int b = 0; b < 2; ++b)
; #pragma unroll
;             for (int m = 0; m < 4; ++m)
; #pragma unroll
;                 for (int n = 0; n < 2; ++n) acc[a][b][m][n] = (f32x4){0.f, 0.f, 0.f, 0.f};
;     bf16x8 At[4][2], B0[2][2], B1[2][2];
;     const char* cA = (const char*)g.A + (size_t)cur.pm * tstepA + (size_t)cur.pn * g.a_pn_off * 2 + (size_t)(cur.pm >> 4) * g.a_adj; const char* cB = (const char*)g.Bt + (size_t)cur.pn * tstepB;
;     PG8_STAGE(PG8_SB(0, 0), cB, voffB); PG8_STAGE(PG8_SB(0, 1), cB + hstepB, voffB); PG8_STAGE(PG8_SA(0, 0), cA, voffA); PG8_STAGE(PG8_SA(0, 1), cA + hstepA, voffA);
;     if (wr == 1) PG8_BAR;
;     PG8_WAIT_V(2); PG8_BAR;
;     PG8_STAGE(PG8_SB(1, 0), cB + kstep, voffB); PG8_STAGE(PG8_SA(1, 0), cA + kstep, voffA); PG8_STAGE(PG8_SB(1, 1), cB + hstepB + kstep, voffB);
.LBB0_297:
	s_andn2_b64 vcc, exec, s[26:27]
	s_cbranch_vccnz .LBB0_328
	s_mov_b32 s98, -1
	v_writelane_b32 v254, s85, 39
	v_writelane_b32 v254, s80, 40
	v_bfe_i32 v4, v2, 27, 1
	v_writelane_b32 v254, s67, 41
	v_lshlrev_b32_e32 v3, 4, v2
	v_lshrrev_b32_e32 v4, 22, v4
	v_writelane_b32 v254, s65, 42
	v_add_u32_e32 v4, v3, v4
	v_writelane_b32 v254, s53, 43
	v_and_b32_e32 v4, 0xfffffc00, v4
	v_writelane_b32 v254, s94, 31
	v_sub_u32_e32 v4, v3, v4
	v_ashrrev_i32_e32 v0, 31, v2
	v_writelane_b32 v254, s95, 32
	s_waitcnt lgkmcnt(0)
	v_lshrrev_b32_e32 v5, 4, v4
	v_writelane_b32 v254, s60, 33
	v_lshrrev_b32_e32 v0, 26, v0
	v_bitop3_b32 v4, v5, v4, 32 bitop3:0x6c
	v_writelane_b32 v254, s61, 34
	v_add_u32_e32 v0, v2, v0
	v_ashrrev_i32_e32 v6, 31, v4
	v_writelane_b32 v254, s58, 35
	v_ashrrev_i32_e32 v0, 6, v0
	v_lshrrev_b32_e32 v6, 26, v6
	v_writelane_b32 v254, s59, 36
	v_lshlrev_b32_e32 v5, 3, v0
	v_add_u32_e32 v6, v4, v6
	s_lshl_b64 s[8:9], s[8:9], 1
	v_readlane_b32 s1, v254, 29
	v_and_b32_e32 v5, -16, v5
	v_ashrrev_i32_e32 v7, 6, v6
	v_and_b32_e32 v6, 0xc0, v6
	s_add_u32 s1, s1, s8
	v_readlane_b32 s8, v254, 30
	v_add_u32_e32 v5, v7, v5
	v_sub_u32_e32 v4, v4, v6
	s_addc_u32 s14, s8, s9
	v_lshlrev_b32_e32 v0, 5, v0
	v_ashrrev_i16_sdwa v4, v223, sext(v4) dst_sel:DWORD dst_unused:UNUSED_PAD src0_sel:DWORD src1_sel:BYTE_0
	v_lshlrev_b32_e32 v6, 1, v5
	v_lshrrev_b32_e32 v8, 2, v5
	v_and_b32_e32 v7, 3, v7
	s_mov_b32 s9, 0x1fffe0
	v_and_b32_e32 v0, 32, v0
	v_bfe_i32 v4, v4, 0, 16
	v_and_b32_e32 v6, 24, v6
	v_and_b32_e32 v8, 4, v8
	v_and_or_b32 v7, v5, s9, v7
	v_or3_b32 v6, v7, v8, v6
	v_add_lshl_u32 v4, v0, v4, 1
	v_add_u32_e32 v3, 0x2000, v3
	v_lshl_add_u32 v0, v5, 11, v4
	v_lshl_add_u32 v180, v6, 11, v4
	v_ashrrev_i32_e32 v4, 31, v3
	v_lshrrev_b32_e32 v4, 22, v4
	v_add_u32_e32 v4, v3, v4
	v_ashrrev_i32_e32 v4, 10, v4
	v_mul_i32_i24_e32 v5, 0x400, v4
	v_sub_u32_e32 v3, v3, v5
	v_lshrrev_b32_e32 v5, 4, v3
	v_bitop3_b32 v3, v5, v3, 32 bitop3:0x6c
	v_ashrrev_i32_e32 v6, 31, v3
	v_lshrrev_b32_e32 v6, 26, v6
	v_lshlrev_b32_e32 v5, 3, v4
	v_add_u32_e32 v6, v3, v6
	v_and_b32_e32 v5, -16, v5
	v_ashrrev_i32_e32 v7, 6, v6
	v_add_u32_e32 v5, v7, v5
	v_and_b32_e32 v7, 3, v7
	v_and_or_b32 v7, v5, s9, v7
	s_ashr_i32 s9, s5, 6
	v_and_b32_e32 v6, 0xc0, v6
	s_lshl_b32 s15, s9, 10
	s_ashr_i32 s55, s54, 31
	s_ashr_i32 s49, s48, 31
	s_ashr_i32 s8, s5, 8
	v_sub_u32_e32 v3, v3, v6
	s_add_i32 s15, s15, 0
	s_lshl_b64 s[26:27], s[54:55], 19
	s_lshl_b64 s[30:31], s[48:49], 19
	v_lshlrev_b32_e32 v4, 5, v4
	v_ashrrev_i16_sdwa v3, v223, sext(v3) dst_sel:DWORD dst_unused:UNUSED_PAD src0_sel:DWORD src1_sel:BYTE_0
	v_lshlrev_b32_e32 v6, 1, v5
	v_lshrrev_b32_e32 v8, 2, v5
	s_add_u32 s56, s1, s30
	v_and_b32_e32 v4, 32, v4
	v_bfe_i32 v3, v3, 0, 16
	v_and_b32_e32 v6, 24, v6
	v_and_b32_e32 v8, 4, v8
	s_addc_u32 s57, s14, s31
	s_add_i32 s29, s15, 0x10000
	s_add_i32 s42, s15, 0x12000
	s_add_i32 s43, s15, 0x14000
	v_or3_b32 v6, v7, v8, v6
	v_add_lshl_u32 v3, v4, v3, 1
	s_mov_b32 m0, s29
	s_nop 0
	global_load_lds_dwordx4 v180, s[56:57]
	s_add_u32 s30, s56, 0x40000
	v_lshl_add_u32 v182, v6, 11, v3
	s_mov_b32 m0, s42
	s_nop 0
	global_load_lds_dwordx4 v182, s[56:57]
	s_addc_u32 s31, s57, 0
	s_add_i32 s44, s15, 0x16000
	s_mov_b32 m0, s43
	s_nop 0
	global_load_lds_dwordx4 v180, s[30:31]
	s_add_u32 s58, s18, s26
	s_mov_b32 m0, s44
	s_nop 0
	global_load_lds_dwordx4 v182, s[30:31]
	s_addc_u32 s59, s19, s27
	s_add_i32 s45, s15, 0x2000
	s_add_i32 s55, s15, 0x4000
	s_mov_b32 m0, s15
	s_nop 0
	global_load_lds_dwordx4 v0, s[58:59]
	s_add_u32 s26, s58, 0x40000
	v_lshl_add_u32 v181, v5, 11, v3
	s_mov_b32 m0, s45
	s_nop 0
	global_load_lds_dwordx4 v181, s[58:59]
	s_addc_u32 s27, s59, 0
	s_add_i32 s88, s15, 0x6000
	s_mov_b32 m0, s55
	s_nop 0
	global_load_lds_dwordx4 v0, s[26:27]
	s_cmp_eq_u32 s8, 1
	s_mov_b32 m0, s88
	s_nop 0
	global_load_lds_dwordx4 v181, s[26:27]
	s_cselect_b64 s[26:27], -1, 0
	v_writelane_b32 v254, s26, 44
	s_mov_b32 s80, s68
	s_cmp_lg_u32 s8, 1
	v_writelane_b32 v254, s27, 45
	s_cbranch_scc1 .LBB0_300
	s_barrier
	s_setprio 1

; #define PG8_STAGE(bufoff, gbase, voff) do { _Pragma("unroll") for (int _i = 0; _i < 2; ++_i) { \
;         const unsigned _m0 = ldsb + (unsigned)((bufoff) + _i * 8192); const char* _gb = (const char*)(gbase); \
;         asm volatile("s_mov_b32 m0, %0\n\ts_nop 0\n\tglobal_load_lds_dwordx4 %1, %2" :: "s"(_m0), "v"((voff)[_i]), "s"(_gb) : "m0", "memory"); } } while (0)
; #define PG8_LDA(dst, b, h) do { _Pragma("unroll") for (int m = 0; m < 4; ++m) _Pragma("unroll") for (int k = 0; k < 2; ++k) dst[m][k] = *(const LAS bf16x8*)(lds + PG8_SA(b, h) + aoff + m * 2048 + k * 1024); } while (0)
; #define PG8_LDB(dst, b, h) do { _Pragma("unroll") for (int n = 0; n < 2; ++n) _Pragma("unroll") for (int k = 0; k < 2; ++k) dst[n][k] = *(const LAS bf16x8*)(lds + PG8_SB(b, h) + boff + n * 2048 + k * 1024); } while (0)
; #define PG8_WAIT_V(n) asm volatile("s_waitcnt vmcnt(" #n ")" ::: "memory")
; #define PG8_WAIT_L(n) asm volatile("s_waitcnt lgkmcnt(" #n ")" ::: "memory")
; #define PG8_BAR __builtin_amdgcn_s_barrier()
; #define PG8_SCHED __builtin_amdgcn_sched_barrier(0)
; template <class Epi, bool ALIGN_EPI>
; __device__ __forceinline__ void gemm_phase(LAS unsigned char* lds, const Gemm g, const StaticOrder& S, const Epi& E) {
;     ...
;         const bool has_next = S.next(ui + 1, nxt);
;         const char* nA = has_next ? (const char*)g.A + (size_t)nxt.pm * tstepA + (size_t)nxt.pn * g.a_pn_off * 2 + (size_t)(nxt.pm >> 4) * g.a_adj : cA; const char* nB = has_next ? (const char*)g.Bt + (size_t)nxt.pn * tstepB : cB;
;         for (int t = 0; t < nt; t += 2) {
;             const bool last = (t == nt - 2);
;             const char* a1 = cA + (size_t)(t + 1) * kstep;
;             const char* a2 = last ? nA : cA + (size_t)(t + 2) * kstep; const char* b2 = last ? nB : cB + (size_t)(t + 2) * kstep;
;             const char* a3 = a2 + kstep; const char* b3 = b2 + kstep;
;             PG8_LDB(B0, 0, 0); PG8_LDB(B1, 0, 1); PG8_SCHED; PG8_LDA(At, 0, 0); PG8_STAGE(PG8_SA(1, 1), a1 + hstepA, voffA);
;             PG8_WAIT_V(8); PG8_WAIT_L(0); PG8_BAR; PG8_MMA(0, 0, At, B0); PG8_MMA(0, 1, At, B1); PG8_BAR; PG8_SCHED;
;             PG8_LDA(At, 0, 1); PG8_STAGE(PG8_SB(0, 0), b2, voffB); PG8_STAGE(PG8_SB(0, 1), b2 + hstepB, voffB); PG8_STAGE(PG8_SA(0, 0), a2, voffA);
;             PG8_WAIT_V(8); PG8_WAIT_L(0); PG8_BAR; PG8_MMA(1, 0, At, B0); PG8_MMA(1, 1, At, B1); PG8_BAR; PG8_SCHED;
.LBB0_305:
	s_ashr_i32 s37, s36, 31
	s_lshl_b64 s[4:5], s[36:37], 19
	s_add_u32 s38, s18, s4
	s_addc_u32 s39, s19, s5
	s_and_b64 s[4:5], s[8:9], exec
	s_cselect_b32 s4, s39, s59
	s_cselect_b32 s5, s38, s58
	s_ashr_i32 s35, s34, 31
	s_lshl_b64 s[50:51], s[34:35], 19
	s_add_u32 s90, s1, s50
	s_addc_u32 s91, s14, s51
	s_and_b64 s[50:51], s[8:9], exec
	s_cselect_b32 s35, s91, s57
	s_cselect_b32 s37, s90, s56
	s_add_u32 s41, s56, 0x100
	s_addc_u32 s49, s57, 0
	s_add_u32 s92, s58, 0x40080
	s_addc_u32 s93, s59, 0
	s_mov_b32 s50, -2
	s_add_u32 s30, s92, 0xfffc0080
	s_addc_u32 s31, s93, -1
	s_cmp_eq_u32 s50, 12
	s_cselect_b32 s60, s5, s30
	s_cselect_b32 s61, s4, s31
	s_cselect_b32 s58, s37, s41
	s_cselect_b32 s59, s35, s49
	s_add_u32 s56, s60, 0x80
	s_addc_u32 s57, s61, 0
	s_mov_b32 m0, s67
	s_nop 0
	global_load_lds_dwordx4 v0, s[92:93]
	s_nop 0
	s_mov_b32 m0, s65
	s_nop 0
	global_load_lds_dwordx4 v181, s[92:93]
	s_waitcnt vmcnt(8)
	s_waitcnt lgkmcnt(0)
	s_barrier
	s_waitcnt lgkmcnt(0)
	v_mfma_f32_16x16x32_bf16 v[142:145], v[74:77], v[162:165], 0
	v_mfma_f32_16x16x32_bf16 v[142:145], v[94:97], v[166:169], v[142:145]
	v_mfma_f32_16x16x32_bf16 v[138:141], v[114:117], v[162:165], 0
	v_mfma_f32_16x16x32_bf16 v[138:141], v[134:137], v[166:169], v[138:141]
	v_mfma_f32_16x16x32_bf16 v[130:133], v[146:149], v[162:165], 0
	v_mfma_f32_16x16x32_bf16 v[130:133], v[150:153], v[166:169], v[130:133]
	v_mfma_f32_16x16x32_bf16 v[126:129], v[154:157], v[162:165], 0
	v_mfma_f32_16x16x32_bf16 v[126:129], v[158:161], v[166:169], v[126:129]
	v_mfma_f32_16x16x32_bf16 v[106:109], v[154:157], v[170:173], 0
	v_mfma_f32_16x16x32_bf16 v[106:109], v[158:161], v[174:177], v[106:109]
	v_mfma_f32_16x16x32_bf16 v[110:113], v[146:149], v[170:173], 0
	v_mfma_f32_16x16x32_bf16 v[110:113], v[150:153], v[174:177], v[110:113]
	v_mfma_f32_16x16x32_bf16 v[118:121], v[114:117], v[170:173], 0
	v_mfma_f32_16x16x32_bf16 v[118:121], v[134:137], v[174:177], v[118:121]
	v_mfma_f32_16x16x32_bf16 v[122:125], v[74:77], v[170:173], 0
	v_mfma_f32_16x16x32_bf16 v[122:125], v[94:97], v[174:177], v[122:125]
	v_mfma_f32_16x16x32_bf16 v[102:105], v[74:77], v[188:191], 0
	v_mfma_f32_16x16x32_bf16 v[102:105], v[94:97], v[202:205], v[102:105]
	v_mfma_f32_16x16x32_bf16 v[98:101], v[114:117], v[188:191], 0
	v_mfma_f32_16x16x32_bf16 v[98:101], v[134:137], v[202:205], v[98:101]
	v_mfma_f32_16x16x32_bf16 v[90:93], v[146:149], v[188:191], 0
	v_mfma_f32_16x16x32_bf16 v[90:93], v[150:153], v[202:205], v[90:93]
	v_mfma_f32_16x16x32_bf16 v[86:89], v[154:157], v[188:191], 0
	v_mfma_f32_16x16x32_bf16 v[86:89], v[158:161], v[202:205], v[86:89]
	v_mfma_f32_16x16x32_bf16 v[66:69], v[154:157], v[206:209], 0
	v_mfma_f32_16x16x32_bf16 v[66:69], v[158:161], v[210:213], v[66:69]
	v_mfma_f32_16x16x32_bf16 v[70:73], v[146:149], v[206:209], 0
	v_mfma_f32_16x16x32_bf16 v[70:73], v[150:153], v[210:213], v[70:73]
	v_mfma_f32_16x16x32_bf16 v[78:81], v[114:117], v[206:209], 0
	v_mfma_f32_16x16x32_bf16 v[78:81], v[134:137], v[210:213], v[78:81]
	v_mfma_f32_16x16x32_bf16 v[82:85], v[74:77], v[206:209], 0
	v_mfma_f32_16x16x32_bf16 v[82:85], v[94:97], v[210:213], v[82:85]
	s_barrier
	ds_read_b128 v[162:165], v186 offset:16384
	ds_read_b128 v[166:169], v186 offset:17408
	ds_read_b128 v[170:173], v186 offset:18432
	ds_read_b128 v[174:177], v186 offset:19456
	ds_read_b128 v[188:191], v186 offset:20480
	ds_read_b128 v[202:205], v186 offset:21504
	ds_read_b128 v[206:209], v186 offset:22528
	ds_read_b128 v[210:213], v186 offset:23552
	s_mov_b32 m0, s29
	s_nop 0
	global_load_lds_dwordx4 v180, s[58:59]
	s_add_u32 s30, s58, 0x40000
	s_mov_b32 m0, s42
	s_nop 0
	global_load_lds_dwordx4 v182, s[58:59]
	s_addc_u32 s31, s59, 0
	s_mov_b32 m0, s43
	s_nop 0
	global_load_lds_dwordx4 v180, s[30:31]
	s_nop 0
	s_mov_b32 m0, s44
	s_nop 0
	global_load_lds_dwordx4 v182, s[30:31]
	s_nop 0
	s_mov_b32 m0, s15
	s_nop 0
	global_load_lds_dwordx4 v0, s[60:61]
	s_nop 0
	s_mov_b32 m0, s45
	s_nop 0
	global_load_lds_dwordx4 v181, s[60:61]
	s_waitcnt vmcnt(8)
	s_waitcnt lgkmcnt(0)
	s_barrier
	s_waitcnt lgkmcnt(0)
	v_mfma_f32_16x16x32_bf16 v[62:65], v[74:77], v[162:165], 0
	v_mfma_f32_16x16x32_bf16 v[62:65], v[94:97], v[166:169], v[62:65]
	v_mfma_f32_16x16x32_bf16 v[58:61], v[114:117], v[162:165], 0
	v_mfma_f32_16x16x32_bf16 v[58:61], v[134:137], v[166:169], v[58:61]
	v_mfma_f32_16x16x32_bf16 v[54:57], v[146:149], v[162:165], 0
	v_mfma_f32_16x16x32_bf16 v[54:57], v[150:153], v[166:169], v[54:57]
	v_mfma_f32_16x16x32_bf16 v[50:53], v[154:157], v[162:165], 0
	v_mfma_f32_16x16x32_bf16 v[50:53], v[158:161], v[166:169], v[50:53]
	v_mfma_f32_16x16x32_bf16 v[34:37], v[154:157], v[170:173], 0
	v_mfma_f32_16x16x32_bf16 v[34:37], v[158:161], v[174:177], v[34:37]
	v_mfma_f32_16x16x32_bf16 v[38:41], v[146:149], v[170:173], 0
	v_mfma_f32_16x16x32_bf16 v[38:41], v[150:153], v[174:177], v[38:41]
	v_mfma_f32_16x16x32_bf16 v[42:45], v[114:117], v[170:173], 0
	v_mfma_f32_16x16x32_bf16 v[42:45], v[134:137], v[174:177], v[42:45]
	v_mfma_f32_16x16x32_bf16 v[46:49], v[74:77], v[170:173], 0
	v_mfma_f32_16x16x32_bf16 v[46:49], v[94:97], v[174:177], v[46:49]
	v_mfma_f32_16x16x32_bf16 v[30:33], v[74:77], v[188:191], 0
	v_mfma_f32_16x16x32_bf16 v[30:33], v[94:97], v[202:205], v[30:33]
	v_mfma_f32_16x16x32_bf16 v[26:29], v[114:117], v[188:191], 0
	v_mfma_f32_16x16x32_bf16 v[26:29], v[134:137], v[202:205], v[26:29]
	v_mfma_f32_16x16x32_bf16 v[22:25], v[146:149], v[188:191], 0
	v_mfma_f32_16x16x32_bf16 v[22:25], v[150:153], v[202:205], v[22:25]
	v_mfma_f32_16x16x32_bf16 v[18:21], v[154:157], v[188:191], 0
	v_mfma_f32_16x16x32_bf16 v[18:21], v[158:161], v[202:205], v[18:21]
	v_mfma_f32_16x16x32_bf16 v[2:5], v[154:157], v[206:209], 0
	v_mfma_f32_16x16x32_bf16 v[2:5], v[158:161], v[210:213], v[2:5]
	v_mfma_f32_16x16x32_bf16 v[6:9], v[146:149], v[206:209], 0
	v_mfma_f32_16x16x32_bf16 v[6:9], v[150:153], v[210:213], v[6:9]
	v_mfma_f32_16x16x32_bf16 v[10:13], v[114:117], v[206:209], 0
	v_mfma_f32_16x16x32_bf16 v[10:13], v[134:137], v[210:213], v[10:13]
	v_mfma_f32_16x16x32_bf16 v[14:17], v[74:77], v[206:209], 0
	v_mfma_f32_16x16x32_bf16 v[14:17], v[94:97], v[210:213], v[14:17]
	s_barrier
; #define PG8_STAGE(bufoff, gbase, voff) do { _Pragma("unroll") for (int _i = 0; _i < 2; ++_i) { \
;         const unsigned _m0 = ldsb + (unsigned)((bufoff) + _i * 8192); const char* _gb = (const char*)(gbase); \
;         asm volatile("s_mov_b32 m0, %0\n\ts_nop 0\n\tglobal_load_lds_dwordx4 %1, %2" :: "s"(_m0), "v"((voff)[_i]), "s"(_gb) : "m0", "memory"); } } while (0)
; #define PG8_LDA(dst, b, h) do { _Pragma("unroll") for (int m = 0; m < 4; ++m) _Pragma("unroll") for (int k = 0; k < 2; ++k) dst[m][k] = *(const LAS bf16x8*)(lds + PG8_SA(b, h) + aoff + m * 2048 + k * 1024); } while (0)
; #define PG8_LDB(dst, b, h) do { _Pragma("unroll") for (int n = 0; n < 2; ++n) _Pragma("unroll") for (int k = 0; k < 2; ++k) dst[n][k] = *(const LAS bf16x8*)(lds + PG8_SB(b, h) + boff + n * 2048 + k * 1024); } while (0)
; #define PG8_MMA(ai, bj, At, Bt) do { __builtin_amdgcn_s_setprio(1); _Pragma("unroll") for (int m = 0; m < 4; ++m) _Pragma("unroll") for (int n = 0; n < 2; ++n) _Pragma("unroll") for (int k = 0; k < 2; ++k) \
;         acc[ai][bj][m][n] = __builtin_amdgcn_mfma_f32_16x16x32_bf16(Bt[n][k], At[m][k], acc[ai][bj][m][n], 0, 0, 0); __builtin_amdgcn_s_setprio(0); } while (0)
; #define PG8_WAIT_V(n) asm volatile("s_waitcnt vmcnt(" #n ")" ::: "memory")
; #define PG8_WAIT_L(n) asm volatile("s_waitcnt lgkmcnt(" #n ")" ::: "memory")
; #define PG8_BAR __builtin_amdgcn_s_barrier()
; #define PG8_SCHED __builtin_amdgcn_sched_barrier(0)
; template <class Epi, bool ALIGN_EPI>
; __device__ __forceinline__ void gemm_phase(LAS unsigned char* lds, const Gemm g, const StaticOrder& S, const Epi& E) {
;     ...
;             PG8_LDB(B0, 1, 0); PG8_LDB(B1, 1, 1); PG8_SCHED; PG8_LDA(At, 1, 0); PG8_STAGE(PG8_SA(0, 1), a2 + hstepA, voffA);
;             PG8_WAIT_V(8); PG8_WAIT_L(0); PG8_BAR; PG8_MMA(0, 0, At, B0); PG8_MMA(0, 1, At, B1); PG8_BAR; PG8_SCHED;
;             PG8_LDA(At, 1, 1); PG8_STAGE(PG8_SB(1, 0), b3, voffB); PG8_STAGE(PG8_SB(1, 1), b3 + hstepB, voffB); PG8_STAGE(PG8_SA(1, 0), a3, voffA);
;             PG8_WAIT_V(8); PG8_WAIT_L(0); PG8_BAR; PG8_MMA(1, 0, At, B0); PG8_MMA(1, 1, At, B1); PG8_BAR; PG8_SCHED;
;         }
;         if constexpr (ALIGN_EPI) { if (wr == 0) PG8_BAR; }
	v_add_u32_e32 v134, 0x18000, v185
	v_add_u32_e32 v158, 0x1c000, v185
	ds_read_b128 v[74:77], v134
	ds_read_b128 v[94:97], v134 offset:1024
	ds_read_b128 v[114:117], v134 offset:2048
	ds_read_b128 v[134:137], v134 offset:3072
	ds_read_b128 v[146:149], v158
	ds_read_b128 v[150:153], v158 offset:1024
	ds_read_b128 v[154:157], v158 offset:2048
	ds_read_b128 v[158:161], v158 offset:3072
	ds_read_b128 v[162:165], v186 offset:32768
	ds_read_b128 v[166:169], v186 offset:33792
	ds_read_b128 v[170:173], v186 offset:34816
	ds_read_b128 v[174:177], v186 offset:35840
	ds_read_b128 v[188:191], v186 offset:36864
	ds_read_b128 v[202:205], v186 offset:37888
	ds_read_b128 v[206:209], v186 offset:38912
	ds_read_b128 v[210:213], v186 offset:39936
	s_add_u32 s30, s60, 0x40000
	s_addc_u32 s31, s61, 0
	s_mov_b32 m0, s55
	s_nop 0
	global_load_lds_dwordx4 v0, s[30:31]
	s_nop 0
	s_mov_b32 m0, s88
	s_nop 0
	global_load_lds_dwordx4 v181, s[30:31]
	s_waitcnt vmcnt(8)
	s_waitcnt lgkmcnt(0)
	s_barrier
	s_waitcnt lgkmcnt(0)
	v_mfma_f32_16x16x32_bf16 v[142:145], v[74:77], v[162:165], v[142:145]
	v_mfma_f32_16x16x32_bf16 v[142:145], v[94:97], v[166:169], v[142:145]
	v_mfma_f32_16x16x32_bf16 v[138:141], v[114:117], v[162:165], v[138:141]
	v_mfma_f32_16x16x32_bf16 v[138:141], v[134:137], v[166:169], v[138:141]
	v_mfma_f32_16x16x32_bf16 v[130:133], v[146:149], v[162:165], v[130:133]
	v_mfma_f32_16x16x32_bf16 v[130:133], v[150:153], v[166:169], v[130:133]
	v_mfma_f32_16x16x32_bf16 v[126:129], v[154:157], v[162:165], v[126:129]
	v_mfma_f32_16x16x32_bf16 v[126:129], v[158:161], v[166:169], v[126:129]
	v_mfma_f32_16x16x32_bf16 v[106:109], v[154:157], v[170:173], v[106:109]
	v_mfma_f32_16x16x32_bf16 v[106:109], v[158:161], v[174:177], v[106:109]
	v_mfma_f32_16x16x32_bf16 v[110:113], v[146:149], v[170:173], v[110:113]
	v_mfma_f32_16x16x32_bf16 v[110:113], v[150:153], v[174:177], v[110:113]
	v_mfma_f32_16x16x32_bf16 v[118:121], v[114:117], v[170:173], v[118:121]
	v_mfma_f32_16x16x32_bf16 v[118:121], v[134:137], v[174:177], v[118:121]
	v_mfma_f32_16x16x32_bf16 v[122:125], v[74:77], v[170:173], v[122:125]
	v_mfma_f32_16x16x32_bf16 v[122:125], v[94:97], v[174:177], v[122:125]
	v_mfma_f32_16x16x32_bf16 v[102:105], v[74:77], v[188:191], v[102:105]
	v_mfma_f32_16x16x32_bf16 v[102:105], v[94:97], v[202:205], v[102:105]
	v_mfma_f32_16x16x32_bf16 v[98:101], v[114:117], v[188:191], v[98:101]
	v_mfma_f32_16x16x32_bf16 v[98:101], v[134:137], v[202:205], v[98:101]
	v_mfma_f32_16x16x32_bf16 v[90:93], v[146:149], v[188:191], v[90:93]
	v_mfma_f32_16x16x32_bf16 v[90:93], v[150:153], v[202:205], v[90:93]
	v_mfma_f32_16x16x32_bf16 v[86:89], v[154:157], v[188:191], v[86:89]
	v_mfma_f32_16x16x32_bf16 v[86:89], v[158:161], v[202:205], v[86:89]
	v_mfma_f32_16x16x32_bf16 v[66:69], v[154:157], v[206:209], v[66:69]
	v_mfma_f32_16x16x32_bf16 v[66:69], v[158:161], v[210:213], v[66:69]
	v_mfma_f32_16x16x32_bf16 v[70:73], v[146:149], v[206:209], v[70:73]
	v_mfma_f32_16x16x32_bf16 v[70:73], v[150:153], v[210:213], v[70:73]
	v_mfma_f32_16x16x32_bf16 v[78:81], v[114:117], v[206:209], v[78:81]
	v_mfma_f32_16x16x32_bf16 v[78:81], v[134:137], v[210:213], v[78:81]
	v_mfma_f32_16x16x32_bf16 v[82:85], v[74:77], v[206:209], v[82:85]
	v_mfma_f32_16x16x32_bf16 v[82:85], v[94:97], v[210:213], v[82:85]
	s_barrier
	ds_read_b128 v[162:165], v186 offset:49152
	ds_read_b128 v[166:169], v186 offset:50176
	ds_read_b128 v[170:173], v186 offset:51200
	ds_read_b128 v[174:177], v186 offset:52224
	ds_read_b128 v[188:191], v186 offset:53248
	ds_read_b128 v[202:205], v186 offset:54272
	ds_read_b128 v[206:209], v186 offset:55296
	ds_read_b128 v[210:213], v186 offset:56320
	s_add_u32 s30, s58, 0x80
	s_addc_u32 s31, s59, 0
	s_mov_b32 m0, s94
	s_nop 0
	global_load_lds_dwordx4 v180, s[30:31]
	s_nop 0
	s_mov_b32 m0, s95
	s_nop 0
	global_load_lds_dwordx4 v182, s[30:31]
	s_add_u32 s30, s58, 0x40080
	s_addc_u32 s31, s59, 0
	s_mov_b32 m0, s17
	s_nop 0
	global_load_lds_dwordx4 v180, s[30:31]
	s_nop 0
	s_mov_b32 m0, s53
	s_nop 0
	global_load_lds_dwordx4 v182, s[30:31]
	s_nop 0
	s_mov_b32 m0, s96
	s_nop 0
	global_load_lds_dwordx4 v0, s[56:57]
	s_nop 0
	s_mov_b32 m0, s97
	s_nop 0
	global_load_lds_dwordx4 v181, s[56:57]
	s_waitcnt vmcnt(8)
	s_waitcnt lgkmcnt(0)
	s_barrier
	s_waitcnt lgkmcnt(0)
	v_mfma_f32_16x16x32_bf16 v[62:65], v[74:77], v[162:165], v[62:65]
	v_mfma_f32_16x16x32_bf16 v[62:65], v[94:97], v[166:169], v[62:65]
	v_mfma_f32_16x16x32_bf16 v[58:61], v[114:117], v[162:165], v[58:61]
	v_mfma_f32_16x16x32_bf16 v[58:61], v[134:137], v[166:169], v[58:61]
	v_mfma_f32_16x16x32_bf16 v[54:57], v[146:149], v[162:165], v[54:57]
	v_mfma_f32_16x16x32_bf16 v[54:57], v[150:153], v[166:169], v[54:57]
	v_mfma_f32_16x16x32_bf16 v[50:53], v[154:157], v[162:165], v[50:53]
	v_mfma_f32_16x16x32_bf16 v[50:53], v[158:161], v[166:169], v[50:53]
	v_mfma_f32_16x16x32_bf16 v[34:37], v[154:157], v[170:173], v[34:37]
	v_mfma_f32_16x16x32_bf16 v[34:37], v[158:161], v[174:177], v[34:37]
	v_mfma_f32_16x16x32_bf16 v[38:41], v[146:149], v[170:173], v[38:41]
	v_mfma_f32_16x16x32_bf16 v[38:41], v[150:153], v[174:177], v[38:41]
	v_mfma_f32_16x16x32_bf16 v[42:45], v[114:117], v[170:173], v[42:45]
	v_mfma_f32_16x16x32_bf16 v[42:45], v[134:137], v[174:177], v[42:45]
	v_mfma_f32_16x16x32_bf16 v[46:49], v[74:77], v[170:173], v[46:49]
	v_mfma_f32_16x16x32_bf16 v[46:49], v[94:97], v[174:177], v[46:49]
	v_mfma_f32_16x16x32_bf16 v[30:33], v[74:77], v[188:191], v[30:33]
	v_mfma_f32_16x16x32_bf16 v[30:33], v[94:97], v[202:205], v[30:33]
	v_mfma_f32_16x16x32_bf16 v[26:29], v[114:117], v[188:191], v[26:29]
	v_mfma_f32_16x16x32_bf16 v[26:29], v[134:137], v[202:205], v[26:29]
	v_mfma_f32_16x16x32_bf16 v[22:25], v[146:149], v[188:191], v[22:25]
	v_mfma_f32_16x16x32_bf16 v[22:25], v[150:153], v[202:205], v[22:25]
	v_mfma_f32_16x16x32_bf16 v[18:21], v[154:157], v[188:191], v[18:21]
	v_mfma_f32_16x16x32_bf16 v[18:21], v[158:161], v[202:205], v[18:21]
	v_mfma_f32_16x16x32_bf16 v[2:5], v[154:157], v[206:209], v[2:5]
	v_mfma_f32_16x16x32_bf16 v[2:5], v[158:161], v[210:213], v[2:5]
	v_mfma_f32_16x16x32_bf16 v[6:9], v[146:149], v[206:209], v[6:9]
	v_mfma_f32_16x16x32_bf16 v[6:9], v[150:153], v[210:213], v[6:9]
	v_mfma_f32_16x16x32_bf16 v[10:13], v[114:117], v[206:209], v[10:13]
	v_mfma_f32_16x16x32_bf16 v[10:13], v[134:137], v[210:213], v[10:13]
	v_mfma_f32_16x16x32_bf16 v[14:17], v[74:77], v[206:209], v[14:17]
	v_mfma_f32_16x16x32_bf16 v[14:17], v[94:97], v[210:213], v[14:17]
	s_barrier
	s_add_i32 s50, s50, 2
	s_add_u32 s41, s41, 0x100
	s_addc_u32 s49, s49, 0
	s_add_u32 s92, s92, 0x100
	s_addc_u32 s93, s93, 0
	s_cmp_gt_u32 s50, 13
; #define PG8_STAGE(bufoff, gbase, voff) do { _Pragma("unroll") for (int _i = 0; _i < 2; ++_i) { \
;         const unsigned _m0 = ldsb + (unsigned)((bufoff) + _i * 8192); const char* _gb = (const char*)(gbase); \
;         asm volatile("s_mov_b32 m0, %0\n\ts_nop 0\n\tglobal_load_lds_dwordx4 %1, %2" :: "s"(_m0), "v"((voff)[_i]), "s"(_gb) : "m0", "memory"); } } while (0)
; #define PG8_LDA(dst, b, h) do { _Pragma("unroll") for (int m = 0; m < 4; ++m) _Pragma("unroll") for (int k = 0; k < 2; ++k) dst[m][k] = *(const LAS bf16x8*)(lds + PG8_SA(b, h) + aoff + m * 2048 + k * 1024); } while (0)
; #define PG8_LDB(dst, b, h) do { _Pragma("unroll") for (int n = 0; n < 2; ++n) _Pragma("unroll") for (int k = 0; k < 2; ++k) dst[n][k] = *(const LAS bf16x8*)(lds + PG8_SB(b, h) + boff + n * 2048 + k * 1024); } while (0)
; #define PG8_MMA(ai, bj, At, Bt) do { __builtin_amdgcn_s_setprio(1); _Pragma("unroll") for (int m = 0; m < 4; ++m) _Pragma("unroll") for (int n = 0; n < 2; ++n) _Pragma("unroll") for (int k = 0; k < 2; ++k) \
;         acc[ai][bj][m][n] = __builtin_amdgcn_mfma_f32_16x16x32_bf16(Bt[n][k], At[m][k], acc[ai][bj][m][n], 0, 0, 0); __builtin_amdgcn_s_setprio(0); } while (0)
; #define PG8_WAIT_V(n) asm volatile("s_waitcnt vmcnt(" #n ")" ::: "memory")
; #define PG8_WAIT_L(n) asm volatile("s_waitcnt lgkmcnt(" #n ")" ::: "memory")
; template <class Epi, bool ALIGN_EPI>
; __device__ __forceinline__ void gemm_phase(LAS unsigned char* lds, const Gemm g, const StaticOrder& S, const Epi& E) {
;     ...
;         for (int t = 0; t < nt; t += 2) {
;             const bool last = (t == nt - 2);
;             const char* a1 = cA + (size_t)(t + 1) * kstep;
;             const char* a2 = last ? nA : cA + (size_t)(t + 2) * kstep; const char* b2 = last ? nB : cB + (size_t)(t + 2) * kstep;
;             const char* a3 = a2 + kstep; const char* b3 = b2 + kstep;
;             PG8_LDB(B0, 0, 0); PG8_LDB(B1, 0, 1); PG8_SCHED; PG8_LDA(At, 0, 0); PG8_STAGE(PG8_SA(1, 1), a1 + hstepA, voffA);
;             PG8_WAIT_V(8); PG8_WAIT_L(0); PG8_BAR; PG8_MMA(0, 0, At, B0); PG8_MMA(0, 1, At, B1); PG8_BAR; PG8_SCHED;
;             PG8_LDA(At, 0, 1); PG8_STAGE(PG8_SB(0, 0), b2, voffB); PG8_STAGE(PG8_SB(0, 1), b2 + hstepB, voffB); PG8_STAGE(PG8_SA(0, 0), a2, voffA);
;             PG8_WAIT_V(8); PG8_WAIT_L(0); PG8_BAR; PG8_MMA(1, 0, At, B0); PG8_MMA(1, 1, At, B1); PG8_BAR; PG8_SCHED;
.LBB0_306:
	v_add_u32_e32 v134, 0x10000, v185
	v_add_u32_e32 v158, 0x14000, v185
	ds_read_b128 v[74:77], v134
	ds_read_b128 v[94:97], v134 offset:1024
	ds_read_b128 v[114:117], v134 offset:2048
	ds_read_b128 v[134:137], v134 offset:3072
	ds_read_b128 v[146:149], v158
	ds_read_b128 v[150:153], v158 offset:1024
	ds_read_b128 v[154:157], v158 offset:2048
	ds_read_b128 v[158:161], v158 offset:3072
	s_add_u32 s30, s92, 0xfffc0080
	s_addc_u32 s31, s93, -1
	s_cmp_eq_u32 s50, 12
	s_cselect_b32 s60, s5, s30
	s_cselect_b32 s61, s4, s31
	s_cselect_b32 s58, s37, s41
	s_cselect_b32 s59, s35, s49
	s_add_u32 s56, s60, 0x80
	s_addc_u32 s57, s61, 0
	ds_read_b128 v[162:165], v186
	ds_read_b128 v[166:169], v186 offset:1024
	ds_read_b128 v[170:173], v186 offset:2048
	ds_read_b128 v[174:177], v186 offset:3072
	ds_read_b128 v[188:191], v186 offset:4096
	ds_read_b128 v[202:205], v186 offset:5120
	ds_read_b128 v[206:209], v186 offset:6144
	ds_read_b128 v[210:213], v186 offset:7168
	s_mov_b32 m0, s67
	s_nop 0
	global_load_lds_dwordx4 v0, s[92:93]
	s_nop 0
	s_mov_b32 m0, s65
	s_nop 0
	global_load_lds_dwordx4 v181, s[92:93]
	s_waitcnt vmcnt(8)
	s_waitcnt lgkmcnt(0)
	s_barrier
	s_waitcnt lgkmcnt(0)
	v_mfma_f32_16x16x32_bf16 v[142:145], v[74:77], v[162:165], v[142:145]
	v_mfma_f32_16x16x32_bf16 v[142:145], v[94:97], v[166:169], v[142:145]
	v_mfma_f32_16x16x32_bf16 v[138:141], v[114:117], v[162:165], v[138:141]
	v_mfma_f32_16x16x32_bf16 v[138:141], v[134:137], v[166:169], v[138:141]
	v_mfma_f32_16x16x32_bf16 v[130:133], v[146:149], v[162:165], v[130:133]
	v_mfma_f32_16x16x32_bf16 v[130:133], v[150:153], v[166:169], v[130:133]
	v_mfma_f32_16x16x32_bf16 v[126:129], v[154:157], v[162:165], v[126:129]
	v_mfma_f32_16x16x32_bf16 v[126:129], v[158:161], v[166:169], v[126:129]
	v_mfma_f32_16x16x32_bf16 v[106:109], v[154:157], v[170:173], v[106:109]
	v_mfma_f32_16x16x32_bf16 v[106:109], v[158:161], v[174:177], v[106:109]
	v_mfma_f32_16x16x32_bf16 v[110:113], v[146:149], v[170:173], v[110:113]
	v_mfma_f32_16x16x32_bf16 v[110:113], v[150:153], v[174:177], v[110:113]
	v_mfma_f32_16x16x32_bf16 v[118:121], v[114:117], v[170:173], v[118:121]
	v_mfma_f32_16x16x32_bf16 v[118:121], v[134:137], v[174:177], v[118:121]
	v_mfma_f32_16x16x32_bf16 v[122:125], v[74:77], v[170:173], v[122:125]
	v_mfma_f32_16x16x32_bf16 v[122:125], v[94:97], v[174:177], v[122:125]
	v_mfma_f32_16x16x32_bf16 v[102:105], v[74:77], v[188:191], v[102:105]
	v_mfma_f32_16x16x32_bf16 v[102:105], v[94:97], v[202:205], v[102:105]
	v_mfma_f32_16x16x32_bf16 v[98:101], v[114:117], v[188:191], v[98:101]
	v_mfma_f32_16x16x32_bf16 v[98:101], v[134:137], v[202:205], v[98:101]
	v_mfma_f32_16x16x32_bf16 v[90:93], v[146:149], v[188:191], v[90:93]
	v_mfma_f32_16x16x32_bf16 v[90:93], v[150:153], v[202:205], v[90:93]
	v_mfma_f32_16x16x32_bf16 v[86:89], v[154:157], v[188:191], v[86:89]
	v_mfma_f32_16x16x32_bf16 v[86:89], v[158:161], v[202:205], v[86:89]
	v_mfma_f32_16x16x32_bf16 v[66:69], v[154:157], v[206:209], v[66:69]
	v_mfma_f32_16x16x32_bf16 v[66:69], v[158:161], v[210:213], v[66:69]
	v_mfma_f32_16x16x32_bf16 v[70:73], v[146:149], v[206:209], v[70:73]
	v_mfma_f32_16x16x32_bf16 v[70:73], v[150:153], v[210:213], v[70:73]
	v_mfma_f32_16x16x32_bf16 v[78:81], v[114:117], v[206:209], v[78:81]
	v_mfma_f32_16x16x32_bf16 v[78:81], v[134:137], v[210:213], v[78:81]
	v_mfma_f32_16x16x32_bf16 v[82:85], v[74:77], v[206:209], v[82:85]
	v_mfma_f32_16x16x32_bf16 v[82:85], v[94:97], v[210:213], v[82:85]
	s_barrier
	ds_read_b128 v[162:165], v186 offset:16384
	ds_read_b128 v[166:169], v186 offset:17408
	ds_read_b128 v[170:173], v186 offset:18432
	ds_read_b128 v[174:177], v186 offset:19456
	ds_read_b128 v[188:191], v186 offset:20480
	ds_read_b128 v[202:205], v186 offset:21504
	ds_read_b128 v[206:209], v186 offset:22528
	ds_read_b128 v[210:213], v186 offset:23552
	s_mov_b32 m0, s29
	s_nop 0
	global_load_lds_dwordx4 v180, s[58:59]
	s_add_u32 s30, s58, 0x40000
	s_mov_b32 m0, s42
	s_nop 0
	global_load_lds_dwordx4 v182, s[58:59]
	s_addc_u32 s31, s59, 0
	s_mov_b32 m0, s43
	s_nop 0
	global_load_lds_dwordx4 v180, s[30:31]
	s_nop 0
	s_mov_b32 m0, s44
	s_nop 0
	global_load_lds_dwordx4 v182, s[30:31]
	s_nop 0
	s_mov_b32 m0, s15
	s_nop 0
	global_load_lds_dwordx4 v0, s[60:61]
	s_nop 0
	s_mov_b32 m0, s45
	s_nop 0
	global_load_lds_dwordx4 v181, s[60:61]
	s_waitcnt vmcnt(8)
	s_waitcnt lgkmcnt(0)
	s_barrier
	s_waitcnt lgkmcnt(0)
	v_mfma_f32_16x16x32_bf16 v[62:65], v[74:77], v[162:165], v[62:65]
	v_mfma_f32_16x16x32_bf16 v[62:65], v[94:97], v[166:169], v[62:65]
	v_mfma_f32_16x16x32_bf16 v[58:61], v[114:117], v[162:165], v[58:61]
	v_mfma_f32_16x16x32_bf16 v[58:61], v[134:137], v[166:169], v[58:61]
	v_mfma_f32_16x16x32_bf16 v[54:57], v[146:149], v[162:165], v[54:57]
	v_mfma_f32_16x16x32_bf16 v[54:57], v[150:153], v[166:169], v[54:57]
	v_mfma_f32_16x16x32_bf16 v[50:53], v[154:157], v[162:165], v[50:53]
	v_mfma_f32_16x16x32_bf16 v[50:53], v[158:161], v[166:169], v[50:53]
	v_mfma_f32_16x16x32_bf16 v[34:37], v[154:157], v[170:173], v[34:37]
	v_mfma_f32_16x16x32_bf16 v[34:37], v[158:161], v[174:177], v[34:37]
	v_mfma_f32_16x16x32_bf16 v[38:41], v[146:149], v[170:173], v[38:41]
	v_mfma_f32_16x16x32_bf16 v[38:41], v[150:153], v[174:177], v[38:41]
	v_mfma_f32_16x16x32_bf16 v[42:45], v[114:117], v[170:173], v[42:45]
	v_mfma_f32_16x16x32_bf16 v[42:45], v[134:137], v[174:177], v[42:45]
	v_mfma_f32_16x16x32_bf16 v[46:49], v[74:77], v[170:173], v[46:49]
	v_mfma_f32_16x16x32_bf16 v[46:49], v[94:97], v[174:177], v[46:49]
	v_mfma_f32_16x16x32_bf16 v[30:33], v[74:77], v[188:191], v[30:33]
	v_mfma_f32_16x16x32_bf16 v[30:33], v[94:97], v[202:205], v[30:33]
	v_mfma_f32_16x16x32_bf16 v[26:29], v[114:117], v[188:191], v[26:29]
	v_mfma_f32_16x16x32_bf16 v[26:29], v[134:137], v[202:205], v[26:29]
	v_mfma_f32_16x16x32_bf16 v[22:25], v[146:149], v[188:191], v[22:25]
	v_mfma_f32_16x16x32_bf16 v[22:25], v[150:153], v[202:205], v[22:25]
	v_mfma_f32_16x16x32_bf16 v[18:21], v[154:157], v[188:191], v[18:21]
	v_mfma_f32_16x16x32_bf16 v[18:21], v[158:161], v[202:205], v[18:21]
	v_mfma_f32_16x16x32_bf16 v[2:5], v[154:157], v[206:209], v[2:5]
	v_mfma_f32_16x16x32_bf16 v[2:5], v[158:161], v[210:213], v[2:5]
	v_mfma_f32_16x16x32_bf16 v[6:9], v[146:149], v[206:209], v[6:9]
	v_mfma_f32_16x16x32_bf16 v[6:9], v[150:153], v[210:213], v[6:9]
	v_mfma_f32_16x16x32_bf16 v[10:13], v[114:117], v[206:209], v[10:13]
	v_mfma_f32_16x16x32_bf16 v[10:13], v[134:137], v[210:213], v[10:13]
	v_mfma_f32_16x16x32_bf16 v[14:17], v[74:77], v[206:209], v[14:17]
	v_mfma_f32_16x16x32_bf16 v[14:17], v[94:97], v[210:213], v[14:17]
	s_barrier
; #define PG8_STAGE(bufoff, gbase, voff) do { _Pragma("unroll") for (int _i = 0; _i < 2; ++_i) { \
;         const unsigned _m0 = ldsb + (unsigned)((bufoff) + _i * 8192); const char* _gb = (const char*)(gbase); \
;         asm volatile("s_mov_b32 m0, %0\n\ts_nop 0\n\tglobal_load_lds_dwordx4 %1, %2" :: "s"(_m0), "v"((voff)[_i]), "s"(_gb) : "m0", "memory"); } } while (0)
; #define PG8_LDA(dst, b, h) do { _Pragma("unroll") for (int m = 0; m < 4; ++m) _Pragma("unroll") for (int k = 0; k < 2; ++k) dst[m][k] = *(const LAS bf16x8*)(lds + PG8_SA(b, h) + aoff + m * 2048 + k * 1024); } while (0)
; #define PG8_LDB(dst, b, h) do { _Pragma("unroll") for (int n = 0; n < 2; ++n) _Pragma("unroll") for (int k = 0; k < 2; ++k) dst[n][k] = *(const LAS bf16x8*)(lds + PG8_SB(b, h) + boff + n * 2048 + k * 1024); } while (0)
; #define PG8_MMA(ai, bj, At, Bt) do { __builtin_amdgcn_s_setprio(1); _Pragma("unroll") for (int m = 0; m < 4; ++m) _Pragma("unroll") for (int n = 0; n < 2; ++n) _Pragma("unroll") for (int k = 0; k < 2; ++k) \
;         acc[ai][bj][m][n] = __builtin_amdgcn_mfma_f32_16x16x32_bf16(Bt[n][k], At[m][k], acc[ai][bj][m][n], 0, 0, 0); __builtin_amdgcn_s_setprio(0); } while (0)
; #define PG8_WAIT_V(n) asm volatile("s_waitcnt vmcnt(" #n ")" ::: "memory")
; #define PG8_WAIT_L(n) asm volatile("s_waitcnt lgkmcnt(" #n ")" ::: "memory")
; #define PG8_BAR __builtin_amdgcn_s_barrier()
; #define PG8_SCHED __builtin_amdgcn_sched_barrier(0)
; template <class Epi, bool ALIGN_EPI>
; __device__ __forceinline__ void gemm_phase(LAS unsigned char* lds, const Gemm g, const StaticOrder& S, const Epi& E) {
;     ...
;             PG8_LDB(B0, 1, 0); PG8_LDB(B1, 1, 1); PG8_SCHED; PG8_LDA(At, 1, 0); PG8_STAGE(PG8_SA(0, 1), a2 + hstepA, voffA);
;             PG8_WAIT_V(8); PG8_WAIT_L(0); PG8_BAR; PG8_MMA(0, 0, At, B0); PG8_MMA(0, 1, At, B1); PG8_BAR; PG8_SCHED;
;             PG8_LDA(At, 1, 1); PG8_STAGE(PG8_SB(1, 0), b3, voffB); PG8_STAGE(PG8_SB(1, 1), b3 + hstepB, voffB); PG8_STAGE(PG8_SA(1, 0), a3, voffA);
;             PG8_WAIT_V(8); PG8_WAIT_L(0); PG8_BAR; PG8_MMA(1, 0, At, B0); PG8_MMA(1, 1, At, B1); PG8_BAR; PG8_SCHED;
;         }
;         if constexpr (ALIGN_EPI) { if (wr == 0) PG8_BAR; }
;         E(acc, cur, wr, wc, fr, fq);
;         if (!has_next) break;
	v_add_u32_e32 v134, 0x18000, v185
	v_add_u32_e32 v158, 0x1c000, v185
	ds_read_b128 v[74:77], v134
	ds_read_b128 v[94:97], v134 offset:1024
	ds_read_b128 v[114:117], v134 offset:2048
	ds_read_b128 v[134:137], v134 offset:3072
	ds_read_b128 v[146:149], v158
	ds_read_b128 v[150:153], v158 offset:1024
	ds_read_b128 v[154:157], v158 offset:2048
	ds_read_b128 v[158:161], v158 offset:3072
	ds_read_b128 v[162:165], v186 offset:32768
	ds_read_b128 v[166:169], v186 offset:33792
	ds_read_b128 v[170:173], v186 offset:34816
	ds_read_b128 v[174:177], v186 offset:35840
	ds_read_b128 v[188:191], v186 offset:36864
	ds_read_b128 v[202:205], v186 offset:37888
	ds_read_b128 v[206:209], v186 offset:38912
	ds_read_b128 v[210:213], v186 offset:39936
	s_add_u32 s30, s60, 0x40000
	s_addc_u32 s31, s61, 0
	s_mov_b32 m0, s55
	s_nop 0
	global_load_lds_dwordx4 v0, s[30:31]
	s_nop 0
	s_mov_b32 m0, s88
	s_nop 0
	global_load_lds_dwordx4 v181, s[30:31]
	s_waitcnt vmcnt(8)
	s_waitcnt lgkmcnt(0)
	s_barrier
	s_waitcnt lgkmcnt(0)
	v_mfma_f32_16x16x32_bf16 v[142:145], v[74:77], v[162:165], v[142:145]
	v_mfma_f32_16x16x32_bf16 v[142:145], v[94:97], v[166:169], v[142:145]
	v_mfma_f32_16x16x32_bf16 v[138:141], v[114:117], v[162:165], v[138:141]
	v_mfma_f32_16x16x32_bf16 v[138:141], v[134:137], v[166:169], v[138:141]
	v_mfma_f32_16x16x32_bf16 v[130:133], v[146:149], v[162:165], v[130:133]
	v_mfma_f32_16x16x32_bf16 v[130:133], v[150:153], v[166:169], v[130:133]
	v_mfma_f32_16x16x32_bf16 v[126:129], v[154:157], v[162:165], v[126:129]
	v_mfma_f32_16x16x32_bf16 v[126:129], v[158:161], v[166:169], v[126:129]
	v_mfma_f32_16x16x32_bf16 v[106:109], v[154:157], v[170:173], v[106:109]
	v_mfma_f32_16x16x32_bf16 v[106:109], v[158:161], v[174:177], v[106:109]
	v_mfma_f32_16x16x32_bf16 v[110:113], v[146:149], v[170:173], v[110:113]
	v_mfma_f32_16x16x32_bf16 v[110:113], v[150:153], v[174:177], v[110:113]
	v_mfma_f32_16x16x32_bf16 v[118:121], v[114:117], v[170:173], v[118:121]
	v_mfma_f32_16x16x32_bf16 v[118:121], v[134:137], v[174:177], v[118:121]
	v_mfma_f32_16x16x32_bf16 v[122:125], v[74:77], v[170:173], v[122:125]
	v_mfma_f32_16x16x32_bf16 v[122:125], v[94:97], v[174:177], v[122:125]
	v_mfma_f32_16x16x32_bf16 v[102:105], v[74:77], v[188:191], v[102:105]
	v_mfma_f32_16x16x32_bf16 v[102:105], v[94:97], v[202:205], v[102:105]
	v_mfma_f32_16x16x32_bf16 v[98:101], v[114:117], v[188:191], v[98:101]
	v_mfma_f32_16x16x32_bf16 v[98:101], v[134:137], v[202:205], v[98:101]
	v_mfma_f32_16x16x32_bf16 v[90:93], v[146:149], v[188:191], v[90:93]
	v_mfma_f32_16x16x32_bf16 v[90:93], v[150:153], v[202:205], v[90:93]
	v_mfma_f32_16x16x32_bf16 v[86:89], v[154:157], v[188:191], v[86:89]
	v_mfma_f32_16x16x32_bf16 v[86:89], v[158:161], v[202:205], v[86:89]
	v_mfma_f32_16x16x32_bf16 v[66:69], v[154:157], v[206:209], v[66:69]
	v_mfma_f32_16x16x32_bf16 v[66:69], v[158:161], v[210:213], v[66:69]
	v_mfma_f32_16x16x32_bf16 v[70:73], v[146:149], v[206:209], v[70:73]
	v_mfma_f32_16x16x32_bf16 v[70:73], v[150:153], v[210:213], v[70:73]
	v_mfma_f32_16x16x32_bf16 v[78:81], v[114:117], v[206:209], v[78:81]
	v_mfma_f32_16x16x32_bf16 v[78:81], v[134:137], v[210:213], v[78:81]
	v_mfma_f32_16x16x32_bf16 v[82:85], v[74:77], v[206:209], v[82:85]
	v_mfma_f32_16x16x32_bf16 v[82:85], v[94:97], v[210:213], v[82:85]
	s_barrier
	ds_read_b128 v[162:165], v186 offset:49152
	ds_read_b128 v[166:169], v186 offset:50176
	ds_read_b128 v[170:173], v186 offset:51200
	ds_read_b128 v[174:177], v186 offset:52224
	ds_read_b128 v[188:191], v186 offset:53248
	ds_read_b128 v[202:205], v186 offset:54272
	ds_read_b128 v[206:209], v186 offset:55296
	ds_read_b128 v[210:213], v186 offset:56320
	s_add_u32 s30, s58, 0x80
	s_addc_u32 s31, s59, 0
	s_mov_b32 m0, s94
	s_nop 0
	global_load_lds_dwordx4 v180, s[30:31]
	s_nop 0
	s_mov_b32 m0, s95
	s_nop 0
	global_load_lds_dwordx4 v182, s[30:31]
	s_add_u32 s30, s58, 0x40080
	s_addc_u32 s31, s59, 0
	s_mov_b32 m0, s17
	s_nop 0
	global_load_lds_dwordx4 v180, s[30:31]
	s_nop 0
	s_mov_b32 m0, s53
	s_nop 0
	global_load_lds_dwordx4 v182, s[30:31]
	s_nop 0
	s_mov_b32 m0, s96
	s_nop 0
	global_load_lds_dwordx4 v0, s[56:57]
	s_nop 0
	s_mov_b32 m0, s97
	s_nop 0
	global_load_lds_dwordx4 v181, s[56:57]
	s_waitcnt vmcnt(8)
	s_waitcnt lgkmcnt(0)
	s_barrier
	s_waitcnt lgkmcnt(0)
	v_mfma_f32_16x16x32_bf16 v[62:65], v[74:77], v[162:165], v[62:65]
	v_mfma_f32_16x16x32_bf16 v[62:65], v[94:97], v[166:169], v[62:65]
	v_mfma_f32_16x16x32_bf16 v[58:61], v[114:117], v[162:165], v[58:61]
	v_mfma_f32_16x16x32_bf16 v[58:61], v[134:137], v[166:169], v[58:61]
	v_mfma_f32_16x16x32_bf16 v[54:57], v[146:149], v[162:165], v[54:57]
	v_mfma_f32_16x16x32_bf16 v[54:57], v[150:153], v[166:169], v[54:57]
	v_mfma_f32_16x16x32_bf16 v[50:53], v[154:157], v[162:165], v[50:53]
	v_mfma_f32_16x16x32_bf16 v[50:53], v[158:161], v[166:169], v[50:53]
	v_mfma_f32_16x16x32_bf16 v[34:37], v[154:157], v[170:173], v[34:37]
	v_mfma_f32_16x16x32_bf16 v[34:37], v[158:161], v[174:177], v[34:37]
	v_mfma_f32_16x16x32_bf16 v[38:41], v[146:149], v[170:173], v[38:41]
	v_mfma_f32_16x16x32_bf16 v[38:41], v[150:153], v[174:177], v[38:41]
	v_mfma_f32_16x16x32_bf16 v[42:45], v[114:117], v[170:173], v[42:45]
	v_mfma_f32_16x16x32_bf16 v[42:45], v[134:137], v[174:177], v[42:45]
	v_mfma_f32_16x16x32_bf16 v[46:49], v[74:77], v[170:173], v[46:49]
	v_mfma_f32_16x16x32_bf16 v[46:49], v[94:97], v[174:177], v[46:49]
	v_mfma_f32_16x16x32_bf16 v[30:33], v[74:77], v[188:191], v[30:33]
	v_mfma_f32_16x16x32_bf16 v[30:33], v[94:97], v[202:205], v[30:33]
	v_mfma_f32_16x16x32_bf16 v[26:29], v[114:117], v[188:191], v[26:29]
	v_mfma_f32_16x16x32_bf16 v[26:29], v[134:137], v[202:205], v[26:29]
	v_mfma_f32_16x16x32_bf16 v[22:25], v[146:149], v[188:191], v[22:25]
	v_mfma_f32_16x16x32_bf16 v[22:25], v[150:153], v[202:205], v[22:25]
	v_mfma_f32_16x16x32_bf16 v[18:21], v[154:157], v[188:191], v[18:21]
	v_mfma_f32_16x16x32_bf16 v[18:21], v[158:161], v[202:205], v[18:21]
	v_mfma_f32_16x16x32_bf16 v[2:5], v[154:157], v[206:209], v[2:5]
	v_mfma_f32_16x16x32_bf16 v[2:5], v[158:161], v[210:213], v[2:5]
	v_mfma_f32_16x16x32_bf16 v[6:9], v[146:149], v[206:209], v[6:9]
	v_mfma_f32_16x16x32_bf16 v[6:9], v[150:153], v[210:213], v[6:9]
	v_mfma_f32_16x16x32_bf16 v[10:13], v[114:117], v[206:209], v[10:13]
	v_mfma_f32_16x16x32_bf16 v[10:13], v[134:137], v[210:213], v[10:13]
	v_mfma_f32_16x16x32_bf16 v[14:17], v[74:77], v[206:209], v[14:17]
	v_mfma_f32_16x16x32_bf16 v[14:17], v[94:97], v[210:213], v[14:17]
	s_barrier
	s_add_i32 s50, s50, 2
	s_add_u32 s41, s41, 0x100
	s_addc_u32 s49, s49, 0
	s_add_u32 s92, s92, 0x100
	s_addc_u32 s93, s93, 0
	s_cmp_gt_u32 s50, 13
	s_cbranch_scc0 .LBB0_306
	v_readlane_b32 s4, v254, 46
	v_readlane_b32 s5, v254, 47
	s_and_b64 vcc, exec, s[4:5]
	s_cbranch_vccz .LBB0_309
	s_barrier

; #define PG8_WAIT_V(n) asm volatile("s_waitcnt vmcnt(" #n ")" ::: "memory")
; #define PG8_BAR __builtin_amdgcn_s_barrier()
; template <class Epi, bool ALIGN_EPI>
; __device__ __forceinline__ void gemm_phase(LAS unsigned char* lds, const Gemm g, const StaticOrder& S, const Epi& E) {
;     ...
;     PG8_WAIT_V(0);
;     if constexpr (!ALIGN_EPI) { if (wr == 0) PG8_BAR; }
;     PG8_BAR;
.LBB0_329:
	s_setprio 0
	s_waitcnt vmcnt(0)
	v_readlane_b32 s58, v254, 35
	v_readlane_b32 s60, v254, 33
	v_readlane_b32 s94, v254, 31
	s_barrier
	v_readlane_b32 s59, v254, 36
	v_readlane_b32 s61, v254, 34
	s_mov_b32 s68, s80
	v_readlane_b32 s95, v254, 32
	v_readlane_b32 s53, v254, 43
	v_readlane_b32 s65, v254, 42
	v_readlane_b32 s67, v254, 41
	v_readlane_b32 s80, v254, 40
	v_readlane_b32 s85, v254, 39
	v_readlane_b32 s34, v254, 38
	v_readlane_b32 s35, v254, 37
	s_cbranch_execnz .LBB0_388

; #define PG8_WAIT_V(n) asm volatile("s_waitcnt vmcnt(" #n ")" ::: "memory")
; #define PG8_BAR __builtin_amdgcn_s_barrier()
; template <class Epi, bool ALIGN_EPI>
; __device__ __forceinline__ void gemm_phase(LAS unsigned char* lds, const Gemm g, const StaticOrder& S, const Epi& E) {
;     int tid = threadIdx.x; asm volatile("" : "+v"(tid));
;     const int wid = __builtin_amdgcn_readfirstlane(tid >> 6), lane = tid & 63, wr = wid >> 2, wc = wid & 3, fr = lane & 15, fq = lane >> 4;
;     const int K = g.K, nt = K / BK, lda = g.lda;
;     unsigned voffA[2], voffB[2];
; #pragma unroll
;     for (int i = 0; i < 2; ++i) { int R, C; stage_rc(tid * 16 + i * 8192, R, C); const int Rb = (R & ~31) + perm32(R & 31);
;         voffA[i] = (unsigned)(R * lda + C) * 2u; voffB[i] = (unsigned)(Rb * K + C) * 2u; }
;     const size_t kstep = (size_t)(BK * 2);
;     const size_t hstepA = (size_t)HALF * lda * 2, hstepB = (size_t)HALF * K * 2;
;     const size_t tstepA = 2 * hstepA, tstepB = 2 * hstepB;
;     const unsigned ldsw = (unsigned)wid * 1024u;
;     const unsigned ldsb = (unsigned)(unsigned long)lds + ldsw;
;     const int aoff = lds_byte(wr * 64 + fr, fq * 8), boff = lds_byte(wc * 32 + fr, fq * 8);
;     ...
;     Unit cur, nxt; int ui = 0;
;     if (!S.next(0, cur)) return;
;     f32x4 acc[2][2][4][2];
; #pragma unroll
;     for (int a = 0; a < 2; ++a)
; #pragma unroll
;         for (int b = 0; b < 2; ++b)
; #pragma unroll
;             for (int m = 0; m < 4; ++m)
; #pragma unroll
;                 for (int n = 0; n < 2; ++n) acc[a][b][m][n] = (f32x4){0.f, 0.f, 0.f, 0.f};
;     bf16x8 At[4][2], B0[2][2], B1[2][2];
;     const char* cA = (const char*)g.A + (size_t)cur.pm * tstepA + (size_t)cur.pn * g.a_pn_off * 2 + (size_t)(cur.pm >> 4) * g.a_adj; const char* cB = (const char*)g.Bt + (size_t)cur.pn * tstepB;
;     PG8_STAGE(PG8_SB(0, 0), cB, voffB); PG8_STAGE(PG8_SB(0, 1), cB + hstepB, voffB); PG8_STAGE(PG8_SA(0, 0), cA, voffA); PG8_STAGE(PG8_SA(0, 1), cA + hstepA, voffA);
;     if (wr == 1) PG8_BAR;
;     PG8_WAIT_V(2); PG8_BAR;
;     PG8_STAGE(PG8_SB(1, 0), cB + kstep, voffB); PG8_STAGE(PG8_SA(1, 0), cA + kstep, voffA); PG8_STAGE(PG8_SB(1, 1), cB + hstepB + kstep, voffB);
.LBB0_336:
	s_andn2_b64 vcc, exec, s[0:1]
	s_cbranch_vccnz .LBB0_388
	v_bfe_i32 v4, v0, 27, 1
	v_lshlrev_b32_e32 v2, 4, v0
	v_lshrrev_b32_e32 v4, 22, v4
	v_writelane_b32 v254, s94, 31
	v_add_u32_e32 v4, v2, v4
	v_and_b32_e32 v4, 0xfffffc00, v4
	v_writelane_b32 v254, s95, 32
	v_writelane_b32 v254, s60, 33
	v_sub_u32_e32 v4, v2, v4
	v_ashrrev_i32_e32 v3, 31, v0
	v_writelane_b32 v254, s61, 34
	s_waitcnt lgkmcnt(0)
	v_lshrrev_b32_e32 v5, 4, v4
	v_writelane_b32 v254, s58, 35
	v_lshrrev_b32_e32 v3, 26, v3
	v_bitop3_b32 v4, v5, v4, 32 bitop3:0x6c
	v_writelane_b32 v254, s59, 36
	v_add_u32_e32 v3, v0, v3
	v_ashrrev_i32_e32 v6, 31, v4
	v_readlane_b32 s24, v254, 27
	v_ashrrev_i32_e32 v3, 6, v3
	v_lshrrev_b32_e32 v6, 26, v6
	v_readlane_b32 s25, v254, 28
	v_lshlrev_b32_e32 v5, 3, v3
	v_add_u32_e32 v6, v4, v6
	s_ashr_i32 s25, s24, 31
	s_mul_i32 s1, s24, 0x640000
	v_readlane_b32 s4, v254, 29
	v_and_b32_e32 v5, -16, v5
	v_ashrrev_i32_e32 v7, 6, v6
	v_and_b32_e32 v6, 0xc0, v6
	s_mul_hi_i32 s0, s24, 0x640000
	s_add_u32 s14, s4, s1
	v_readlane_b32 s1, v254, 30
	v_add_u32_e32 v5, v7, v5
	v_sub_u32_e32 v4, v4, v6
	s_addc_u32 s15, s1, s0
	v_lshlrev_b32_e32 v3, 5, v3
	v_ashrrev_i16_sdwa v4, v223, sext(v4) dst_sel:DWORD dst_unused:UNUSED_PAD src0_sel:DWORD src1_sel:BYTE_0
	v_lshlrev_b32_e32 v6, 1, v5
	v_lshrrev_b32_e32 v8, 2, v5
	v_and_b32_e32 v7, 3, v7
	s_mov_b32 s0, 0x1fffe0
	v_and_b32_e32 v3, 32, v3
	v_bfe_i32 v4, v4, 0, 16
	v_and_b32_e32 v6, 24, v6
	v_and_b32_e32 v8, 4, v8
	v_and_or_b32 v7, v5, s0, v7
	v_or3_b32 v6, v7, v8, v6
	v_add_lshl_u32 v3, v3, v4, 1
	v_add_u32_e32 v2, 0x2000, v2
	v_lshl_add_u32 v180, v5, 11, v3
	v_lshl_add_u32 v181, v6, 11, v3
	v_ashrrev_i32_e32 v3, 31, v2
	v_lshrrev_b32_e32 v3, 22, v3
	v_add_u32_e32 v3, v2, v3
	v_ashrrev_i32_e32 v3, 10, v3
	v_mul_i32_i24_e32 v4, 0x400, v3
	v_sub_u32_e32 v2, v2, v4
	v_lshrrev_b32_e32 v4, 4, v2
	v_bitop3_b32 v2, v4, v2, 32 bitop3:0x6c
	v_ashrrev_i32_e32 v5, 31, v2
	v_lshrrev_b32_e32 v5, 26, v5
	v_lshlrev_b32_e32 v4, 3, v3
	v_add_u32_e32 v5, v2, v5
	v_and_b32_e32 v4, -16, v4
	v_ashrrev_i32_e32 v6, 6, v5
	s_ashr_i32 s4, s6, 6
	v_add_u32_e32 v4, v6, v4
	v_and_b32_e32 v5, 0xc0, v5
	v_and_b32_e32 v6, 3, v6
	v_sub_u32_e32 v2, v2, v5
	v_and_or_b32 v6, v4, s0, v6
	s_lshl_b32 s0, s4, 10
	s_ashr_i32 s11, s10, 31
	s_ashr_i32 s9, s46, 31
	s_mov_b32 s8, s46
	v_lshlrev_b32_e32 v3, 5, v3
	v_ashrrev_i16_sdwa v2, v223, sext(v2) dst_sel:DWORD dst_unused:UNUSED_PAD src0_sel:DWORD src1_sel:BYTE_0
	v_lshlrev_b32_e32 v5, 1, v4
	v_lshrrev_b32_e32 v7, 2, v4
	s_ashr_i32 s5, s6, 8
	s_add_i32 s42, s0, 0
	s_lshl_b64 s[0:1], s[10:11], 19
	s_lshl_b64 s[8:9], s[8:9], 19
	v_and_b32_e32 v3, 32, v3
	v_bfe_i32 v2, v2, 0, 16
	v_and_b32_e32 v5, 24, v5
	v_and_b32_e32 v7, 4, v7
	s_add_u32 s36, s14, s8
	v_or3_b32 v5, v6, v7, v5
	v_add_lshl_u32 v2, v3, v2, 1
	s_addc_u32 s37, s15, s9
	s_add_i32 s43, s42, 0x10000
	s_mov_b32 m0, s43
	s_nop 0
	global_load_lds_dwordx4 v181, s[36:37]
	s_add_i32 s44, s42, 0x12000
	s_add_i32 s45, s42, 0x14000
	v_lshl_add_u32 v183, v5, 11, v2
	s_mov_b32 m0, s44
	s_nop 0
	global_load_lds_dwordx4 v183, s[36:37]
	s_add_u32 s8, s36, 0x40000
	s_addc_u32 s9, s37, 0
	s_mov_b32 m0, s45
	s_nop 0
	global_load_lds_dwordx4 v181, s[8:9]
	s_add_i32 s56, s42, 0x16000
	s_mov_b32 m0, s56
	s_nop 0
	global_load_lds_dwordx4 v183, s[8:9]
	s_add_u32 s38, s18, s0
	s_addc_u32 s39, s19, s1
	s_mov_b32 m0, s42
	s_nop 0
	global_load_lds_dwordx4 v180, s[38:39]
	s_add_i32 s57, s42, 0x2000
	s_add_i32 s58, s42, 0x4000
	v_lshl_add_u32 v182, v4, 11, v2
	s_mov_b32 m0, s57
	s_nop 0
	global_load_lds_dwordx4 v182, s[38:39]
	s_add_u32 s0, s38, 0x40000
	s_addc_u32 s1, s39, 0
	s_mov_b32 m0, s58
	s_nop 0
	global_load_lds_dwordx4 v180, s[0:1]
	s_add_i32 s59, s42, 0x6000
	s_mov_b32 m0, s59
	s_nop 0
	global_load_lds_dwordx4 v182, s[0:1]
	s_cmp_eq_u32 s5, 1
	s_cselect_b64 s[0:1], -1, 0
	s_cmp_lg_u32 s5, 1
	s_cbranch_scc1 .LBB0_339
	s_barrier
	s_setprio 1

; #define PG8_STAGE(bufoff, gbase, voff) do { _Pragma("unroll") for (int _i = 0; _i < 2; ++_i) { \
;         const unsigned _m0 = ldsb + (unsigned)((bufoff) + _i * 8192); const char* _gb = (const char*)(gbase); \
;         asm volatile("s_mov_b32 m0, %0\n\ts_nop 0\n\tglobal_load_lds_dwordx4 %1, %2" :: "s"(_m0), "v"((voff)[_i]), "s"(_gb) : "m0", "memory"); } } while (0)
; #define PG8_LDA(dst, b, h) do { _Pragma("unroll") for (int m = 0; m < 4; ++m) _Pragma("unroll") for (int k = 0; k < 2; ++k) dst[m][k] = *(const LAS bf16x8*)(lds + PG8_SA(b, h) + aoff + m * 2048 + k * 1024); } while (0)
; #define PG8_LDB(dst, b, h) do { _Pragma("unroll") for (int n = 0; n < 2; ++n) _Pragma("unroll") for (int k = 0; k < 2; ++k) dst[n][k] = *(const LAS bf16x8*)(lds + PG8_SB(b, h) + boff + n * 2048 + k * 1024); } while (0)
; #define PG8_MMA(ai, bj, At, Bt) do { __builtin_amdgcn_s_setprio(1); _Pragma("unroll") for (int m = 0; m < 4; ++m) _Pragma("unroll") for (int n = 0; n < 2; ++n) _Pragma("unroll") for (int k = 0; k < 2; ++k) \
;         acc[ai][bj][m][n] = __builtin_amdgcn_mfma_f32_16x16x32_bf16(Bt[n][k], At[m][k], acc[ai][bj][m][n], 0, 0, 0); __builtin_amdgcn_s_setprio(0); } while (0)
; #define PG8_WAIT_V(n) asm volatile("s_waitcnt vmcnt(" #n ")" ::: "memory")
; #define PG8_WAIT_L(n) asm volatile("s_waitcnt lgkmcnt(" #n ")" ::: "memory")
; template <class Epi, bool ALIGN_EPI>
; __device__ __forceinline__ void gemm_phase(LAS unsigned char* lds, const Gemm g, const StaticOrder& S, const Epi& E) {
;     ...
;         for (int t = 0; t < nt; t += 2) {
;             const bool last = (t == nt - 2);
;             const char* a1 = cA + (size_t)(t + 1) * kstep;
;             const char* a2 = last ? nA : cA + (size_t)(t + 2) * kstep; const char* b2 = last ? nB : cB + (size_t)(t + 2) * kstep;
;             const char* a3 = a2 + kstep; const char* b3 = b2 + kstep;
;             PG8_LDB(B0, 0, 0); PG8_LDB(B1, 0, 1); PG8_SCHED; PG8_LDA(At, 0, 0); PG8_STAGE(PG8_SA(1, 1), a1 + hstepA, voffA);
;             PG8_WAIT_V(8); PG8_WAIT_L(0); PG8_BAR; PG8_MMA(0, 0, At, B0); PG8_MMA(0, 1, At, B1); PG8_BAR; PG8_SCHED;
;             PG8_LDA(At, 0, 1); PG8_STAGE(PG8_SB(0, 0), b2, voffB); PG8_STAGE(PG8_SB(0, 1), b2 + hstepB, voffB); PG8_STAGE(PG8_SA(0, 0), a2, voffA);
;             PG8_WAIT_V(8); PG8_WAIT_L(0); PG8_BAR; PG8_MMA(1, 0, At, B0); PG8_MMA(1, 1, At, B1); PG8_BAR; PG8_SCHED;
.LBB0_349:
	v_add_u32_e32 v0, 0x10000, v187
	ds_read_b128 v[34:37], v0
	ds_read_b128 v[54:57], v0 offset:1024
	ds_read_b128 v[74:77], v0 offset:2048
	ds_read_b128 v[94:97], v0 offset:3072
	v_add_u32_e32 v0, 0x14000, v187
	ds_read_b128 v[110:113], v0
	ds_read_b128 v[126:129], v0 offset:1024
	ds_read_b128 v[146:149], v0 offset:2048
	ds_read_b128 v[160:163], v0 offset:3072
	s_add_u32 s38, s36, 0xfffc0080
	s_addc_u32 s39, s37, -1
	s_cmp_eq_u32 s50, 12
	s_cselect_b32 s54, s5, s38
	s_cselect_b32 s55, s4, s39
	s_cselect_b32 s48, s27, s29
	s_cselect_b32 s49, s11, s41
	s_add_u32 s38, s54, 0x80
	s_addc_u32 s39, s55, 0
	ds_read_b128 v[164:167], v188
	ds_read_b128 v[168:171], v188 offset:1024
	ds_read_b128 v[172:175], v188 offset:2048
	ds_read_b128 v[176:179], v188 offset:3072
	ds_read_b128 v[190:193], v188 offset:4096
	ds_read_b128 v[202:205], v188 offset:5120
	ds_read_b128 v[206:209], v188 offset:6144
	ds_read_b128 v[210:213], v188 offset:7168
	s_mov_b32 m0, s91
	s_nop 0
	global_load_lds_dwordx4 v180, s[36:37]
	s_nop 0
	s_mov_b32 m0, s93
	s_nop 0
	global_load_lds_dwordx4 v182, s[36:37]
	s_waitcnt vmcnt(8)
	s_waitcnt lgkmcnt(0)
	s_barrier
	s_waitcnt lgkmcnt(0)
	v_mfma_f32_16x16x32_bf16 v[154:157], v[34:37], v[164:167], v[154:157]
	v_mfma_f32_16x16x32_bf16 v[154:157], v[54:57], v[168:171], v[154:157]
	v_mfma_f32_16x16x32_bf16 v[150:153], v[74:77], v[164:167], v[150:153]
	v_mfma_f32_16x16x32_bf16 v[150:153], v[94:97], v[168:171], v[150:153]
	v_mfma_f32_16x16x32_bf16 v[142:145], v[110:113], v[164:167], v[142:145]
	v_mfma_f32_16x16x32_bf16 v[142:145], v[126:129], v[168:171], v[142:145]
	v_mfma_f32_16x16x32_bf16 v[138:141], v[146:149], v[164:167], v[138:141]
	v_mfma_f32_16x16x32_bf16 v[138:141], v[160:163], v[168:171], v[138:141]
	v_mfma_f32_16x16x32_bf16 v[118:121], v[146:149], v[172:175], v[118:121]
	v_mfma_f32_16x16x32_bf16 v[118:121], v[160:163], v[176:179], v[118:121]
	v_mfma_f32_16x16x32_bf16 v[122:125], v[110:113], v[172:175], v[122:125]
	v_mfma_f32_16x16x32_bf16 v[122:125], v[126:129], v[176:179], v[122:125]
	v_mfma_f32_16x16x32_bf16 v[130:133], v[74:77], v[172:175], v[130:133]
	v_mfma_f32_16x16x32_bf16 v[130:133], v[94:97], v[176:179], v[130:133]
	v_mfma_f32_16x16x32_bf16 v[134:137], v[34:37], v[172:175], v[134:137]
	v_mfma_f32_16x16x32_bf16 v[134:137], v[54:57], v[176:179], v[134:137]
	v_mfma_f32_16x16x32_bf16 v[114:117], v[34:37], v[190:193], v[114:117]
	v_mfma_f32_16x16x32_bf16 v[114:117], v[54:57], v[202:205], v[114:117]
	v_mfma_f32_16x16x32_bf16 v[106:109], v[74:77], v[190:193], v[106:109]
	v_mfma_f32_16x16x32_bf16 v[106:109], v[94:97], v[202:205], v[106:109]
	v_mfma_f32_16x16x32_bf16 v[102:105], v[110:113], v[190:193], v[102:105]
	v_mfma_f32_16x16x32_bf16 v[102:105], v[126:129], v[202:205], v[102:105]
	v_mfma_f32_16x16x32_bf16 v[98:101], v[146:149], v[190:193], v[98:101]
	v_mfma_f32_16x16x32_bf16 v[98:101], v[160:163], v[202:205], v[98:101]
	v_mfma_f32_16x16x32_bf16 v[78:81], v[146:149], v[206:209], v[78:81]
	v_mfma_f32_16x16x32_bf16 v[78:81], v[160:163], v[210:213], v[78:81]
	v_mfma_f32_16x16x32_bf16 v[82:85], v[110:113], v[206:209], v[82:85]
	v_mfma_f32_16x16x32_bf16 v[82:85], v[126:129], v[210:213], v[82:85]
	v_mfma_f32_16x16x32_bf16 v[86:89], v[74:77], v[206:209], v[86:89]
	v_mfma_f32_16x16x32_bf16 v[86:89], v[94:97], v[210:213], v[86:89]
	v_mfma_f32_16x16x32_bf16 v[90:93], v[34:37], v[206:209], v[90:93]
	v_mfma_f32_16x16x32_bf16 v[90:93], v[54:57], v[210:213], v[90:93]
	s_barrier
	ds_read_b128 v[164:167], v188 offset:16384
	ds_read_b128 v[168:171], v188 offset:17408
	ds_read_b128 v[172:175], v188 offset:18432
	ds_read_b128 v[176:179], v188 offset:19456
	ds_read_b128 v[190:193], v188 offset:20480
	ds_read_b128 v[202:205], v188 offset:21504
	ds_read_b128 v[206:209], v188 offset:22528
	ds_read_b128 v[210:213], v188 offset:23552
	s_mov_b32 m0, s43
	s_nop 0
	global_load_lds_dwordx4 v181, s[48:49]
	s_add_u32 s96, s48, 0x40000
	s_mov_b32 m0, s44
	s_nop 0
	global_load_lds_dwordx4 v183, s[48:49]
	s_addc_u32 s97, s49, 0
	s_mov_b32 m0, s45
	s_nop 0
	global_load_lds_dwordx4 v181, s[96:97]
	s_nop 0
	s_mov_b32 m0, s56
	s_nop 0
	global_load_lds_dwordx4 v183, s[96:97]
	s_nop 0
	s_mov_b32 m0, s42
	s_nop 0
	global_load_lds_dwordx4 v180, s[54:55]
	s_nop 0
	s_mov_b32 m0, s57
	s_nop 0
	global_load_lds_dwordx4 v182, s[54:55]
	s_waitcnt vmcnt(8)
	s_waitcnt lgkmcnt(0)
	s_barrier
	s_waitcnt lgkmcnt(0)
	v_mfma_f32_16x16x32_bf16 v[70:73], v[34:37], v[164:167], v[70:73]
	v_mfma_f32_16x16x32_bf16 v[66:69], v[74:77], v[164:167], v[66:69]
	v_mfma_f32_16x16x32_bf16 v[50:53], v[34:37], v[172:175], v[50:53]
	v_mfma_f32_16x16x32_bf16 v[46:49], v[74:77], v[172:175], v[46:49]
	v_mfma_f32_16x16x32_bf16 v[30:33], v[34:37], v[190:193], v[30:33]
	v_mfma_f32_16x16x32_bf16 v[26:29], v[74:77], v[190:193], v[26:29]
	v_mfma_f32_16x16x32_bf16 v[14:17], v[34:37], v[206:209], v[14:17]
	v_mfma_f32_16x16x32_bf16 v[10:13], v[74:77], v[206:209], v[10:13]
	v_mfma_f32_16x16x32_bf16 v[70:73], v[54:57], v[168:171], v[70:73]
	v_mfma_f32_16x16x32_bf16 v[66:69], v[94:97], v[168:171], v[66:69]
	v_mfma_f32_16x16x32_bf16 v[50:53], v[54:57], v[176:179], v[50:53]
	v_mfma_f32_16x16x32_bf16 v[46:49], v[94:97], v[176:179], v[46:49]
	v_mfma_f32_16x16x32_bf16 v[30:33], v[54:57], v[202:205], v[30:33]
	v_mfma_f32_16x16x32_bf16 v[26:29], v[94:97], v[202:205], v[26:29]
	v_mfma_f32_16x16x32_bf16 v[14:17], v[54:57], v[210:213], v[14:17]
	v_mfma_f32_16x16x32_bf16 v[10:13], v[94:97], v[210:213], v[10:13]
	v_mfma_f32_16x16x32_bf16 v[42:45], v[110:113], v[172:175], v[42:45]
	v_mfma_f32_16x16x32_bf16 v[38:41], v[146:149], v[172:175], v[38:41]
	v_mfma_f32_16x16x32_bf16 v[22:25], v[110:113], v[190:193], v[22:25]
	v_mfma_f32_16x16x32_bf16 v[18:21], v[146:149], v[190:193], v[18:21]
	v_mfma_f32_16x16x32_bf16 v[6:9], v[110:113], v[206:209], v[6:9]
	v_mfma_f32_16x16x32_bf16 v[2:5], v[146:149], v[206:209], v[2:5]
	v_mfma_f32_16x16x32_bf16 v[34:37], v[110:113], v[164:167], v[62:65]
	v_mfma_f32_16x16x32_bf16 v[54:57], v[146:149], v[164:167], v[58:61]
	v_mfma_f32_16x16x32_bf16 v[42:45], v[126:129], v[176:179], v[42:45]
	v_mfma_f32_16x16x32_bf16 v[38:41], v[160:163], v[176:179], v[38:41]
	v_mfma_f32_16x16x32_bf16 v[22:25], v[126:129], v[202:205], v[22:25]
	v_mfma_f32_16x16x32_bf16 v[18:21], v[160:163], v[202:205], v[18:21]
	v_mfma_f32_16x16x32_bf16 v[6:9], v[126:129], v[210:213], v[6:9]
	v_mfma_f32_16x16x32_bf16 v[2:5], v[160:163], v[210:213], v[2:5]
	v_mfma_f32_16x16x32_bf16 v[34:37], v[126:129], v[168:171], v[34:37]
	v_mfma_f32_16x16x32_bf16 v[54:57], v[160:163], v[168:171], v[54:57]
	s_barrier
; #define PG8_STAGE(bufoff, gbase, voff) do { _Pragma("unroll") for (int _i = 0; _i < 2; ++_i) { \
;         const unsigned _m0 = ldsb + (unsigned)((bufoff) + _i * 8192); const char* _gb = (const char*)(gbase); \
;         asm volatile("s_mov_b32 m0, %0\n\ts_nop 0\n\tglobal_load_lds_dwordx4 %1, %2" :: "s"(_m0), "v"((voff)[_i]), "s"(_gb) : "m0", "memory"); } } while (0)
; #define PG8_LDA(dst, b, h) do { _Pragma("unroll") for (int m = 0; m < 4; ++m) _Pragma("unroll") for (int k = 0; k < 2; ++k) dst[m][k] = *(const LAS bf16x8*)(lds + PG8_SA(b, h) + aoff + m * 2048 + k * 1024); } while (0)
; #define PG8_LDB(dst, b, h) do { _Pragma("unroll") for (int n = 0; n < 2; ++n) _Pragma("unroll") for (int k = 0; k < 2; ++k) dst[n][k] = *(const LAS bf16x8*)(lds + PG8_SB(b, h) + boff + n * 2048 + k * 1024); } while (0)
; #define PG8_MMA(ai, bj, At, Bt) do { __builtin_amdgcn_s_setprio(1); _Pragma("unroll") for (int m = 0; m < 4; ++m) _Pragma("unroll") for (int n = 0; n < 2; ++n) _Pragma("unroll") for (int k = 0; k < 2; ++k) \
;         acc[ai][bj][m][n] = __builtin_amdgcn_mfma_f32_16x16x32_bf16(Bt[n][k], At[m][k], acc[ai][bj][m][n], 0, 0, 0); __builtin_amdgcn_s_setprio(0); } while (0)
; #define PG8_WAIT_V(n) asm volatile("s_waitcnt vmcnt(" #n ")" ::: "memory")
; #define PG8_WAIT_L(n) asm volatile("s_waitcnt lgkmcnt(" #n ")" ::: "memory")
; #define PG8_BAR __builtin_amdgcn_s_barrier()
; #define PG8_SCHED __builtin_amdgcn_sched_barrier(0)
; template <class Epi, bool ALIGN_EPI>
; __device__ __forceinline__ void gemm_phase(LAS unsigned char* lds, const Gemm g, const StaticOrder& S, const Epi& E) {
;     ...
;             PG8_LDB(B0, 1, 0); PG8_LDB(B1, 1, 1); PG8_SCHED; PG8_LDA(At, 1, 0); PG8_STAGE(PG8_SA(0, 1), a2 + hstepA, voffA);
;             PG8_WAIT_V(8); PG8_WAIT_L(0); PG8_BAR; PG8_MMA(0, 0, At, B0); PG8_MMA(0, 1, At, B1); PG8_BAR; PG8_SCHED;
;             PG8_LDA(At, 1, 1); PG8_STAGE(PG8_SB(1, 0), b3, voffB); PG8_STAGE(PG8_SB(1, 1), b3 + hstepB, voffB); PG8_STAGE(PG8_SA(1, 0), a3, voffA);
;             PG8_WAIT_V(8); PG8_WAIT_L(0); PG8_BAR; PG8_MMA(1, 0, At, B0); PG8_MMA(1, 1, At, B1); PG8_BAR; PG8_SCHED;
;         }
;         if constexpr (ALIGN_EPI) { if (wr == 0) PG8_BAR; }
;         E(acc, cur, wr, wc, fr, fq);
;         if (!has_next) break;
	v_add_u32_e32 v0, 0x18000, v187
	ds_read_b128 v[58:61], v0
	ds_read_b128 v[62:65], v0 offset:1024
	ds_read_b128 v[74:77], v0 offset:2048
	ds_read_b128 v[94:97], v0 offset:3072
	v_add_u32_e32 v0, 0x1c000, v187
	ds_read_b128 v[110:113], v0
	ds_read_b128 v[126:129], v0 offset:1024
	ds_read_b128 v[146:149], v0 offset:2048
	ds_read_b128 v[160:163], v0 offset:3072
	ds_read_b128 v[164:167], v188 offset:32768
	ds_read_b128 v[168:171], v188 offset:33792
	ds_read_b128 v[172:175], v188 offset:34816
	ds_read_b128 v[176:179], v188 offset:35840
	ds_read_b128 v[190:193], v188 offset:36864
	ds_read_b128 v[202:205], v188 offset:37888
	ds_read_b128 v[206:209], v188 offset:38912
	ds_read_b128 v[210:213], v188 offset:39936
	s_add_u32 s54, s54, 0x40000
	s_addc_u32 s55, s55, 0
	s_mov_b32 m0, s58
	s_nop 0
	global_load_lds_dwordx4 v180, s[54:55]
	s_nop 0
	s_mov_b32 m0, s59
	s_nop 0
	global_load_lds_dwordx4 v182, s[54:55]
	s_waitcnt vmcnt(8)
	s_waitcnt lgkmcnt(0)
	s_barrier
	s_waitcnt lgkmcnt(0)
	v_mfma_f32_16x16x32_bf16 v[154:157], v[58:61], v[164:167], v[154:157]
	v_mfma_f32_16x16x32_bf16 v[154:157], v[62:65], v[168:171], v[154:157]
	v_mfma_f32_16x16x32_bf16 v[150:153], v[74:77], v[164:167], v[150:153]
	v_mfma_f32_16x16x32_bf16 v[150:153], v[94:97], v[168:171], v[150:153]
	v_mfma_f32_16x16x32_bf16 v[142:145], v[110:113], v[164:167], v[142:145]
	v_mfma_f32_16x16x32_bf16 v[142:145], v[126:129], v[168:171], v[142:145]
	v_mfma_f32_16x16x32_bf16 v[138:141], v[146:149], v[164:167], v[138:141]
	v_mfma_f32_16x16x32_bf16 v[138:141], v[160:163], v[168:171], v[138:141]
	v_mfma_f32_16x16x32_bf16 v[118:121], v[146:149], v[172:175], v[118:121]
	v_mfma_f32_16x16x32_bf16 v[118:121], v[160:163], v[176:179], v[118:121]
	v_mfma_f32_16x16x32_bf16 v[122:125], v[110:113], v[172:175], v[122:125]
	v_mfma_f32_16x16x32_bf16 v[122:125], v[126:129], v[176:179], v[122:125]
	v_mfma_f32_16x16x32_bf16 v[130:133], v[74:77], v[172:175], v[130:133]
	v_mfma_f32_16x16x32_bf16 v[130:133], v[94:97], v[176:179], v[130:133]
	v_mfma_f32_16x16x32_bf16 v[134:137], v[58:61], v[172:175], v[134:137]
	v_mfma_f32_16x16x32_bf16 v[134:137], v[62:65], v[176:179], v[134:137]
	v_mfma_f32_16x16x32_bf16 v[114:117], v[58:61], v[190:193], v[114:117]
	v_mfma_f32_16x16x32_bf16 v[114:117], v[62:65], v[202:205], v[114:117]
	v_mfma_f32_16x16x32_bf16 v[106:109], v[74:77], v[190:193], v[106:109]
	v_mfma_f32_16x16x32_bf16 v[106:109], v[94:97], v[202:205], v[106:109]
	v_mfma_f32_16x16x32_bf16 v[102:105], v[110:113], v[190:193], v[102:105]
	v_mfma_f32_16x16x32_bf16 v[102:105], v[126:129], v[202:205], v[102:105]
	v_mfma_f32_16x16x32_bf16 v[98:101], v[146:149], v[190:193], v[98:101]
	v_mfma_f32_16x16x32_bf16 v[98:101], v[160:163], v[202:205], v[98:101]
	v_mfma_f32_16x16x32_bf16 v[78:81], v[146:149], v[206:209], v[78:81]
	v_mfma_f32_16x16x32_bf16 v[78:81], v[160:163], v[210:213], v[78:81]
	v_mfma_f32_16x16x32_bf16 v[82:85], v[110:113], v[206:209], v[82:85]
	v_mfma_f32_16x16x32_bf16 v[82:85], v[126:129], v[210:213], v[82:85]
	v_mfma_f32_16x16x32_bf16 v[86:89], v[74:77], v[206:209], v[86:89]
	v_mfma_f32_16x16x32_bf16 v[86:89], v[94:97], v[210:213], v[86:89]
	v_mfma_f32_16x16x32_bf16 v[90:93], v[58:61], v[206:209], v[90:93]
	v_mfma_f32_16x16x32_bf16 v[90:93], v[62:65], v[210:213], v[90:93]
	s_barrier
	ds_read_b128 v[164:167], v188 offset:49152
	ds_read_b128 v[168:171], v188 offset:50176
	ds_read_b128 v[172:175], v188 offset:51200
	ds_read_b128 v[176:179], v188 offset:52224
	ds_read_b128 v[190:193], v188 offset:53248
	ds_read_b128 v[202:205], v188 offset:54272
	ds_read_b128 v[206:209], v188 offset:55296
	ds_read_b128 v[210:213], v188 offset:56320
	s_add_u32 s54, s48, 0x80
	s_addc_u32 s55, s49, 0
	s_mov_b32 m0, s17
	s_nop 0
	global_load_lds_dwordx4 v181, s[54:55]
	s_add_u32 s48, s48, 0x40080
	s_mov_b32 m0, s60
	s_nop 0
	global_load_lds_dwordx4 v183, s[54:55]
	s_addc_u32 s49, s49, 0
	s_mov_b32 m0, s89
	s_nop 0
	global_load_lds_dwordx4 v181, s[48:49]
	s_nop 0
	s_mov_b32 m0, s90
	s_nop 0
	global_load_lds_dwordx4 v183, s[48:49]
	s_nop 0
	s_mov_b32 m0, s61
	s_nop 0
	global_load_lds_dwordx4 v180, s[38:39]
	s_nop 0
	s_mov_b32 m0, s88
	s_nop 0
	global_load_lds_dwordx4 v182, s[38:39]
	s_waitcnt vmcnt(8)
	s_waitcnt lgkmcnt(0)
	s_barrier
	s_waitcnt lgkmcnt(0)
	v_mfma_f32_16x16x32_bf16 v[70:73], v[58:61], v[164:167], v[70:73]
	v_mfma_f32_16x16x32_bf16 v[66:69], v[74:77], v[164:167], v[66:69]
	v_mfma_f32_16x16x32_bf16 v[50:53], v[58:61], v[172:175], v[50:53]
	v_mfma_f32_16x16x32_bf16 v[46:49], v[74:77], v[172:175], v[46:49]
	v_mfma_f32_16x16x32_bf16 v[30:33], v[58:61], v[190:193], v[30:33]
	v_mfma_f32_16x16x32_bf16 v[26:29], v[74:77], v[190:193], v[26:29]
	v_mfma_f32_16x16x32_bf16 v[14:17], v[58:61], v[206:209], v[14:17]
	v_mfma_f32_16x16x32_bf16 v[10:13], v[74:77], v[206:209], v[10:13]
	v_mfma_f32_16x16x32_bf16 v[70:73], v[62:65], v[168:171], v[70:73]
	v_mfma_f32_16x16x32_bf16 v[66:69], v[94:97], v[168:171], v[66:69]
	v_mfma_f32_16x16x32_bf16 v[50:53], v[62:65], v[176:179], v[50:53]
	v_mfma_f32_16x16x32_bf16 v[46:49], v[94:97], v[176:179], v[46:49]
	v_mfma_f32_16x16x32_bf16 v[30:33], v[62:65], v[202:205], v[30:33]
	v_mfma_f32_16x16x32_bf16 v[26:29], v[94:97], v[202:205], v[26:29]
	v_mfma_f32_16x16x32_bf16 v[14:17], v[62:65], v[210:213], v[14:17]
	v_mfma_f32_16x16x32_bf16 v[10:13], v[94:97], v[210:213], v[10:13]
	v_mfma_f32_16x16x32_bf16 v[34:37], v[110:113], v[164:167], v[34:37]
	v_mfma_f32_16x16x32_bf16 v[62:65], v[126:129], v[168:171], v[34:37]
	v_mfma_f32_16x16x32_bf16 v[34:37], v[146:149], v[164:167], v[54:57]
	v_mfma_f32_16x16x32_bf16 v[58:61], v[160:163], v[168:171], v[34:37]
	v_mfma_f32_16x16x32_bf16 v[34:37], v[110:113], v[172:175], v[42:45]
	v_mfma_f32_16x16x32_bf16 v[42:45], v[126:129], v[176:179], v[34:37]
	v_mfma_f32_16x16x32_bf16 v[34:37], v[146:149], v[172:175], v[38:41]
	v_mfma_f32_16x16x32_bf16 v[22:25], v[110:113], v[190:193], v[22:25]
	v_mfma_f32_16x16x32_bf16 v[18:21], v[146:149], v[190:193], v[18:21]
	v_mfma_f32_16x16x32_bf16 v[6:9], v[110:113], v[206:209], v[6:9]
	v_mfma_f32_16x16x32_bf16 v[2:5], v[146:149], v[206:209], v[2:5]
	v_mfma_f32_16x16x32_bf16 v[38:41], v[160:163], v[176:179], v[34:37]
	v_mfma_f32_16x16x32_bf16 v[22:25], v[126:129], v[202:205], v[22:25]
	v_mfma_f32_16x16x32_bf16 v[18:21], v[160:163], v[202:205], v[18:21]
	v_mfma_f32_16x16x32_bf16 v[6:9], v[126:129], v[210:213], v[6:9]
	v_mfma_f32_16x16x32_bf16 v[2:5], v[160:163], v[210:213], v[2:5]
	s_barrier
	s_add_i32 s50, s50, 2
	s_add_u32 s29, s29, 0x100
	s_addc_u32 s41, s41, 0
	s_add_u32 s36, s36, 0x100
	s_addc_u32 s37, s37, 0
	s_cmp_gt_u32 s50, 13
	s_cbranch_scc0 .LBB0_349
	s_and_b64 vcc, exec, s[24:25]
	s_cbranch_vccz .LBB0_352
	s_barrier

; #define PG8_WAIT_V(n) asm volatile("s_waitcnt vmcnt(" #n ")" ::: "memory")
; #define PG8_BAR __builtin_amdgcn_s_barrier()
; template <class Epi, bool ALIGN_EPI>
; __device__ __forceinline__ void gemm_phase(LAS unsigned char* lds, const Gemm g, const StaticOrder& S, const Epi& E) {
;     ...
;     PG8_WAIT_V(0);
;     if constexpr (!ALIGN_EPI) { if (wr == 0) PG8_BAR; }
;     PG8_BAR;
.LBB0_387:
	s_setprio 0
	s_waitcnt vmcnt(0)
	v_readlane_b32 s58, v254, 35
	v_readlane_b32 s60, v254, 33
	v_readlane_b32 s94, v254, 31
	v_readlane_b32 s59, v254, 36
	v_readlane_b32 s61, v254, 34
	v_readlane_b32 s95, v254, 32
	s_barrier
